# EpiResid 16B layout + skip redundant first-iteration DMA waits + 16B gate layout + merged up-proj stores + SWA DPP reductions
# speedup vs baseline: 1.0300x; 1.0099x over previous
; #define LAS __attribute__((address_space(3)))
; __device__ __forceinline__ f32x4 mfma16(bf16x8 a, bf16x8 b, f32x4 c) { return __builtin_amdgcn_mfma_f32_16x16x32_bf16(a, b, c, 0, 0, 0); }
; __device__ __forceinline__ void swa_unit(LAS unsigned char* L, bf16_t* Z, const float* sinks, int b, int qb, int kvh) {
;     ...
;     const float slope = exp2f(-(float)(hq + 1)) * 1.4426950408889634f; const float sink = sinks[hq] * 1.4426950408889634f;
;     const int kmin = (t0 == 0) ? 128 : 0;
; #pragma unroll
;     for (int rt = 0; rt < 4; ++rt) {
;         const int kbase = 64 * half + 16 * rt;
;         const bf16x8 qa0 = qf[rt][0], qa1 = qf[rt][1];
;         f32x4 sc[9];
; #pragma unroll
;         for (int n = 0; n < 9; ++n) { const LAS bf16_t* kb = Ks + (kbase + 16 * n + l15) * 72 + quad * 8; f32x4 a4 = (f32x4){0.f, 0.f, 0.f, 0.f};
;             a4 = mfma16(qa0, *(const LAS bf16x8*)kb, a4); a4 = mfma16(qa1, *(const LAS bf16x8*)(kb + 32), a4); sc[n] = a4; }
;         float mx[4] = {sink, sink, sink, sink};
; #pragma unroll
;         for (int n = 0; n < 9; ++n)
; #pragma unroll
;             for (int j = 0; j < 4; ++j) { const int qi = kbase + quad * 4 + j, kk = kbase + 16 * n + l15; const int dist = qi + 128 - kk;
;                 const bool valid = ((n >= 1 && n <= 7) || ((dist >= 0) && (dist < 128))) && (kk >= kmin);
;                 const float lg = valid ? sc[n][j] * (0.125f * 1.4426950408889634f) - slope * (float)dist : -INFINITY; sc[n][j] = lg; mx[j] = fmaxf(mx[j], lg); }
.LBB0_486:
	s_or_b64 exec, exec, s[0:1]
	v_add_u32_e32 v0, 1, v40
	v_cvt_f32_i32_e32 v0, v0
	s_mov_b32 s0, 0x42fc0000
	v_mov_b32_e32 v34, 0x42800000
	v_ashrrev_i32_e32 v41, 31, v40
	v_cmp_lt_f32_e32 vcc, s0, v0
	s_waitcnt lgkmcnt(0)
	s_barrier
	v_cndmask_b32_e32 v34, 0, v34, vcc
	v_sub_f32_e32 v0, v34, v0
	v_exp_f32_e32 v0, v0
	v_not_b32_e32 v34, 63
	v_cndmask_b32_e32 v34, 0, v34, vcc
	v_ldexp_f32 v0, v0, v34
	v_lshl_add_u64 v[34:35], v[40:41], 2, s[52:53]
	global_load_dword v70, v[34:35], off
	v_and_b32_e32 v35, 64, v249
	v_mul_f32_e32 v75, 0x3fb8aa3b, v0
	v_xor_b32_e32 v0, 1, v249
	v_add_u32_e32 v35, 64, v35
	v_cmp_lt_i32_e32 vcc, v0, v35
	v_add_u32_e32 v79, 0, v38
	v_and_b32_e32 v76, 0x4f, v43
	v_cndmask_b32_e32 v0, v249, v0, vcc
	v_lshlrev_b32_e32 v71, 2, v0
	v_xor_b32_e32 v0, 2, v249
	v_cmp_lt_i32_e32 vcc, v0, v35
	v_lshlrev_b32_e32 v34, 2, v83
	v_lshlrev_b32_e32 v36, 1, v39
	v_cndmask_b32_e32 v0, v249, v0, vcc
	v_lshlrev_b32_e32 v72, 2, v0
	v_xor_b32_e32 v0, 4, v249
	v_cmp_lt_i32_e32 vcc, v0, v35
	v_mad_u32_u24 v82, v76, s67, v79
	v_or_b32_e32 v78, 0x80, v34
	v_cndmask_b32_e32 v0, v249, v0, vcc
	v_lshlrev_b32_e32 v73, 2, v0
	v_xor_b32_e32 v0, 8, v249
	v_cmp_lt_i32_e32 vcc, v0, v35
	v_mul_u32_u24_e32 v35, 0x150, v80
	v_add3_u32 v69, v87, v35, v36
	v_add_u32_e32 v85, 0, v36
	v_or_b32_e32 v68, s13, v34
	ds_read_b128 v[34:37], v82
	ds_read_b128 v[38:41], v82 offset:64
	s_waitcnt lgkmcnt(1)
	v_mfma_f32_16x16x32_bf16 v[34:37], v[30:33], v[34:37], 0
	v_or_b32_e32 v95, v78, v81
	s_cmp_lg_u32 s12, 0
	s_cselect_b64 s[42:43], -1, 0
	s_waitcnt lgkmcnt(0)
	v_mfma_f32_16x16x32_bf16 v[62:65], v[26:29], v[38:41], v[34:37]
	ds_read_b128 v[38:41], v82 offset:2368
	v_cndmask_b32_e32 v0, v249, v0, vcc
	s_movk_i32 s8, 0x7f
	ds_read_b128 v[34:37], v82 offset:2304
	s_waitcnt lgkmcnt(0)
	v_mfma_f32_16x16x32_bf16 v[34:37], v[30:33], v[34:37], 0
	s_movk_i32 s9, 0x7e
	s_movk_i32 s10, 0x7d
	v_lshlrev_b32_e32 v74, 2, v0
	v_mfma_f32_16x16x32_bf16 v[58:61], v[26:29], v[38:41], v[34:37]
	ds_read_b128 v[38:41], v82 offset:4672
	v_lshlrev_b32_e32 v0, 1, v80
	s_add_i32 s24, s24, s90
	s_nop 0
	ds_read_b128 v[34:37], v82 offset:4608
	s_waitcnt lgkmcnt(0)
	v_mfma_f32_16x16x32_bf16 v[34:37], v[30:33], v[34:37], 0
	ds_read_b128 v[88:91], v82 offset:16192
	s_waitcnt vmcnt(0)
	v_mul_f32_e32 v77, 0x3fb8aa3b, v70
	v_mfma_f32_16x16x32_bf16 v[54:57], v[26:29], v[38:41], v[34:37]
	ds_read_b128 v[38:41], v82 offset:6976
	s_nop 2
	ds_read_b128 v[34:37], v82 offset:6912
	s_waitcnt lgkmcnt(0)
	v_mfma_f32_16x16x32_bf16 v[34:37], v[30:33], v[34:37], 0
	v_mfma_f32_16x16x32_bf16 v[50:53], v[26:29], v[38:41], v[34:37]
	ds_read_b128 v[38:41], v82 offset:9280
	s_nop 5
	ds_read_b128 v[34:37], v82 offset:9216
	s_waitcnt lgkmcnt(0)
	v_mfma_f32_16x16x32_bf16 v[34:37], v[30:33], v[34:37], 0
	v_mfma_f32_16x16x32_bf16 v[46:49], v[26:29], v[38:41], v[34:37]
	ds_read_b128 v[38:41], v82 offset:11584
	s_nop 5
	ds_read_b128 v[34:37], v82 offset:11520
	s_waitcnt lgkmcnt(0)
	v_mfma_f32_16x16x32_bf16 v[34:37], v[30:33], v[34:37], 0
	v_mfma_f32_16x16x32_bf16 v[42:45], v[26:29], v[38:41], v[34:37]
	ds_read_b128 v[38:41], v82 offset:13888
	s_nop 5
	ds_read_b128 v[34:37], v82 offset:13824
	s_waitcnt lgkmcnt(0)
	v_mfma_f32_16x16x32_bf16 v[34:37], v[30:33], v[34:37], 0
	v_mfma_f32_16x16x32_bf16 v[38:41], v[26:29], v[38:41], v[34:37]
	s_nop 6
	ds_read_b128 v[34:37], v82 offset:16128
	s_waitcnt lgkmcnt(0)
	v_mfma_f32_16x16x32_bf16 v[34:37], v[30:33], v[34:37], 0
	v_mfma_f32_16x16x32_bf16 v[34:37], v[26:29], v[88:91], v[34:37]
	ds_read_b128 v[88:91], v82 offset:18432
	s_waitcnt lgkmcnt(0)
	v_mfma_f32_16x16x32_bf16 v[30:33], v[30:33], v[88:91], 0
	ds_read_b128 v[88:91], v82 offset:18496
	s_waitcnt lgkmcnt(0)
	v_mfma_f32_16x16x32_bf16 v[26:29], v[26:29], v[88:91], v[30:33]
	s_nop 4
	v_sub_u32_e32 v30, v95, v76
	v_cvt_f32_ubyte0_e32 v31, v30
	v_cmp_gt_u32_e32 vcc, s20, v30
	v_mul_f32_e32 v31, v75, v31
	s_and_b64 vcc, s[42:43], vcc
	v_fma_f32 v31, v62, s36, -v31
	v_cndmask_b32_e32 v33, v251, v31, vcc
	v_add_u32_e32 v31, 1, v30
	v_cvt_f32_u32_e32 v31, v31
	v_cmp_gt_u32_e32 vcc, s8, v30
	s_and_b64 vcc, s[42:43], vcc
	v_add_u32_e32 v82, 3, v30
	v_mul_f32_e32 v31, v75, v31
	v_fma_f32 v31, v63, s36, -v31
	v_cndmask_b32_e32 v32, v251, v31, vcc
	v_add_u32_e32 v31, 2, v30
	v_cvt_f32_u32_e32 v31, v31
	v_cmp_gt_u32_e32 vcc, s9, v30
	s_and_b64 vcc, s[42:43], vcc
	v_max_f32_e32 v62, v77, v33
	v_mul_f32_e32 v31, v75, v31
	v_fma_f32 v31, v64, s36, -v31
	v_cndmask_b32_e32 v31, v251, v31, vcc
	v_cmp_gt_u32_e32 vcc, s10, v30
	v_cvt_f32_u32_e32 v30, v82
	v_or_b32_e32 v82, 16, v81
	v_or_b32_e32 v86, v82, v80
	v_sub_u32_e32 v84, v95, v86
	v_cvt_f32_ubyte0_e32 v88, v84
	v_mul_f32_e32 v88, v75, v88
	v_fma_f32 v58, v58, s36, -v88
	v_add_u32_e32 v88, 1, v84
	v_cvt_f32_u32_e32 v88, v88
	v_mul_f32_e32 v30, v75, v30
	s_and_b64 vcc, s[42:43], vcc
	v_fma_f32 v30, v65, s36, -v30
	v_mul_f32_e32 v88, v75, v88
	v_fma_f32 v59, v59, s36, -v88
	v_cndmask_b32_e64 v92, v251, v59, s[42:43]
	v_add_u32_e32 v59, 2, v84
	v_cvt_f32_u32_e32 v59, v59
	v_cndmask_b32_e32 v30, v251, v30, vcc
	v_max_f32_e32 v65, v77, v30
	v_cndmask_b32_e64 v58, v251, v58, s[42:43]
	v_mul_f32_e32 v59, v75, v59
	v_fma_f32 v59, v60, s36, -v59
	v_cndmask_b32_e64 v88, v251, v59, s[42:43]
	v_add_u32_e32 v59, 3, v84
	v_cvt_f32_u32_e32 v59, v59
	v_or_b32_e32 v60, 32, v81
	v_or_b32_e32 v84, v60, v80
	v_max_f32_e32 v64, v77, v31
	v_mul_f32_e32 v59, v75, v59
	v_fma_f32 v59, v61, s36, -v59
	v_cndmask_b32_e64 v90, v251, v59, s[42:43]
	v_sub_u32_e32 v59, v95, v84
	v_cvt_f32_ubyte0_e32 v61, v59
	v_mul_f32_e32 v61, v75, v61
	v_fma_f32 v54, v54, s36, -v61
	v_add_u32_e32 v61, 1, v59
; #define LAS __attribute__((address_space(3)))
; __device__ __forceinline__ f32x4 mfma16(bf16x8 a, bf16x8 b, f32x4 c) { return __builtin_amdgcn_mfma_f32_16x16x32_bf16(a, b, c, 0, 0, 0); }
; __device__ __forceinline__ void swa_unit(LAS unsigned char* L, bf16_t* Z, const float* sinks, int b, int qb, int kvh) {
;     ...
;         for (int n = 0; n < 9; ++n) { const LAS bf16_t* kb = Ks + (kbase + 16 * n + l15) * 72 + quad * 8; f32x4 a4 = (f32x4){0.f, 0.f, 0.f, 0.f};
;             a4 = mfma16(qa0, *(const LAS bf16x8*)kb, a4); a4 = mfma16(qa1, *(const LAS bf16x8*)(kb + 32), a4); sc[n] = a4; }
;         float mx[4] = {sink, sink, sink, sink};
; #pragma unroll
;         for (int n = 0; n < 9; ++n)
; #pragma unroll
;             for (int j = 0; j < 4; ++j) { const int qi = kbase + quad * 4 + j, kk = kbase + 16 * n + l15; const int dist = qi + 128 - kk;
;                 const bool valid = ((n >= 1 && n <= 7) || ((dist >= 0) && (dist < 128))) && (kk >= kmin);
;                 const float lg = valid ? sc[n][j] * (0.125f * 1.4426950408889634f) - slope * (float)dist : -INFINITY; sc[n][j] = lg; mx[j] = fmaxf(mx[j], lg); }
; #pragma unroll
;         for (int j = 0; j < 4; ++j) { mx[j] = fmaxf(mx[j], __shfl_xor(mx[j], 1)); mx[j] = fmaxf(mx[j], __shfl_xor(mx[j], 2)); mx[j] = fmaxf(mx[j], __shfl_xor(mx[j], 4)); mx[j] = fmaxf(mx[j], __shfl_xor(mx[j], 8)); }
	v_cvt_f32_u32_e32 v61, v61
	v_cndmask_b32_e64 v54, v251, v54, s[42:43]
	v_max3_f32 v62, v62, v58, v54
	v_max_f32_e32 v63, v77, v32
	v_mul_f32_e32 v61, v75, v61
	v_fma_f32 v55, v55, s36, -v61
	v_add_u32_e32 v61, 2, v59
	v_cvt_f32_u32_e32 v61, v61
	v_cndmask_b32_e64 v55, v251, v55, s[42:43]
	v_max3_f32 v63, v63, v92, v55
	v_mul_f32_e32 v61, v75, v61
	v_fma_f32 v56, v56, s36, -v61
	v_cndmask_b32_e64 v91, v251, v56, s[42:43]
	v_add_u32_e32 v56, 3, v59
	v_cvt_f32_u32_e32 v56, v56
	v_max3_f32 v64, v64, v88, v91
	v_mul_f32_e32 v56, v75, v56
	v_fma_f32 v56, v57, s36, -v56
	v_cndmask_b32_e64 v94, v251, v56, s[42:43]
	v_or_b32_e32 v56, 48, v81
	v_or_b32_e32 v61, v56, v80
	v_sub_u32_e32 v59, v95, v61
	v_max3_f32 v57, v65, v90, v94
	v_cvt_f32_ubyte0_e32 v65, v59
	v_mul_f32_e32 v65, v75, v65
	v_fma_f32 v50, v50, s36, -v65
	v_cndmask_b32_e64 v89, v251, v50, s[42:43]
	v_add_u32_e32 v50, 1, v59
	v_cvt_f32_u32_e32 v50, v50
	v_or_b32_e32 v65, s12, v81
	v_cmp_eq_u32_e32 vcc, 0, v65
	v_mul_f32_e32 v50, v75, v50
	v_fma_f32 v50, v51, s36, -v50
	v_add_u32_e32 v51, 3, v59
	v_cvt_f32_u32_e32 v51, v51
	v_cndmask_b32_e64 v93, v251, v50, s[42:43]
	v_add_u32_e32 v50, 2, v59
	v_cvt_f32_u32_e32 v50, v50
	v_mul_f32_e32 v51, v75, v51
	v_fma_f32 v51, v53, s36, -v51
	v_add_u32_e32 v53, v81, v80
	v_mul_f32_e32 v50, v75, v50
	v_add_u32_e32 v59, 64, v53
	v_fma_f32 v50, v52, s36, -v50
	v_sub_u32_e32 v52, v95, v59
	v_cvt_f32_i32_e32 v65, v52
	v_cndmask_b32_e64 v50, v251, v50, s[42:43]
	v_cndmask_b32_e64 v51, v251, v51, s[42:43]
	v_mul_f32_e32 v65, v75, v65
	v_fma_f32 v46, v46, s36, -v65
	v_cndmask_b32_e32 v46, v46, v251, vcc
	v_max3_f32 v65, v62, v89, v46
	v_add_u32_e32 v62, 1, v52
	v_cvt_f32_i32_e32 v62, v62
	v_mul_f32_e32 v62, v75, v62
	v_fma_f32 v47, v47, s36, -v62
	v_add_u32_e32 v62, 2, v52
	v_cvt_f32_i32_e32 v62, v62
	v_add_u32_e32 v52, 3, v52
	v_cvt_f32_i32_e32 v52, v52
	v_cndmask_b32_e32 v47, v47, v251, vcc
	v_mul_f32_e32 v62, v75, v62
	v_fma_f32 v48, v48, s36, -v62
	v_cndmask_b32_e32 v48, v48, v251, vcc
	v_max3_f32 v96, v64, v50, v48
	v_add_u32_e32 v64, 0x50, v53
	v_mul_f32_e32 v52, v75, v52
	v_sub_u32_e32 v62, v95, v64
	v_fma_f32 v49, v49, s36, -v52
	v_cvt_f32_i32_e32 v52, v62
	v_max3_f32 v63, v63, v93, v47
	v_cndmask_b32_e32 v49, v49, v251, vcc
	v_max3_f32 v57, v57, v51, v49
	v_mul_f32_e32 v52, v75, v52
	v_fma_f32 v42, v42, s36, -v52
	v_cndmask_b32_e32 v52, v42, v251, vcc
	v_add_u32_e32 v42, 1, v62
	v_cvt_f32_i32_e32 v42, v42
	v_mul_f32_e32 v42, v75, v42
	v_fma_f32 v42, v43, s36, -v42
	v_cndmask_b32_e32 v43, v42, v251, vcc
	v_add_u32_e32 v42, 2, v62
	v_cvt_f32_i32_e32 v42, v42
	v_mul_f32_e32 v42, v75, v42
	v_fma_f32 v42, v44, s36, -v42
	v_cndmask_b32_e32 v44, v42, v251, vcc
	v_add_u32_e32 v42, 3, v62
	v_cvt_f32_i32_e32 v42, v42
	v_add_u32_e32 v62, 0x60, v53
	v_mul_f32_e32 v42, v75, v42
	v_fma_f32 v42, v45, s36, -v42
	v_sub_u32_e32 v45, v95, v62
	v_cvt_f32_i32_e32 v97, v45
	v_cndmask_b32_e32 v42, v42, v251, vcc
	v_mul_f32_e32 v97, v75, v97
	v_fma_f32 v38, v38, s36, -v97
	v_cndmask_b32_e32 v38, v38, v251, vcc
	v_max3_f32 v97, v65, v52, v38
	v_add_u32_e32 v65, 1, v45
	v_cvt_f32_i32_e32 v65, v65
	v_mul_f32_e32 v65, v75, v65
	v_fma_f32 v39, v39, s36, -v65
	v_cndmask_b32_e32 v39, v39, v251, vcc
	v_max3_f32 v98, v63, v43, v39
	v_add_u32_e32 v63, 2, v45
	v_add_u32_e32 v45, 3, v45
	v_cvt_f32_i32_e32 v45, v45
	v_add_u32_e32 v65, 0x70, v53
	v_sub_u32_e32 v53, v95, v65
	v_cvt_f32_i32_e32 v63, v63
	v_mul_f32_e32 v45, v75, v45
	v_fma_f32 v41, v41, s36, -v45
	v_cvt_f32_i32_e32 v45, v53
	v_mul_f32_e32 v63, v75, v63
	v_fma_f32 v40, v40, s36, -v63
	v_or_b32_e32 v63, 0x80, v76
	v_mul_f32_e32 v45, v75, v45
	v_fma_f32 v34, v34, s36, -v45
	v_cndmask_b32_e32 v45, v34, v251, vcc
	v_add_u32_e32 v34, 1, v53
	v_cvt_f32_i32_e32 v34, v34
	v_cndmask_b32_e32 v40, v40, v251, vcc
	v_max3_f32 v96, v96, v44, v40
	v_cndmask_b32_e32 v41, v41, v251, vcc
	v_mul_f32_e32 v34, v75, v34
	v_fma_f32 v34, v35, s36, -v34
	v_cndmask_b32_e32 v35, v34, v251, vcc
	v_add_u32_e32 v34, 2, v53
	v_cvt_f32_i32_e32 v34, v34
	v_max3_f32 v57, v57, v42, v41
	v_mul_f32_e32 v34, v75, v34
	v_fma_f32 v34, v36, s36, -v34
	v_cndmask_b32_e32 v36, v34, v251, vcc
	v_add_u32_e32 v34, 3, v53
	v_cvt_f32_i32_e32 v34, v34
	v_sub_u32_e32 v53, v95, v63
	v_cmp_gt_u32_e64 s[0:1], s20, v53
	v_add_u32_e32 v95, 1, v53
	v_mul_f32_e32 v34, v75, v34
	v_fma_f32 v34, v37, s36, -v34
	v_cvt_f32_i32_e32 v37, v53
	v_cndmask_b32_e32 v34, v34, v251, vcc
	v_mul_f32_e32 v37, v75, v37
	v_fma_f32 v26, v26, s36, -v37
	v_cndmask_b32_e64 v37, v251, v26, s[0:1]
	v_cmp_gt_u32_e64 s[0:1], s20, v95
	v_cvt_f32_i32_e32 v95, v95
	v_max3_f32 v26, v97, v45, v37
	v_add_u32_e32 v97, 2, v53
	v_add_u32_e32 v53, 3, v53
	v_mul_f32_e32 v95, v75, v95
	v_fma_f32 v27, v27, s36, -v95
	v_cndmask_b32_e64 v27, v251, v27, s[0:1]
	v_cmp_gt_u32_e64 s[0:1], s20, v97
	v_cvt_f32_i32_e32 v97, v97
	v_max3_f32 v95, v98, v35, v27
	v_mul_f32_e32 v97, v75, v97
	v_fma_f32 v28, v28, s36, -v97
	v_cndmask_b32_e64 v28, v251, v28, s[0:1]
	v_cmp_gt_u32_e64 s[0:1], s20, v53
	v_cvt_f32_i32_e32 v53, v53
	v_max3_f32 v96, v96, v36, v28
	v_mul_f32_e32 v53, v75, v53
	v_fma_f32 v29, v29, s36, -v53
	v_cndmask_b32_e64 v53, v251, v29, s[0:1]
	s_nop 1
	v_mov_b32_dpp v29, v26 quad_perm:[1,0,3,2] row_mask:0xf bank_mask:0xf
	v_max3_f32 v57, v57, v34, v53
	s_waitcnt lgkmcnt(0)
	v_max_f32_e32 v29, v29, v29
	v_max_f32_e32 v26, v26, v29
	s_nop 1
	v_mov_b32_dpp v29, v26 quad_perm:[2,3,0,1] row_mask:0xf bank_mask:0xf
	s_waitcnt lgkmcnt(0)
	v_max_f32_e32 v29, v29, v29
	v_max_f32_e32 v26, v26, v29
	s_nop 1
	v_mov_b32_dpp v29, v26 row_half_mirror row_mask:0xf bank_mask:0xf
	s_waitcnt lgkmcnt(0)
; __device__ __forceinline__ unsigned hwbf(float f) { return cvt_pk_bf16(f, 0.f) & 0xffffu; }
; __device__ __forceinline__ void swa_unit(LAS unsigned char* L, bf16_t* Z, const float* sinks, int b, int qb, int kvh) {
;     ...
;         for (int j = 0; j < 4; ++j) { mx[j] = fmaxf(mx[j], __shfl_xor(mx[j], 1)); mx[j] = fmaxf(mx[j], __shfl_xor(mx[j], 2)); mx[j] = fmaxf(mx[j], __shfl_xor(mx[j], 4)); mx[j] = fmaxf(mx[j], __shfl_xor(mx[j], 8)); }
;         float sum[4] = {0.f, 0.f, 0.f, 0.f};
; #pragma unroll
;         for (int n = 0; n < 9; ++n)
; #pragma unroll
;             for (int j = 0; j < 4; ++j) { const float p = __builtin_amdgcn_exp2f(sc[n][j] - mx[j]); sum[j] += p; Pw[(quad * 4 + j) * 168 + 16 * n + l15] = (bf16_t)hwbf(p); }
	v_max_f32_e32 v29, v29, v29
	v_max_f32_e32 v26, v26, v29
	s_nop 1
	v_mov_b32_dpp v29, v26 row_mirror row_mask:0xf bank_mask:0xf
	s_waitcnt lgkmcnt(0)
	v_max_f32_e32 v29, v29, v29
	v_max_f32_e32 v26, v26, v29
	s_nop 1
	v_mov_b32_dpp v29, v95 quad_perm:[1,0,3,2] row_mask:0xf bank_mask:0xf
	v_sub_f32_e32 v33, v33, v26
	v_exp_f32_e32 v33, v33
	s_waitcnt lgkmcnt(0)
	v_max_f32_e32 v29, v29, v29
	v_max_f32_e32 v29, v95, v29
	s_nop 1
	v_mov_b32_dpp v95, v29 quad_perm:[2,3,0,1] row_mask:0xf bank_mask:0xf
	v_add_f32_e32 v97, 0, v33
	s_nop 1
	v_cvt_pk_bf16_f32 v33, v33, v1
	s_waitcnt lgkmcnt(0)
	v_max_f32_e32 v95, v95, v95
	v_max_f32_e32 v29, v29, v95
	s_nop 1
	v_mov_b32_dpp v95, v29 row_half_mirror row_mask:0xf bank_mask:0xf
	s_waitcnt lgkmcnt(0)
	v_max_f32_e32 v95, v95, v95
	v_max_f32_e32 v29, v29, v95
	s_nop 1
	v_mov_b32_dpp v95, v29 row_mirror row_mask:0xf bank_mask:0xf
	s_waitcnt lgkmcnt(0)
	v_max_f32_e32 v95, v95, v95
	v_max_f32_e32 v29, v29, v95
	s_nop 1
	v_mov_b32_dpp v95, v96 quad_perm:[1,0,3,2] row_mask:0xf bank_mask:0xf
	v_sub_f32_e32 v32, v32, v29
	v_exp_f32_e32 v32, v32
	v_sub_f32_e32 v27, v27, v29
	v_exp_f32_e32 v27, v27
	s_waitcnt lgkmcnt(0)
	v_max_f32_e32 v95, v95, v95
	v_max_f32_e32 v95, v96, v95
	s_nop 1
	v_mov_b32_dpp v96, v95 quad_perm:[2,3,0,1] row_mask:0xf bank_mask:0xf
	s_waitcnt lgkmcnt(0)
	v_max_f32_e32 v96, v96, v96
	v_max_f32_e32 v95, v95, v96
	s_nop 1
	v_mov_b32_dpp v96, v95 row_half_mirror row_mask:0xf bank_mask:0xf
	s_waitcnt lgkmcnt(0)
	v_max_f32_e32 v96, v96, v96
	v_max_f32_e32 v95, v95, v96
	s_nop 1
	v_mov_b32_dpp v96, v95 row_mirror row_mask:0xf bank_mask:0xf
	s_waitcnt lgkmcnt(0)
	v_max_f32_e32 v96, v96, v96
	v_max_f32_e32 v95, v95, v96
	s_nop 1
	v_mov_b32_dpp v96, v57 quad_perm:[1,0,3,2] row_mask:0xf bank_mask:0xf
	v_sub_f32_e32 v31, v31, v95
	v_exp_f32_e32 v31, v31
	s_waitcnt lgkmcnt(0)
	v_max_f32_e32 v96, v96, v96
	v_max_f32_e32 v57, v57, v96
	s_nop 1
	v_mov_b32_dpp v96, v57 quad_perm:[2,3,0,1] row_mask:0xf bank_mask:0xf
	s_waitcnt lgkmcnt(0)
	v_max_f32_e32 v96, v96, v96
	v_max_f32_e32 v57, v57, v96
	s_nop 1
	v_mov_b32_dpp v96, v57 row_half_mirror row_mask:0xf bank_mask:0xf
	s_waitcnt lgkmcnt(0)
	v_max_f32_e32 v96, v96, v96
	v_max_f32_e32 v57, v57, v96
	s_nop 1
	v_mov_b32_dpp v96, v57 row_mirror row_mask:0xf bank_mask:0xf
	s_waitcnt lgkmcnt(0)
	v_max_f32_e32 v96, v96, v96
	v_max_f32_e32 v96, v57, v96
	v_sub_f32_e32 v30, v30, v96
	v_mul_u32_u24_e32 v57, 0x540, v83
	v_exp_f32_e32 v30, v30
	v_add3_u32 v57, v87, v0, v57
	ds_write_b16 v57, v33
	v_add_f32_e32 v33, 0, v32
	s_nop 1
	v_cvt_pk_bf16_f32 v32, v32, v1
	ds_write_b16 v57, v32 offset:336
	v_add_f32_e32 v32, 0, v31
	s_nop 1
	v_cvt_pk_bf16_f32 v31, v31, v1
	ds_write_b16 v57, v31 offset:672
	v_add_f32_e32 v31, 0, v30
	s_nop 1
	v_cvt_pk_bf16_f32 v30, v30, v1
	ds_write_b16 v57, v30 offset:1008
	v_sub_f32_e32 v30, v58, v26
	v_exp_f32_e32 v30, v30
	s_nop 0
	v_add_f32_e32 v58, v30, v97
	s_nop 1
	v_cvt_pk_bf16_f32 v30, v30, v1
	ds_write_b16 v57, v30 offset:32
	v_sub_f32_e32 v30, v92, v29
	v_exp_f32_e32 v30, v30
	s_nop 0
	v_add_f32_e32 v33, v30, v33
	s_nop 1
	v_cvt_pk_bf16_f32 v30, v30, v1
	ds_write_b16 v57, v30 offset:368
	v_sub_f32_e32 v30, v88, v95
	v_exp_f32_e32 v30, v30
	s_nop 0
	v_add_f32_e32 v32, v30, v32
	s_nop 1
	v_cvt_pk_bf16_f32 v30, v30, v1
	ds_write_b16 v57, v30 offset:704
	v_sub_f32_e32 v30, v90, v96
	v_exp_f32_e32 v30, v30
	s_nop 0
	v_add_f32_e32 v31, v30, v31
	s_nop 1
	v_cvt_pk_bf16_f32 v30, v30, v1
	ds_write_b16 v57, v30 offset:1040
	v_sub_f32_e32 v30, v54, v26
	v_exp_f32_e32 v30, v30
	s_nop 0
	v_add_f32_e32 v54, v30, v58
	s_nop 1
	v_cvt_pk_bf16_f32 v30, v30, v1
	ds_write_b16 v57, v30 offset:64
	v_sub_f32_e32 v30, v55, v29
	v_exp_f32_e32 v30, v30
	s_nop 0
	v_add_f32_e32 v33, v30, v33
	s_nop 1
	v_cvt_pk_bf16_f32 v30, v30, v1
	ds_write_b16 v57, v30 offset:400
	v_sub_f32_e32 v30, v91, v95
	v_exp_f32_e32 v30, v30
	s_nop 0
	v_add_f32_e32 v32, v30, v32
	s_nop 1
	v_cvt_pk_bf16_f32 v30, v30, v1
	ds_write_b16 v57, v30 offset:736
	v_sub_f32_e32 v30, v94, v96
	v_exp_f32_e32 v30, v30
	s_nop 0
	v_add_f32_e32 v31, v30, v31
	s_nop 1
	v_cvt_pk_bf16_f32 v30, v30, v1
	ds_write_b16 v57, v30 offset:1072
	v_sub_f32_e32 v30, v89, v26
	v_exp_f32_e32 v30, v30
	s_nop 0
	v_add_f32_e32 v54, v30, v54
	s_nop 1
	v_cvt_pk_bf16_f32 v30, v30, v1
	ds_write_b16 v57, v30 offset:96
	v_sub_f32_e32 v30, v93, v29
	v_exp_f32_e32 v30, v30
	s_nop 0
	v_add_f32_e32 v33, v30, v33
	s_nop 1
	v_cvt_pk_bf16_f32 v30, v30, v1
	ds_write_b16 v57, v30 offset:432
	v_sub_f32_e32 v30, v50, v95
	v_exp_f32_e32 v30, v30
	s_nop 0
	v_add_f32_e32 v32, v30, v32
	s_nop 1
	v_cvt_pk_bf16_f32 v30, v30, v1
	ds_write_b16 v57, v30 offset:768
	v_sub_f32_e32 v30, v51, v96
	v_exp_f32_e32 v30, v30
	s_nop 0
	v_add_f32_e32 v31, v30, v31
	s_nop 1
	v_cvt_pk_bf16_f32 v30, v30, v1
	ds_write_b16 v57, v30 offset:1104
	v_sub_f32_e32 v30, v46, v26
	v_exp_f32_e32 v30, v30
	s_nop 0
	v_add_f32_e32 v46, v30, v54
	s_nop 1
	v_cvt_pk_bf16_f32 v30, v30, v1
	ds_write_b16 v57, v30 offset:128
	v_sub_f32_e32 v30, v47, v29
	v_exp_f32_e32 v30, v30
	v_mov_b64_e32 v[54:55], s[68:69]
	v_add_f32_e32 v33, v30, v33
	s_nop 1
	v_cvt_pk_bf16_f32 v30, v30, v1
	ds_write_b16 v57, v30 offset:464
	v_sub_f32_e32 v30, v48, v95
	v_exp_f32_e32 v30, v30
	s_nop 0
	v_add_f32_e32 v32, v30, v32
	s_nop 1
	v_cvt_pk_bf16_f32 v30, v30, v1
	ds_write_b16 v57, v30 offset:800
	v_sub_f32_e32 v30, v49, v96
	v_exp_f32_e32 v30, v30
	s_nop 0
	v_add_f32_e32 v31, v30, v31
	s_nop 1
	v_cvt_pk_bf16_f32 v30, v30, v1
	ds_write_b16 v57, v30 offset:1136
	v_sub_f32_e32 v30, v52, v26
	v_exp_f32_e32 v30, v30
	s_nop 0
	v_add_f32_e32 v46, v30, v46
	s_nop 1
	v_cvt_pk_bf16_f32 v30, v30, v1
; #define LAS __attribute__((address_space(3)))
; __device__ __forceinline__ unsigned hwbf(float f) { return cvt_pk_bf16(f, 0.f) & 0xffffu; }
; __device__ __forceinline__ f32x4 mfma16(bf16x8 a, bf16x8 b, f32x4 c) { return __builtin_amdgcn_mfma_f32_16x16x32_bf16(a, b, c, 0, 0, 0); }
; __device__ __forceinline__ void swa_unit(LAS unsigned char* L, bf16_t* Z, const float* sinks, int b, int qb, int kvh) {
;     ...
;         for (int n = 0; n < 9; ++n)
; #pragma unroll
;             for (int j = 0; j < 4; ++j) { const float p = __builtin_amdgcn_exp2f(sc[n][j] - mx[j]); sum[j] += p; Pw[(quad * 4 + j) * 168 + 16 * n + l15] = (bf16_t)hwbf(p); }
;         float rden[4];
; #pragma unroll
;         for (int j = 0; j < 4; ++j) { sum[j] += __shfl_xor(sum[j], 1); sum[j] += __shfl_xor(sum[j], 2); sum[j] += __shfl_xor(sum[j], 4); sum[j] += __shfl_xor(sum[j], 8);
;             rden[j] = __builtin_amdgcn_rcpf(sum[j] + __builtin_amdgcn_exp2f(sink - mx[j])); }
;         asm volatile("s_waitcnt lgkmcnt(0)" ::: "memory");
;         f32x4 o4[4];
; #pragma unroll
;         for (int nd = 0; nd < 4; ++nd) o4[nd] = (f32x4){0.f, 0.f, 0.f, 0.f};
; #pragma unroll
;         for (int ks = 0; ks < 5; ++ks) { const bf16x8 a = *(const LAS bf16x8*)(Pw + l15 * 168 + ks * 32 + quad * 8);
; #pragma unroll
;             for (int nd = 0; nd < 4; ++nd) o4[nd] = mfma16(a, *(const LAS bf16x8*)(Vt + (nd * 16 + l15) * 280 + kbase + ks * 32 + quad * 8), o4[nd]); }
	ds_write_b16 v57, v30 offset:160
	v_sub_f32_e32 v30, v43, v29
	v_exp_f32_e32 v30, v30
	s_nop 0
	v_add_f32_e32 v33, v30, v33
	s_nop 1
	v_cvt_pk_bf16_f32 v30, v30, v1
	ds_write_b16 v57, v30 offset:496
	v_sub_f32_e32 v30, v44, v95
	v_exp_f32_e32 v30, v30
	s_nop 0
	v_add_f32_e32 v32, v30, v32
	s_nop 1
	v_cvt_pk_bf16_f32 v30, v30, v1
	ds_write_b16 v57, v30 offset:832
	v_sub_f32_e32 v30, v42, v96
	v_exp_f32_e32 v30, v30
	s_nop 0
	v_add_f32_e32 v31, v30, v31
	s_nop 1
	v_cvt_pk_bf16_f32 v30, v30, v1
	ds_write_b16 v57, v30 offset:1168
	v_sub_f32_e32 v30, v38, v26
	v_exp_f32_e32 v30, v30
	s_nop 0
	v_add_f32_e32 v38, v30, v46
	s_nop 1
	v_cvt_pk_bf16_f32 v30, v30, v1
	ds_write_b16 v57, v30 offset:192
	v_sub_f32_e32 v30, v39, v29
	v_exp_f32_e32 v30, v30
	s_nop 0
	v_add_f32_e32 v33, v30, v33
	s_nop 1
	v_cvt_pk_bf16_f32 v30, v30, v1
	ds_write_b16 v57, v30 offset:528
	v_sub_f32_e32 v30, v40, v95
	v_exp_f32_e32 v30, v30
	s_nop 0
	v_add_f32_e32 v32, v30, v32
	s_nop 1
	v_cvt_pk_bf16_f32 v30, v30, v1
	ds_write_b16 v57, v30 offset:864
	v_sub_f32_e32 v30, v41, v96
	v_exp_f32_e32 v30, v30
	s_nop 0
	v_add_f32_e32 v31, v30, v31
	s_nop 1
	v_cvt_pk_bf16_f32 v30, v30, v1
	ds_write_b16 v57, v30 offset:1200
	v_sub_f32_e32 v30, v45, v26
	v_exp_f32_e32 v30, v30
	s_nop 0
	v_add_f32_e32 v38, v30, v38
	s_nop 1
	v_cvt_pk_bf16_f32 v30, v30, v1
	ds_write_b16 v57, v30 offset:224
	v_sub_f32_e32 v30, v35, v29
	v_exp_f32_e32 v30, v30
	s_nop 0
	v_add_f32_e32 v33, v30, v33
	s_nop 1
	v_cvt_pk_bf16_f32 v30, v30, v1
	ds_write_b16 v57, v30 offset:560
	v_sub_f32_e32 v30, v36, v95
	v_exp_f32_e32 v30, v30
	s_nop 0
	v_add_f32_e32 v32, v30, v32
	s_nop 1
	v_cvt_pk_bf16_f32 v30, v30, v1
	ds_write_b16 v57, v30 offset:896
	v_sub_f32_e32 v30, v34, v96
	v_exp_f32_e32 v30, v30
	s_nop 0
	v_add_f32_e32 v31, v30, v31
	s_nop 1
	v_cvt_pk_bf16_f32 v30, v30, v1
	ds_write_b16 v57, v30 offset:1232
	v_sub_f32_e32 v30, v37, v26
	v_exp_f32_e32 v30, v30
	v_fma_f32 v26, v70, s34, -v26
	v_exp_f32_e32 v26, v26
	v_add_f32_e32 v34, v30, v38
	s_nop 1
	v_cvt_pk_bf16_f32 v30, v30, v1
	ds_write_b16 v57, v30 offset:256
	v_add_f32_e32 v30, v27, v33
	s_nop 1
	v_cvt_pk_bf16_f32 v27, v27, v1
	ds_write_b16 v57, v27 offset:592
	v_sub_f32_e32 v27, v28, v95
	v_exp_f32_e32 v27, v27
	s_nop 0
	v_add_f32_e32 v28, v27, v32
	s_nop 1
	v_cvt_pk_bf16_f32 v27, v27, v1
	ds_write_b16 v57, v27 offset:928
	v_sub_f32_e32 v27, v53, v96
	v_exp_f32_e32 v27, v27
	s_nop 0
	v_add_f32_e32 v31, v27, v31
	s_nop 1
	v_cvt_pk_bf16_f32 v27, v27, v1
	ds_write_b16 v57, v27 offset:1264
	s_nop 1
	v_mov_b32_dpp v27, v34 quad_perm:[1,0,3,2] row_mask:0xf bank_mask:0xf
	s_waitcnt lgkmcnt(0)
	s_waitcnt lgkmcnt(0)
	v_add_f32_e32 v27, v34, v27
	s_nop 1
	v_mov_b32_dpp v32, v27 quad_perm:[2,3,0,1] row_mask:0xf bank_mask:0xf
	s_waitcnt lgkmcnt(0)
	v_add_f32_e32 v27, v27, v32
	s_nop 1
	v_mov_b32_dpp v32, v27 row_half_mirror row_mask:0xf bank_mask:0xf
	s_waitcnt lgkmcnt(0)
	v_add_f32_e32 v27, v27, v32
	s_nop 1
	v_mov_b32_dpp v32, v27 row_mirror row_mask:0xf bank_mask:0xf
	s_waitcnt lgkmcnt(0)
	v_add_f32_e32 v27, v27, v32
	v_add_f32_e32 v26, v26, v27
	v_rcp_f32_e32 v46, v26
	s_nop 1
	v_mov_b32_dpp v26, v30 quad_perm:[1,0,3,2] row_mask:0xf bank_mask:0xf
	s_waitcnt lgkmcnt(0)
	v_add_f32_e32 v26, v30, v26
	s_nop 1
	v_mov_b32_dpp v27, v26 quad_perm:[2,3,0,1] row_mask:0xf bank_mask:0xf
	v_lshlrev_b32_e32 v30, 1, v81
	s_waitcnt lgkmcnt(0)
	v_add_f32_e32 v26, v26, v27
	s_nop 1
	v_mov_b32_dpp v27, v26 row_half_mirror row_mask:0xf bank_mask:0xf
	s_waitcnt lgkmcnt(0)
	v_add_f32_e32 v26, v26, v27
	s_nop 1
	v_mov_b32_dpp v27, v26 row_mirror row_mask:0xf bank_mask:0xf
	s_waitcnt lgkmcnt(0)
	v_add_f32_e32 v26, v26, v27
	v_fma_f32 v27, v70, s34, -v29
	v_exp_f32_e32 v27, v27
	s_nop 0
	v_add_f32_e32 v26, v27, v26
	v_rcp_f32_e32 v47, v26
	s_nop 1
	v_mov_b32_dpp v26, v28 quad_perm:[1,0,3,2] row_mask:0xf bank_mask:0xf
	s_waitcnt lgkmcnt(0)
	v_add_f32_e32 v26, v28, v26
	s_nop 1
	v_mov_b32_dpp v27, v26 quad_perm:[2,3,0,1] row_mask:0xf bank_mask:0xf
	s_waitcnt lgkmcnt(0)
	v_add_f32_e32 v26, v26, v27
	s_nop 1
	v_mov_b32_dpp v27, v26 row_half_mirror row_mask:0xf bank_mask:0xf
	s_waitcnt lgkmcnt(0)
	v_add_f32_e32 v26, v26, v27
	s_nop 1
	v_mov_b32_dpp v27, v26 row_mirror row_mask:0xf bank_mask:0xf
	s_waitcnt lgkmcnt(0)
	v_add_f32_e32 v26, v26, v27
	v_fma_f32 v27, v70, s34, -v95
	v_exp_f32_e32 v27, v27
	s_nop 0
	v_add_f32_e32 v26, v27, v26
	v_rcp_f32_e32 v48, v26
	s_nop 1
	v_mov_b32_dpp v26, v31 quad_perm:[1,0,3,2] row_mask:0xf bank_mask:0xf
	s_waitcnt lgkmcnt(0)
	v_add_f32_e32 v26, v31, v26
	s_nop 1
	v_mov_b32_dpp v27, v26 quad_perm:[2,3,0,1] row_mask:0xf bank_mask:0xf
	v_mul_u32_u24_e32 v31, 0x230, v80
	v_add3_u32 v58, v85, v30, v31
	ds_read_b128 v[30:33], v58 offset:36864
	ds_read_b128 v[34:37], v58 offset:45824
	s_waitcnt lgkmcnt(2)
	v_add_f32_e32 v26, v26, v27
	s_nop 1
	v_mov_b32_dpp v27, v26 row_half_mirror row_mask:0xf bank_mask:0xf
	ds_read_b128 v[38:41], v58 offset:54784
	ds_read_b128 v[42:45], v58 offset:63744
	s_waitcnt lgkmcnt(2)
	v_add_f32_e32 v26, v26, v27
	s_nop 1
	v_mov_b32_dpp v27, v26 row_mirror row_mask:0xf bank_mask:0xf
	s_waitcnt lgkmcnt(0)
	v_add_f32_e32 v26, v26, v27
	v_fma_f32 v27, v70, s34, -v96
	v_exp_f32_e32 v27, v27
	s_nop 0
	v_add_f32_e32 v26, v27, v26
	v_rcp_f32_e32 v49, v26
	ds_read_b128 v[26:29], v69
	s_waitcnt lgkmcnt(0)
	v_mfma_f32_16x16x32_bf16 v[30:33], v[26:29], v[30:33], 0
	v_mfma_f32_16x16x32_bf16 v[34:37], v[26:29], v[34:37], 0
	v_mfma_f32_16x16x32_bf16 v[38:41], v[26:29], v[38:41], 0
	v_mfma_f32_16x16x32_bf16 v[26:29], v[26:29], v[42:45], 0
	ds_read_b128 v[42:45], v69 offset:64
	ds_read_b128 v[50:53], v58 offset:36928
	s_waitcnt lgkmcnt(0)
; #define LAS __attribute__((address_space(3)))
; __device__ __forceinline__ unsigned hwbf(float f) { return cvt_pk_bf16(f, 0.f) & 0xffffu; }
; __device__ __forceinline__ f32x4 mfma16(bf16x8 a, bf16x8 b, f32x4 c) { return __builtin_amdgcn_mfma_f32_16x16x32_bf16(a, b, c, 0, 0, 0); }
; __device__ __forceinline__ void swa_unit(LAS unsigned char* L, bf16_t* Z, const float* sinks, int b, int qb, int kvh) {
;     ...
;         for (int n = 0; n < 9; ++n) { const LAS bf16_t* kb = Ks + (kbase + 16 * n + l15) * 72 + quad * 8; f32x4 a4 = (f32x4){0.f, 0.f, 0.f, 0.f};
;             a4 = mfma16(qa0, *(const LAS bf16x8*)kb, a4); a4 = mfma16(qa1, *(const LAS bf16x8*)(kb + 32), a4); sc[n] = a4; }
;     ...
;         for (int ks = 0; ks < 5; ++ks) { const bf16x8 a = *(const LAS bf16x8*)(Pw + l15 * 168 + ks * 32 + quad * 8);
; #pragma unroll
;             for (int nd = 0; nd < 4; ++nd) o4[nd] = mfma16(a, *(const LAS bf16x8*)(Vt + (nd * 16 + l15) * 280 + kbase + ks * 32 + quad * 8), o4[nd]); }
; #pragma unroll
;         for (int nd = 0; nd < 4; ++nd)
; #pragma unroll
;             for (int j = 0; j < 4; ++j) Z[(rowbase + t0 + kbase + quad * 4 + j) * ZLD + ZSQ + hq * 64 + nd * 16 + l15] = (bf16_t)hwbf(o4[nd][j] * rden[j]);
	v_mfma_f32_16x16x32_bf16 v[30:33], v[42:45], v[50:53], v[30:33]
	ds_read_b128 v[50:53], v58 offset:45888
	s_waitcnt lgkmcnt(0)
	v_mfma_f32_16x16x32_bf16 v[34:37], v[42:45], v[50:53], v[34:37]
	ds_read_b128 v[50:53], v58 offset:54848
	s_waitcnt lgkmcnt(0)
	v_mfma_f32_16x16x32_bf16 v[38:41], v[42:45], v[50:53], v[38:41]
	ds_read_b128 v[50:53], v58 offset:63808
	s_waitcnt lgkmcnt(0)
	v_mfma_f32_16x16x32_bf16 v[26:29], v[42:45], v[50:53], v[26:29]
	ds_read_b128 v[42:45], v69 offset:128
	ds_read_b128 v[50:53], v58 offset:36992
	s_waitcnt lgkmcnt(0)
	v_mfma_f32_16x16x32_bf16 v[30:33], v[42:45], v[50:53], v[30:33]
	ds_read_b128 v[50:53], v58 offset:45952
	s_waitcnt lgkmcnt(0)
	v_mfma_f32_16x16x32_bf16 v[34:37], v[42:45], v[50:53], v[34:37]
	ds_read_b128 v[50:53], v58 offset:54912
	s_waitcnt lgkmcnt(0)
	v_mfma_f32_16x16x32_bf16 v[38:41], v[42:45], v[50:53], v[38:41]
	ds_read_b128 v[50:53], v58 offset:63872
	s_waitcnt lgkmcnt(0)
	v_mfma_f32_16x16x32_bf16 v[26:29], v[42:45], v[50:53], v[26:29]
	ds_read_b128 v[42:45], v69 offset:192
	ds_read_b128 v[50:53], v58 offset:37056
	s_waitcnt lgkmcnt(0)
	v_mfma_f32_16x16x32_bf16 v[50:53], v[42:45], v[50:53], v[30:33]
	s_nop 2
	ds_read_b128 v[30:33], v58 offset:46016
	s_waitcnt lgkmcnt(0)
	v_mfma_f32_16x16x32_bf16 v[88:91], v[42:45], v[30:33], v[34:37]
	ds_read_b128 v[30:33], v58 offset:54976
	s_nop 1
	ds_read_b128 v[34:37], v58 offset:63936
	s_waitcnt lgkmcnt(1)
	v_mfma_f32_16x16x32_bf16 v[30:33], v[42:45], v[30:33], v[38:41]
	s_waitcnt lgkmcnt(0)
	v_mfma_f32_16x16x32_bf16 v[26:29], v[42:45], v[34:37], v[26:29]
	ds_read_b128 v[42:45], v69 offset:256
	ds_read_b128 v[34:37], v58 offset:37120
	ds_read_b128 v[38:41], v58 offset:46080
	s_waitcnt lgkmcnt(1)
	v_mfma_f32_16x16x32_bf16 v[34:37], v[42:45], v[34:37], v[50:53]
	s_nop 2
	ds_read_b128 v[50:53], v58 offset:55040
	s_waitcnt lgkmcnt(0)
	v_mfma_f32_16x16x32_bf16 v[30:33], v[42:45], v[50:53], v[30:33]
	ds_read_b128 v[50:53], v58 offset:64000
	s_nop 0
	v_mul_f32_e32 v34, v46, v34
	s_nop 1
	v_cvt_pk_bf16_f32 v34, v34, v1
	s_waitcnt lgkmcnt(0)
	v_mfma_f32_16x16x32_bf16 v[26:29], v[42:45], v[50:53], v[26:29]
	v_or3_b32 v52, v68, v81, s54
	s_nop 1
	v_mul_f32_e32 v30, v46, v30
	v_mad_u32_u24 v81, v86, s67, v79
	v_mfma_f32_16x16x32_bf16 v[38:41], v[42:45], v[38:41], v[88:91]
	v_mad_u64_u32 v[42:43], s[0:1], v52, s74, v[54:55]
	v_mad_i32_i24 v43, s55, v250, v43
	v_lshl_add_u64 v[42:43], v[42:43], 0, v[66:67]
	v_lshl_add_u64 v[42:43], v[42:43], 0, v[0:1]
	v_lshl_add_u64 v[44:45], v[42:43], 0, s[16:17]
	v_add_co_u32_e64 v42, s[0:1], s78, v42
	v_mul_f32_e32 v26, v46, v26
	s_nop 0
	v_addc_co_u32_e64 v43, s[0:1], 0, v43, s[0:1]
	global_store_short v[42:43], v34, off offset:3072
	v_mul_f32_e32 v34, v47, v35
	s_nop 1
	v_cvt_pk_bf16_f32 v50, v34, v1
	v_or_b32_e32 v34, 1, v52
	v_mad_u64_u32 v[34:35], s[0:1], v34, s74, v[54:55]
	v_mad_i32_i24 v35, s55, v250, v35
	v_lshl_add_u64 v[34:35], v[34:35], 0, v[66:67]
	v_lshl_add_u64 v[34:35], v[34:35], 0, v[0:1]
	v_lshl_add_u64 v[42:43], v[34:35], 0, s[16:17]
	v_add_co_u32_e64 v34, s[0:1], s78, v34
	s_nop 1
	v_addc_co_u32_e64 v35, s[0:1], 0, v35, s[0:1]
	global_store_short v[34:35], v50, off offset:3072
	v_mul_f32_e32 v34, v48, v36
	s_nop 1
	v_cvt_pk_bf16_f32 v36, v34, v1
	v_or_b32_e32 v34, 2, v52
	v_mad_u64_u32 v[34:35], s[0:1], v34, s74, v[54:55]
	v_mad_i32_i24 v35, s55, v250, v35
	v_lshl_add_u64 v[34:35], v[34:35], 0, v[66:67]
	v_lshl_add_u64 v[34:35], v[34:35], 0, v[0:1]
	v_lshl_add_u64 v[50:51], v[34:35], 0, s[16:17]
	v_add_co_u32_e64 v34, s[0:1], s78, v34
	s_nop 1
	v_addc_co_u32_e64 v35, s[0:1], 0, v35, s[0:1]
	global_store_short v[34:35], v36, off offset:3072
	v_mul_f32_e32 v34, v49, v37
	s_nop 1
	v_cvt_pk_bf16_f32 v53, v34, v1
	v_or_b32_e32 v34, 3, v52
	v_mad_u64_u32 v[34:35], s[0:1], v34, s74, v[54:55]
	v_mad_i32_i24 v35, s55, v250, v35
	v_lshl_add_u64 v[34:35], v[34:35], 0, v[66:67]
	v_lshl_add_u64 v[34:35], v[34:35], 0, v[0:1]
	v_lshl_add_u64 v[36:37], v[34:35], 0, s[16:17]
	v_add_co_u32_e64 v34, s[0:1], s78, v34
	s_nop 1
	v_addc_co_u32_e64 v35, s[0:1], 0, v35, s[0:1]
	global_store_short v[34:35], v53, off offset:3072
	v_mul_f32_e32 v34, v46, v38
	s_nop 1
	v_cvt_pk_bf16_f32 v34, v34, v1
	global_store_short v[44:45], v34, off offset:32
	v_mul_f32_e32 v34, v47, v39
	s_nop 1
	v_cvt_pk_bf16_f32 v34, v34, v1
	global_store_short v[42:43], v34, off offset:32
	v_mul_f32_e32 v34, v48, v40
	s_nop 1
	v_cvt_pk_bf16_f32 v34, v34, v1
	global_store_short v[50:51], v34, off offset:32
	v_mul_f32_e32 v34, v49, v41
	s_nop 1
	v_cvt_pk_bf16_f32 v34, v34, v1
	global_store_short v[36:37], v34, off offset:32
	s_nop 1
	v_cvt_pk_bf16_f32 v30, v30, v1
	global_store_short v[44:45], v30, off offset:64
	v_mul_f32_e32 v30, v47, v31
	s_nop 1
	v_cvt_pk_bf16_f32 v30, v30, v1
	global_store_short v[42:43], v30, off offset:64
	v_mul_f32_e32 v30, v48, v32
	s_nop 1
	v_cvt_pk_bf16_f32 v30, v30, v1
	global_store_short v[50:51], v30, off offset:64
	v_mul_f32_e32 v30, v49, v33
	s_nop 1
	v_cvt_pk_bf16_f32 v30, v30, v1
	global_store_short v[36:37], v30, off offset:64
	s_nop 1
	v_cvt_pk_bf16_f32 v26, v26, v1
	global_store_short v[44:45], v26, off offset:96
	v_mul_f32_e32 v26, v47, v27
	s_nop 1
	v_cvt_pk_bf16_f32 v26, v26, v1
	global_store_short v[42:43], v26, off offset:96
	v_mul_f32_e32 v26, v48, v28
	s_nop 1
	v_cvt_pk_bf16_f32 v26, v26, v1
	global_store_short v[50:51], v26, off offset:96
	v_mul_f32_e32 v26, v49, v29
	s_nop 1
	v_cvt_pk_bf16_f32 v26, v26, v1
	global_store_short v[36:37], v26, off offset:96
	s_waitcnt lgkmcnt(0)
	ds_read_b128 v[26:29], v81
	ds_read_b128 v[30:33], v81 offset:64
	s_waitcnt lgkmcnt(1)
; #define LAS __attribute__((address_space(3)))
; __device__ __forceinline__ f32x4 mfma16(bf16x8 a, bf16x8 b, f32x4 c) { return __builtin_amdgcn_mfma_f32_16x16x32_bf16(a, b, c, 0, 0, 0); }
; __device__ __forceinline__ void swa_unit(LAS unsigned char* L, bf16_t* Z, const float* sinks, int b, int qb, int kvh) {
;     ...
;         const bf16x8 qa0 = qf[rt][0], qa1 = qf[rt][1];
;         f32x4 sc[9];
; #pragma unroll
;         for (int n = 0; n < 9; ++n) { const LAS bf16_t* kb = Ks + (kbase + 16 * n + l15) * 72 + quad * 8; f32x4 a4 = (f32x4){0.f, 0.f, 0.f, 0.f};
;             a4 = mfma16(qa0, *(const LAS bf16x8*)kb, a4); a4 = mfma16(qa1, *(const LAS bf16x8*)(kb + 32), a4); sc[n] = a4; }
;         float mx[4] = {sink, sink, sink, sink};
; #pragma unroll
;         for (int n = 0; n < 9; ++n)
; #pragma unroll
;             for (int j = 0; j < 4; ++j) { const int qi = kbase + quad * 4 + j, kk = kbase + 16 * n + l15; const int dist = qi + 128 - kk;
;                 const bool valid = ((n >= 1 && n <= 7) || ((dist >= 0) && (dist < 128))) && (kk >= kmin);
;                 const float lg = valid ? sc[n][j] * (0.125f * 1.4426950408889634f) - slope * (float)dist : -INFINITY; sc[n][j] = lg; mx[j] = fmaxf(mx[j], lg); }
	v_mfma_f32_16x16x32_bf16 v[26:29], v[22:25], v[26:29], 0
	ds_read_b128 v[90:93], v81 offset:16192
	s_waitcnt lgkmcnt(1)
	v_mfma_f32_16x16x32_bf16 v[86:89], v[18:21], v[30:33], v[26:29]
	ds_read_b128 v[30:33], v81 offset:2368
	s_nop 3
	ds_read_b128 v[26:29], v81 offset:2304
	s_waitcnt lgkmcnt(0)
	v_mfma_f32_16x16x32_bf16 v[26:29], v[22:25], v[26:29], 0
	v_mfma_f32_16x16x32_bf16 v[50:53], v[18:21], v[30:33], v[26:29]
	ds_read_b128 v[30:33], v81 offset:4672
	s_nop 5
	ds_read_b128 v[26:29], v81 offset:4608
	s_waitcnt lgkmcnt(0)
	v_mfma_f32_16x16x32_bf16 v[26:29], v[22:25], v[26:29], 0
	v_mfma_f32_16x16x32_bf16 v[46:49], v[18:21], v[30:33], v[26:29]
	ds_read_b128 v[30:33], v81 offset:6976
	s_nop 5
	ds_read_b128 v[26:29], v81 offset:6912
	s_waitcnt lgkmcnt(0)
	v_mfma_f32_16x16x32_bf16 v[26:29], v[22:25], v[26:29], 0
	v_mfma_f32_16x16x32_bf16 v[42:45], v[18:21], v[30:33], v[26:29]
	ds_read_b128 v[30:33], v81 offset:9280
	s_nop 5
	ds_read_b128 v[26:29], v81 offset:9216
	s_waitcnt lgkmcnt(0)
	v_mfma_f32_16x16x32_bf16 v[26:29], v[22:25], v[26:29], 0
	v_mfma_f32_16x16x32_bf16 v[38:41], v[18:21], v[30:33], v[26:29]
	ds_read_b128 v[30:33], v81 offset:11584
	s_nop 5
	ds_read_b128 v[26:29], v81 offset:11520
	s_waitcnt lgkmcnt(0)
	v_mfma_f32_16x16x32_bf16 v[26:29], v[22:25], v[26:29], 0
	v_mfma_f32_16x16x32_bf16 v[34:37], v[18:21], v[30:33], v[26:29]
	ds_read_b128 v[30:33], v81 offset:13888
	s_nop 5
	ds_read_b128 v[26:29], v81 offset:13824
	s_waitcnt lgkmcnt(0)
	v_mfma_f32_16x16x32_bf16 v[26:29], v[22:25], v[26:29], 0
	v_mfma_f32_16x16x32_bf16 v[30:33], v[18:21], v[30:33], v[26:29]
	s_nop 6
	ds_read_b128 v[26:29], v81 offset:16128
	s_waitcnt lgkmcnt(0)
	v_mfma_f32_16x16x32_bf16 v[26:29], v[22:25], v[26:29], 0
	v_mfma_f32_16x16x32_bf16 v[26:29], v[18:21], v[90:93], v[26:29]
	ds_read_b128 v[90:93], v81 offset:18432
	s_waitcnt lgkmcnt(0)
	v_mfma_f32_16x16x32_bf16 v[22:25], v[22:25], v[90:93], 0
	ds_read_b128 v[90:93], v81 offset:18496
	s_waitcnt lgkmcnt(0)
	v_mfma_f32_16x16x32_bf16 v[18:21], v[18:21], v[90:93], v[22:25]
	v_or_b32_e32 v90, v78, v82
	s_nop 3
	v_sub_u32_e32 v24, v78, v80
	v_add_u32_e32 v23, 1, v24
	v_cvt_f32_u32_e32 v23, v23
	v_sub_u32_e32 v93, v90, v84
	v_add_u32_e32 v83, 2, v24
	v_cvt_f32_u32_e32 v83, v83
	v_mul_f32_e32 v81, v75, v23
	v_fma_f32 v23, v87, s36, -v81
	v_cvt_f32_ubyte0_e32 v87, v93
	v_mul_f32_e32 v87, v75, v87
	v_fma_f32 v50, v50, s36, -v87
	v_cndmask_b32_e64 v87, v251, v50, s[42:43]
	v_add_u32_e32 v50, 1, v93
	v_cvt_f32_u32_e32 v50, v50
	v_mul_f32_e32 v83, v75, v83
	v_fma_f32 v85, v88, s36, -v83
	v_cvt_f32_ubyte0_e32 v22, v24
	v_mul_f32_e32 v50, v75, v50
	v_fma_f32 v50, v51, s36, -v50
	v_add_u32_e32 v51, 3, v93
	v_cndmask_b32_e64 v88, v251, v50, s[42:43]
	v_add_u32_e32 v50, 2, v93
	v_cvt_f32_u32_e32 v51, v51
	v_cvt_f32_u32_e32 v50, v50
	v_cmp_gt_u32_e64 s[0:1], s20, v24
	v_mul_f32_e32 v80, v75, v22
	v_mul_f32_e32 v51, v75, v51
	v_mul_f32_e32 v50, v75, v50
	v_fma_f32 v51, v53, s36, -v51
	v_sub_u32_e32 v53, v90, v61
	v_fma_f32 v50, v52, s36, -v50
	v_cndmask_b32_e64 v52, v251, v51, s[42:43]
	v_cvt_f32_ubyte0_e32 v51, v53
	s_and_b64 s[44:45], s[42:43], s[0:1]
	v_fma_f32 v22, v86, s36, -v80
	v_mul_f32_e32 v51, v75, v51
	v_cndmask_b32_e64 v22, v251, v22, s[44:45]
	v_fma_f32 v46, v46, s36, -v51
	v_max_f32_e32 v25, v77, v22
	v_cndmask_b32_e64 v46, v251, v46, s[42:43]
	v_max3_f32 v93, v25, v87, v46
	v_add_u32_e32 v25, 1, v53
	v_cvt_f32_u32_e32 v25, v25
	v_cmp_gt_u32_e64 s[0:1], s8, v24
	s_and_b64 s[46:47], s[42:43], s[0:1]
	v_cmp_gt_u32_e64 s[0:1], s9, v24
	v_mul_f32_e32 v25, v75, v25
	v_fma_f32 v25, v47, s36, -v25
	v_cndmask_b32_e64 v47, v251, v25, s[42:43]
	v_add_u32_e32 v25, 2, v53
	v_cvt_f32_u32_e32 v25, v25
	s_and_b64 s[48:49], s[42:43], s[0:1]
	v_cndmask_b32_e64 v86, v251, v85, s[48:49]
	v_add_u32_e32 v85, 3, v24
	v_mul_f32_e32 v25, v75, v25
	v_fma_f32 v25, v48, s36, -v25
	v_cmp_gt_u32_e64 s[0:1], s10, v24
	v_cvt_f32_u32_e32 v24, v85
	v_cndmask_b32_e64 v51, v251, v25, s[42:43]
	v_add_u32_e32 v25, 3, v53
	v_cvt_f32_u32_e32 v25, v25
	v_mul_f32_e32 v85, v75, v24
	s_and_b64 s[50:51], s[42:43], s[0:1]
	v_fma_f32 v24, v89, s36, -v85
	v_mul_f32_e32 v25, v75, v25
	v_cndmask_b32_e64 v89, v251, v24, s[50:51]
	v_fma_f32 v25, v49, s36, -v25
	v_max_f32_e32 v24, v77, v89
	v_cndmask_b32_e64 v49, v251, v25, s[42:43]
	v_max3_f32 v53, v24, v52, v49
	v_sub_u32_e32 v24, v90, v59
	v_cvt_f32_ubyte0_e32 v25, v24
	v_mul_f32_e32 v25, v75, v25
	v_fma_f32 v25, v42, s36, -v25
	v_add_u32_e32 v42, 2, v24
	v_cndmask_b32_e32 v48, v25, v251, vcc
	v_add_u32_e32 v25, 1, v24
	v_cvt_f32_u32_e32 v42, v42
	v_add_u32_e32 v24, 3, v24
	v_cvt_f32_u32_e32 v24, v24
	v_cvt_f32_u32_e32 v25, v25
	v_mul_f32_e32 v42, v75, v42
	v_fma_f32 v42, v44, s36, -v42
	v_mul_f32_e32 v24, v75, v24
	v_sub_u32_e32 v44, v90, v64
	v_fma_f32 v24, v45, s36, -v24
	v_add_u32_e32 v45, 1, v44
	v_cvt_f32_i32_e32 v45, v45
	v_cndmask_b32_e64 v23, v251, v23, s[46:47]
	v_mul_f32_e32 v25, v75, v25
	v_max_f32_e32 v91, v77, v23
	v_mul_f32_e32 v45, v75, v45
	v_fma_f32 v25, v43, s36, -v25
	v_fma_f32 v39, v39, s36, -v45
	v_max3_f32 v91, v91, v88, v47
	v_cndmask_b32_e32 v25, v25, v251, vcc
	v_cndmask_b32_e32 v39, v39, v251, vcc
	v_max3_f32 v45, v91, v25, v39
	v_add_u32_e32 v91, 2, v44
	v_cvt_f32_i32_e32 v91, v91
	v_cndmask_b32_e32 v43, v42, v251, vcc
	v_cvt_f32_i32_e32 v42, v44
	v_add_u32_e32 v44, 3, v44
	v_cvt_f32_i32_e32 v44, v44
	v_mul_f32_e32 v91, v75, v91
	v_max_f32_e32 v92, v77, v86
	v_cndmask_b32_e64 v50, v251, v50, s[42:43]
	v_fma_f32 v40, v40, s36, -v91
	v_max3_f32 v92, v92, v50, v51
	v_cndmask_b32_e32 v40, v40, v251, vcc
	v_max3_f32 v91, v92, v43, v40
	v_mul_f32_e32 v44, v75, v44
	v_sub_u32_e32 v92, v90, v62
; __device__ __forceinline__ void swa_unit(LAS unsigned char* L, bf16_t* Z, const float* sinks, int b, int qb, int kvh) {
;     ...
;             for (int j = 0; j < 4; ++j) { const int qi = kbase + quad * 4 + j, kk = kbase + 16 * n + l15; const int dist = qi + 128 - kk;
;                 const bool valid = ((n >= 1 && n <= 7) || ((dist >= 0) && (dist < 128))) && (kk >= kmin);
;                 const float lg = valid ? sc[n][j] * (0.125f * 1.4426950408889634f) - slope * (float)dist : -INFINITY; sc[n][j] = lg; mx[j] = fmaxf(mx[j], lg); }
; #pragma unroll
;         for (int j = 0; j < 4; ++j) { mx[j] = fmaxf(mx[j], __shfl_xor(mx[j], 1)); mx[j] = fmaxf(mx[j], __shfl_xor(mx[j], 2)); mx[j] = fmaxf(mx[j], __shfl_xor(mx[j], 4)); mx[j] = fmaxf(mx[j], __shfl_xor(mx[j], 8)); }
	v_fma_f32 v41, v41, s36, -v44
	v_cvt_f32_i32_e32 v44, v92
	v_mul_f32_e32 v42, v75, v42
	v_fma_f32 v38, v38, s36, -v42
	v_cndmask_b32_e32 v42, v38, v251, vcc
	v_mul_f32_e32 v44, v75, v44
	v_fma_f32 v34, v34, s36, -v44
	v_cndmask_b32_e32 v44, v34, v251, vcc
	v_add_u32_e32 v34, 1, v92
	v_cvt_f32_i32_e32 v34, v34
	v_max3_f32 v38, v93, v48, v42
	v_cndmask_b32_e32 v24, v24, v251, vcc
	v_cndmask_b32_e32 v41, v41, v251, vcc
	v_mul_f32_e32 v34, v75, v34
	v_fma_f32 v34, v35, s36, -v34
	v_cndmask_b32_e32 v35, v34, v251, vcc
	v_add_u32_e32 v34, 2, v92
	v_cvt_f32_i32_e32 v34, v34
	v_max3_f32 v53, v53, v24, v41
	s_cmpk_gt_i32 s24, 0x1ff
	v_mul_f32_e32 v34, v75, v34
	v_fma_f32 v34, v36, s36, -v34
	v_cndmask_b32_e32 v36, v34, v251, vcc
	v_add_u32_e32 v34, 3, v92
	v_cvt_f32_i32_e32 v34, v34
	v_mul_f32_e32 v34, v75, v34
	v_fma_f32 v34, v37, s36, -v34
	v_sub_u32_e32 v37, v90, v65
	v_cvt_f32_i32_e32 v92, v37
	v_cndmask_b32_e32 v34, v34, v251, vcc
	v_mul_f32_e32 v92, v75, v92
	v_fma_f32 v30, v30, s36, -v92
	v_cndmask_b32_e32 v30, v30, v251, vcc
	v_max3_f32 v92, v38, v44, v30
	v_add_u32_e32 v38, 1, v37
	v_cvt_f32_i32_e32 v38, v38
	v_mul_f32_e32 v38, v75, v38
	v_fma_f32 v31, v31, s36, -v38
	v_add_u32_e32 v38, 2, v37
	v_add_u32_e32 v37, 3, v37
	v_cvt_f32_i32_e32 v38, v38
	v_cvt_f32_i32_e32 v37, v37
	v_cndmask_b32_e32 v31, v31, v251, vcc
	v_max3_f32 v93, v45, v35, v31
	v_mul_f32_e32 v38, v75, v38
	v_mul_f32_e32 v37, v75, v37
	v_fma_f32 v32, v32, s36, -v38
	v_fma_f32 v33, v33, s36, -v37
	v_sub_u32_e32 v38, v90, v63
	v_cndmask_b32_e32 v37, v33, v251, vcc
	v_cvt_f32_i32_e32 v33, v38
	v_max3_f32 v53, v53, v34, v37
	v_cndmask_b32_e32 v32, v32, v251, vcc
	v_max3_f32 v91, v91, v36, v32
	v_mul_f32_e32 v33, v75, v33
	v_fma_f32 v45, v26, s36, -v33
	v_add_u32_e32 v26, 1, v38
	v_cvt_f32_i32_e32 v26, v26
	v_mul_f32_e32 v26, v75, v26
	v_fma_f32 v33, v27, s36, -v26
	v_add_u32_e32 v26, 2, v38
	v_cvt_f32_i32_e32 v26, v26
	v_mul_f32_e32 v26, v75, v26
	v_fma_f32 v28, v28, s36, -v26
	v_add_u32_e32 v26, 3, v38
	v_or_b32_e32 v38, 0x90, v76
	v_sub_u32_e32 v90, v90, v38
	v_cvt_f32_i32_e32 v26, v26
	v_cvt_f32_i32_e32 v27, v90
	v_cmp_gt_u32_e64 s[0:1], s20, v90
	v_mul_f32_e32 v26, v75, v26
	v_mul_f32_e32 v27, v75, v27
	v_fma_f32 v26, v29, s36, -v26
	v_fma_f32 v18, v18, s36, -v27
	v_add_u32_e32 v29, 1, v90
	v_cndmask_b32_e64 v27, v251, v18, s[0:1]
	v_cmp_gt_u32_e64 s[0:1], s20, v29
	v_cvt_f32_i32_e32 v29, v29
	v_max3_f32 v18, v92, v45, v27
	v_mul_f32_e32 v29, v75, v29
	v_fma_f32 v19, v19, s36, -v29
	v_add_u32_e32 v29, 2, v90
	v_cndmask_b32_e64 v19, v251, v19, s[0:1]
	v_cmp_gt_u32_e64 s[0:1], s20, v29
	v_cvt_f32_i32_e32 v29, v29
	v_max3_f32 v92, v93, v33, v19
	v_mul_f32_e32 v29, v75, v29
	v_fma_f32 v20, v20, s36, -v29
	v_cndmask_b32_e64 v29, v251, v20, s[0:1]
	v_add_u32_e32 v20, 3, v90
	v_cmp_gt_u32_e64 s[0:1], s20, v20
	v_cvt_f32_i32_e32 v20, v20
	v_max3_f32 v91, v91, v28, v29
	v_mul_f32_e32 v20, v75, v20
	v_fma_f32 v20, v21, s36, -v20
	v_cndmask_b32_e64 v21, v251, v20, s[0:1]
	s_nop 1
	v_mov_b32_dpp v20, v18 quad_perm:[1,0,3,2] row_mask:0xf bank_mask:0xf
	v_max3_f32 v90, v53, v26, v21
	s_waitcnt lgkmcnt(0)
	v_max_f32_e32 v20, v20, v20
	v_max_f32_e32 v18, v18, v20
	s_nop 1
	v_mov_b32_dpp v20, v18 quad_perm:[2,3,0,1] row_mask:0xf bank_mask:0xf
	s_waitcnt lgkmcnt(0)
	v_max_f32_e32 v20, v20, v20
	v_max_f32_e32 v18, v18, v20
	s_nop 1
	v_mov_b32_dpp v20, v18 row_half_mirror row_mask:0xf bank_mask:0xf
	s_waitcnt lgkmcnt(0)
	v_max_f32_e32 v20, v20, v20
	v_max_f32_e32 v18, v18, v20
	s_nop 1
	v_mov_b32_dpp v20, v18 row_mirror row_mask:0xf bank_mask:0xf
	s_waitcnt lgkmcnt(0)
	v_max_f32_e32 v20, v20, v20
	v_max_f32_e32 v18, v18, v20
	s_nop 1
	v_mov_b32_dpp v20, v92 quad_perm:[1,0,3,2] row_mask:0xf bank_mask:0xf
	v_sub_f32_e32 v22, v22, v18
	v_exp_f32_e32 v22, v22
	s_waitcnt lgkmcnt(0)
	v_max_f32_e32 v20, v20, v20
	v_max_f32_e32 v20, v92, v20
	s_nop 1
	v_mov_b32_dpp v53, v20 quad_perm:[2,3,0,1] row_mask:0xf bank_mask:0xf
	s_waitcnt lgkmcnt(0)
	v_max_f32_e32 v53, v53, v53
	v_max_f32_e32 v20, v20, v53
	s_nop 1
	v_mov_b32_dpp v53, v20 row_half_mirror row_mask:0xf bank_mask:0xf
	s_waitcnt lgkmcnt(0)
	v_max_f32_e32 v53, v53, v53
	v_max_f32_e32 v20, v20, v53
	s_nop 1
	v_mov_b32_dpp v53, v20 row_mirror row_mask:0xf bank_mask:0xf
	s_waitcnt lgkmcnt(0)
	v_max_f32_e32 v53, v53, v53
	v_max_f32_e32 v20, v20, v53
	s_nop 1
	v_mov_b32_dpp v53, v91 quad_perm:[1,0,3,2] row_mask:0xf bank_mask:0xf
	v_sub_f32_e32 v19, v19, v20
	v_exp_f32_e32 v19, v19
	s_waitcnt lgkmcnt(0)
	v_max_f32_e32 v53, v53, v53
	v_max_f32_e32 v53, v91, v53
	s_nop 1
	v_mov_b32_dpp v91, v53 quad_perm:[2,3,0,1] row_mask:0xf bank_mask:0xf
	s_waitcnt lgkmcnt(0)
	v_max_f32_e32 v91, v91, v91
	v_max_f32_e32 v53, v53, v91
	s_nop 1
	v_mov_b32_dpp v91, v53 row_half_mirror row_mask:0xf bank_mask:0xf
	s_waitcnt lgkmcnt(0)
	v_max_f32_e32 v91, v91, v91
	v_max_f32_e32 v53, v53, v91
	s_nop 1
	v_mov_b32_dpp v91, v53 row_mirror row_mask:0xf bank_mask:0xf
	s_waitcnt lgkmcnt(0)
	v_max_f32_e32 v91, v91, v91
	v_max_f32_e32 v53, v53, v91
	s_nop 1
	v_mov_b32_dpp v91, v90 quad_perm:[1,0,3,2] row_mask:0xf bank_mask:0xf
	s_waitcnt lgkmcnt(0)
	v_max_f32_e32 v91, v91, v91
	v_max_f32_e32 v90, v90, v91
	s_nop 1
	v_mov_b32_dpp v91, v90 quad_perm:[2,3,0,1] row_mask:0xf bank_mask:0xf
	s_waitcnt lgkmcnt(0)
	v_max_f32_e32 v91, v91, v91
	v_max_f32_e32 v90, v90, v91
	s_nop 1
	v_mov_b32_dpp v91, v90 row_half_mirror row_mask:0xf bank_mask:0xf
	s_waitcnt lgkmcnt(0)
	v_max_f32_e32 v91, v91, v91
	v_max_f32_e32 v90, v90, v91
	s_nop 1
	v_mov_b32_dpp v91, v90 row_mirror row_mask:0xf bank_mask:0xf
	s_waitcnt lgkmcnt(0)
; __device__ __forceinline__ unsigned hwbf(float f) { return cvt_pk_bf16(f, 0.f) & 0xffffu; }
; __device__ __forceinline__ void swa_unit(LAS unsigned char* L, bf16_t* Z, const float* sinks, int b, int qb, int kvh) {
;     ...
;         float sum[4] = {0.f, 0.f, 0.f, 0.f};
; #pragma unroll
;         for (int n = 0; n < 9; ++n)
; #pragma unroll
;             for (int j = 0; j < 4; ++j) { const float p = __builtin_amdgcn_exp2f(sc[n][j] - mx[j]); sum[j] += p; Pw[(quad * 4 + j) * 168 + 16 * n + l15] = (bf16_t)hwbf(p); }
	v_max_f32_e32 v91, v91, v91
	v_max_f32_e32 v90, v90, v91
	v_add_f32_e32 v91, 0, v22
	s_nop 1
	v_cvt_pk_bf16_f32 v22, v22, v1
	ds_write_b16 v57, v22
	v_sub_f32_e32 v22, v23, v20
	v_exp_f32_e32 v22, v22
	s_nop 0
	v_add_f32_e32 v23, 0, v22
	s_nop 1
	v_cvt_pk_bf16_f32 v22, v22, v1
	ds_write_b16 v57, v22 offset:336
	v_sub_f32_e32 v22, v86, v53
	v_exp_f32_e32 v22, v22
	s_nop 0
	v_add_f32_e32 v86, 0, v22
	s_nop 1
	v_cvt_pk_bf16_f32 v22, v22, v1
	ds_write_b16 v57, v22 offset:672
	v_sub_f32_e32 v22, v89, v90
	v_exp_f32_e32 v22, v22
	s_nop 0
	v_add_f32_e32 v89, 0, v22
	s_nop 1
	v_cvt_pk_bf16_f32 v22, v22, v1
	ds_write_b16 v57, v22 offset:1008
	v_sub_f32_e32 v22, v87, v18
	v_exp_f32_e32 v22, v22
	s_nop 0
	v_add_f32_e32 v87, v22, v91
	s_nop 1
	v_cvt_pk_bf16_f32 v22, v22, v1
	ds_write_b16 v57, v22 offset:32
	v_sub_f32_e32 v22, v88, v20
	v_exp_f32_e32 v22, v22
	s_nop 0
	v_add_f32_e32 v23, v22, v23
	s_nop 1
	v_cvt_pk_bf16_f32 v22, v22, v1
	ds_write_b16 v57, v22 offset:368
	v_sub_f32_e32 v22, v50, v53
	v_exp_f32_e32 v22, v22
	s_nop 0
	v_add_f32_e32 v50, v22, v86
	s_nop 1
	v_cvt_pk_bf16_f32 v22, v22, v1
	ds_write_b16 v57, v22 offset:704
	v_sub_f32_e32 v22, v52, v90
	v_exp_f32_e32 v22, v22
	s_nop 0
	v_add_f32_e32 v52, v22, v89
	s_nop 1
	v_cvt_pk_bf16_f32 v22, v22, v1
	ds_write_b16 v57, v22 offset:1040
	v_sub_f32_e32 v22, v46, v18
	v_exp_f32_e32 v22, v22
	s_nop 0
	v_add_f32_e32 v46, v22, v87
	s_nop 1
	v_cvt_pk_bf16_f32 v22, v22, v1
	ds_write_b16 v57, v22 offset:64
	v_sub_f32_e32 v22, v47, v20
	v_exp_f32_e32 v22, v22
	s_nop 0
	v_add_f32_e32 v23, v22, v23
	s_nop 1
	v_cvt_pk_bf16_f32 v22, v22, v1
	ds_write_b16 v57, v22 offset:400
	v_sub_f32_e32 v22, v51, v53
	v_exp_f32_e32 v22, v22
	s_nop 0
	v_add_f32_e32 v47, v22, v50
	s_nop 1
	v_cvt_pk_bf16_f32 v22, v22, v1
	ds_write_b16 v57, v22 offset:736
	v_sub_f32_e32 v22, v49, v90
	v_exp_f32_e32 v22, v22
	s_nop 0
	v_add_f32_e32 v49, v22, v52
	s_nop 1
	v_cvt_pk_bf16_f32 v22, v22, v1
	ds_write_b16 v57, v22 offset:1072
	v_sub_f32_e32 v22, v48, v18
	v_exp_f32_e32 v22, v22
	s_nop 0
	v_add_f32_e32 v46, v22, v46
	s_nop 1
	v_cvt_pk_bf16_f32 v22, v22, v1
	ds_write_b16 v57, v22 offset:96
	v_sub_f32_e32 v22, v25, v20
	v_exp_f32_e32 v22, v22
	s_nop 0
	v_add_f32_e32 v23, v22, v23
	s_nop 1
	v_cvt_pk_bf16_f32 v22, v22, v1
	ds_write_b16 v57, v22 offset:432
	v_sub_f32_e32 v22, v43, v53
	v_exp_f32_e32 v22, v22
	v_or3_b32 v43, v68, v82, s54
	v_add_f32_e32 v25, v22, v47
	s_nop 1
	v_cvt_pk_bf16_f32 v22, v22, v1
	ds_write_b16 v57, v22 offset:768
	v_sub_f32_e32 v22, v24, v90
	v_exp_f32_e32 v22, v22
	s_nop 0
	v_add_f32_e32 v24, v22, v49
	s_nop 1
	v_cvt_pk_bf16_f32 v22, v22, v1
	ds_write_b16 v57, v22 offset:1104
	v_sub_f32_e32 v22, v42, v18
	v_exp_f32_e32 v22, v22
	s_nop 0
	v_add_f32_e32 v42, v22, v46
	s_nop 1
	v_cvt_pk_bf16_f32 v22, v22, v1
	ds_write_b16 v57, v22 offset:128
	v_sub_f32_e32 v22, v39, v20
	v_exp_f32_e32 v22, v22
	s_nop 0
	v_add_f32_e32 v23, v22, v23
	s_nop 1
	v_cvt_pk_bf16_f32 v22, v22, v1
	ds_write_b16 v57, v22 offset:464
	v_sub_f32_e32 v22, v40, v53
	v_exp_f32_e32 v22, v22
	s_nop 0
	v_add_f32_e32 v25, v22, v25
	s_nop 1
	v_cvt_pk_bf16_f32 v22, v22, v1
	ds_write_b16 v57, v22 offset:800
	v_sub_f32_e32 v22, v41, v90
	v_exp_f32_e32 v22, v22
	s_nop 0
	v_add_f32_e32 v24, v22, v24
	s_nop 1
	v_cvt_pk_bf16_f32 v22, v22, v1
	ds_write_b16 v57, v22 offset:1136
	v_sub_f32_e32 v22, v44, v18
	v_exp_f32_e32 v22, v22
	s_nop 0
	v_add_f32_e32 v39, v22, v42
	s_nop 1
	v_cvt_pk_bf16_f32 v22, v22, v1
	ds_write_b16 v57, v22 offset:160
	v_sub_f32_e32 v22, v35, v20
	v_exp_f32_e32 v22, v22
	s_nop 0
	v_add_f32_e32 v23, v22, v23
	s_nop 1
	v_cvt_pk_bf16_f32 v22, v22, v1
	ds_write_b16 v57, v22 offset:496
	v_sub_f32_e32 v22, v36, v53
	v_exp_f32_e32 v22, v22
	s_nop 0
	v_add_f32_e32 v25, v22, v25
	s_nop 1
	v_cvt_pk_bf16_f32 v22, v22, v1
	ds_write_b16 v57, v22 offset:832
	v_sub_f32_e32 v22, v34, v90
	v_exp_f32_e32 v22, v22
	s_nop 0
	v_add_f32_e32 v24, v22, v24
	s_nop 1
	v_cvt_pk_bf16_f32 v22, v22, v1
	ds_write_b16 v57, v22 offset:1168
	v_sub_f32_e32 v22, v30, v18
	v_exp_f32_e32 v22, v22
	s_nop 0
	v_add_f32_e32 v30, v22, v39
	s_nop 1
	v_cvt_pk_bf16_f32 v22, v22, v1
	ds_write_b16 v57, v22 offset:192
	v_sub_f32_e32 v22, v31, v20
	v_exp_f32_e32 v22, v22
	s_nop 0
	v_add_f32_e32 v23, v22, v23
	s_nop 1
	v_cvt_pk_bf16_f32 v22, v22, v1
	ds_write_b16 v57, v22 offset:528
	v_sub_f32_e32 v22, v32, v53
	v_exp_f32_e32 v22, v22
	s_nop 0
	v_add_f32_e32 v25, v22, v25
	s_nop 1
	v_cvt_pk_bf16_f32 v22, v22, v1
	ds_write_b16 v57, v22 offset:864
	v_sub_f32_e32 v22, v37, v90
	v_exp_f32_e32 v22, v22
	s_nop 0
	v_add_f32_e32 v24, v22, v24
	s_nop 1
	v_cvt_pk_bf16_f32 v22, v22, v1
	ds_write_b16 v57, v22 offset:1200
	v_sub_f32_e32 v22, v45, v18
	v_exp_f32_e32 v22, v22
	s_nop 0
	v_add_f32_e32 v30, v22, v30
	s_nop 1
	v_cvt_pk_bf16_f32 v22, v22, v1
	ds_write_b16 v57, v22 offset:224
	v_sub_f32_e32 v22, v33, v20
	v_exp_f32_e32 v22, v22
	s_nop 0
	v_add_f32_e32 v23, v22, v23
	s_nop 1
	v_cvt_pk_bf16_f32 v22, v22, v1
	ds_write_b16 v57, v22 offset:560
	v_sub_f32_e32 v22, v28, v53
	v_exp_f32_e32 v22, v22
	s_nop 0
	v_add_f32_e32 v25, v22, v25
	s_nop 1
	v_cvt_pk_bf16_f32 v22, v22, v1
	ds_write_b16 v57, v22 offset:896
	v_sub_f32_e32 v22, v26, v90
	v_exp_f32_e32 v22, v22
	s_nop 0
	v_add_f32_e32 v24, v22, v24
	s_nop 1
	v_cvt_pk_bf16_f32 v22, v22, v1
	ds_write_b16 v57, v22 offset:1232
	v_sub_f32_e32 v22, v27, v18
	v_exp_f32_e32 v22, v22
	v_fma_f32 v18, v70, s34, -v18
	v_exp_f32_e32 v18, v18
	v_add_f32_e32 v26, v22, v30
	s_nop 1
	v_cvt_pk_bf16_f32 v22, v22, v1
	ds_write_b16 v57, v22 offset:256
	v_add_f32_e32 v22, v19, v23
	s_nop 1
	v_cvt_pk_bf16_f32 v19, v19, v1
	ds_write_b16 v57, v19 offset:592
	v_sub_f32_e32 v19, v29, v53
	v_exp_f32_e32 v19, v19
	s_nop 0
	v_add_f32_e32 v23, v19, v25
	s_nop 1
	v_cvt_pk_bf16_f32 v19, v19, v1
	ds_write_b16 v57, v19 offset:928
	v_sub_f32_e32 v19, v21, v90
	v_exp_f32_e32 v19, v19
	s_nop 0
	v_add_f32_e32 v21, v19, v24
	s_nop 1
	v_cvt_pk_bf16_f32 v19, v19, v1
	ds_write_b16 v57, v19 offset:1264
	s_nop 1
	v_mov_b32_dpp v19, v26 quad_perm:[1,0,3,2] row_mask:0xf bank_mask:0xf
	s_waitcnt lgkmcnt(0)
; #define LAS __attribute__((address_space(3)))
; __device__ __forceinline__ f32x4 mfma16(bf16x8 a, bf16x8 b, f32x4 c) { return __builtin_amdgcn_mfma_f32_16x16x32_bf16(a, b, c, 0, 0, 0); }
; __device__ __forceinline__ void swa_unit(LAS unsigned char* L, bf16_t* Z, const float* sinks, int b, int qb, int kvh) {
;     ...
;         for (int j = 0; j < 4; ++j) { sum[j] += __shfl_xor(sum[j], 1); sum[j] += __shfl_xor(sum[j], 2); sum[j] += __shfl_xor(sum[j], 4); sum[j] += __shfl_xor(sum[j], 8);
;             rden[j] = __builtin_amdgcn_rcpf(sum[j] + __builtin_amdgcn_exp2f(sink - mx[j])); }
;         asm volatile("s_waitcnt lgkmcnt(0)" ::: "memory");
;         f32x4 o4[4];
; #pragma unroll
;         for (int nd = 0; nd < 4; ++nd) o4[nd] = (f32x4){0.f, 0.f, 0.f, 0.f};
; #pragma unroll
;         for (int ks = 0; ks < 5; ++ks) { const bf16x8 a = *(const LAS bf16x8*)(Pw + l15 * 168 + ks * 32 + quad * 8);
; #pragma unroll
;             for (int nd = 0; nd < 4; ++nd) o4[nd] = mfma16(a, *(const LAS bf16x8*)(Vt + (nd * 16 + l15) * 280 + kbase + ks * 32 + quad * 8), o4[nd]); }
	s_waitcnt lgkmcnt(0)
	v_add_f32_e32 v19, v26, v19
	s_nop 1
	v_mov_b32_dpp v24, v19 quad_perm:[2,3,0,1] row_mask:0xf bank_mask:0xf
	s_waitcnt lgkmcnt(0)
	v_add_f32_e32 v19, v19, v24
	s_nop 1
	v_mov_b32_dpp v24, v19 row_half_mirror row_mask:0xf bank_mask:0xf
	s_waitcnt lgkmcnt(0)
	v_add_f32_e32 v19, v19, v24
	s_nop 1
	v_mov_b32_dpp v24, v19 row_mirror row_mask:0xf bank_mask:0xf
	s_waitcnt lgkmcnt(0)
	v_add_f32_e32 v19, v19, v24
	v_add_f32_e32 v18, v18, v19
	v_rcp_f32_e32 v39, v18
	s_nop 1
	v_mov_b32_dpp v18, v22 quad_perm:[1,0,3,2] row_mask:0xf bank_mask:0xf
	s_waitcnt lgkmcnt(0)
	v_add_f32_e32 v18, v22, v18
	s_nop 1
	v_mov_b32_dpp v19, v18 quad_perm:[2,3,0,1] row_mask:0xf bank_mask:0xf
	s_waitcnt lgkmcnt(0)
	v_add_f32_e32 v18, v18, v19
	s_nop 1
	v_mov_b32_dpp v19, v18 row_half_mirror row_mask:0xf bank_mask:0xf
	s_waitcnt lgkmcnt(0)
	v_add_f32_e32 v18, v18, v19
	s_nop 1
	v_mov_b32_dpp v19, v18 row_mirror row_mask:0xf bank_mask:0xf
	s_waitcnt lgkmcnt(0)
	v_add_f32_e32 v18, v18, v19
	v_fma_f32 v19, v70, s34, -v20
	v_exp_f32_e32 v19, v19
	s_nop 0
	v_add_f32_e32 v18, v19, v18
	v_rcp_f32_e32 v40, v18
	s_nop 1
	v_mov_b32_dpp v18, v23 quad_perm:[1,0,3,2] row_mask:0xf bank_mask:0xf
	s_waitcnt lgkmcnt(0)
	v_add_f32_e32 v18, v23, v18
	s_nop 1
	v_mov_b32_dpp v19, v18 quad_perm:[2,3,0,1] row_mask:0xf bank_mask:0xf
	s_waitcnt lgkmcnt(0)
	v_add_f32_e32 v18, v18, v19
	s_nop 1
	v_mov_b32_dpp v19, v18 row_half_mirror row_mask:0xf bank_mask:0xf
	s_waitcnt lgkmcnt(0)
	v_add_f32_e32 v18, v18, v19
	s_nop 1
	v_mov_b32_dpp v19, v18 row_mirror row_mask:0xf bank_mask:0xf
	s_waitcnt lgkmcnt(0)
	v_add_f32_e32 v18, v18, v19
	v_fma_f32 v19, v70, s34, -v53
	v_exp_f32_e32 v19, v19
	s_nop 0
	v_add_f32_e32 v18, v19, v18
	v_rcp_f32_e32 v41, v18
	s_nop 1
	v_mov_b32_dpp v18, v21 quad_perm:[1,0,3,2] row_mask:0xf bank_mask:0xf
	s_waitcnt lgkmcnt(0)
	v_add_f32_e32 v18, v21, v18
	s_nop 1
	v_mov_b32_dpp v19, v18 quad_perm:[2,3,0,1] row_mask:0xf bank_mask:0xf
	s_waitcnt lgkmcnt(0)
	v_add_f32_e32 v18, v18, v19
	s_nop 1
	v_mov_b32_dpp v19, v18 row_half_mirror row_mask:0xf bank_mask:0xf
	s_waitcnt lgkmcnt(0)
	v_add_f32_e32 v18, v18, v19
	s_nop 1
	v_mov_b32_dpp v19, v18 row_mirror row_mask:0xf bank_mask:0xf
	s_waitcnt lgkmcnt(0)
	v_add_f32_e32 v18, v18, v19
	v_fma_f32 v19, v70, s34, -v90
	v_exp_f32_e32 v19, v19
	s_nop 0
	v_add_f32_e32 v18, v19, v18
	v_rcp_f32_e32 v42, v18
	ds_read_b128 v[18:21], v69
	ds_read_b128 v[22:25], v58 offset:36896
	ds_read_b128 v[26:29], v58 offset:45856
	ds_read_b128 v[30:33], v58 offset:54816
	ds_read_b128 v[34:37], v58 offset:63776
	s_waitcnt lgkmcnt(3)
	v_mfma_f32_16x16x32_bf16 v[22:25], v[18:21], v[22:25], 0
	s_waitcnt lgkmcnt(2)
	v_mfma_f32_16x16x32_bf16 v[26:29], v[18:21], v[26:29], 0
	s_waitcnt lgkmcnt(1)
	v_mfma_f32_16x16x32_bf16 v[30:33], v[18:21], v[30:33], 0
	s_waitcnt lgkmcnt(0)
	v_mfma_f32_16x16x32_bf16 v[18:21], v[18:21], v[34:37], 0
	ds_read_b128 v[34:37], v69 offset:64
	ds_read_b128 v[44:47], v58 offset:36960
	s_waitcnt lgkmcnt(0)
	v_mfma_f32_16x16x32_bf16 v[22:25], v[34:37], v[44:47], v[22:25]
	ds_read_b128 v[44:47], v58 offset:45920
	s_waitcnt lgkmcnt(0)
	v_mfma_f32_16x16x32_bf16 v[26:29], v[34:37], v[44:47], v[26:29]
	ds_read_b128 v[44:47], v58 offset:54880
	s_waitcnt lgkmcnt(0)
	v_mfma_f32_16x16x32_bf16 v[30:33], v[34:37], v[44:47], v[30:33]
	ds_read_b128 v[44:47], v58 offset:63840
	s_waitcnt lgkmcnt(0)
	v_mfma_f32_16x16x32_bf16 v[18:21], v[34:37], v[44:47], v[18:21]
	ds_read_b128 v[34:37], v69 offset:128
	ds_read_b128 v[44:47], v58 offset:37024
	s_waitcnt lgkmcnt(0)
	v_mfma_f32_16x16x32_bf16 v[22:25], v[34:37], v[44:47], v[22:25]
	ds_read_b128 v[44:47], v58 offset:45984
	s_waitcnt lgkmcnt(0)
	v_mfma_f32_16x16x32_bf16 v[26:29], v[34:37], v[44:47], v[26:29]
	ds_read_b128 v[44:47], v58 offset:54944
	s_waitcnt lgkmcnt(0)
	v_mfma_f32_16x16x32_bf16 v[30:33], v[34:37], v[44:47], v[30:33]
	ds_read_b128 v[44:47], v58 offset:63904
	s_waitcnt lgkmcnt(0)
	v_mfma_f32_16x16x32_bf16 v[18:21], v[34:37], v[44:47], v[18:21]
	ds_read_b128 v[34:37], v69 offset:192
	ds_read_b128 v[44:47], v58 offset:37088
	s_waitcnt lgkmcnt(0)
	v_mfma_f32_16x16x32_bf16 v[44:47], v[34:37], v[44:47], v[22:25]
	s_nop 2
	ds_read_b128 v[22:25], v58 offset:46048
	s_waitcnt lgkmcnt(0)
	v_mfma_f32_16x16x32_bf16 v[48:51], v[34:37], v[22:25], v[26:29]
	ds_read_b128 v[22:25], v58 offset:55008
	s_nop 1
	ds_read_b128 v[26:29], v58 offset:63968
	s_waitcnt lgkmcnt(1)
	v_mfma_f32_16x16x32_bf16 v[22:25], v[34:37], v[22:25], v[30:33]
	s_waitcnt lgkmcnt(0)
	v_mfma_f32_16x16x32_bf16 v[18:21], v[34:37], v[26:29], v[18:21]
	ds_read_b128 v[34:37], v69 offset:256
	ds_read_b128 v[26:29], v58 offset:37152
	ds_read_b128 v[30:33], v58 offset:46112
	s_waitcnt lgkmcnt(1)
	v_mfma_f32_16x16x32_bf16 v[26:29], v[34:37], v[26:29], v[44:47]
	s_nop 2
	ds_read_b128 v[44:47], v58 offset:55072
	s_waitcnt lgkmcnt(0)
	v_mfma_f32_16x16x32_bf16 v[22:25], v[34:37], v[44:47], v[22:25]
	ds_read_b128 v[44:47], v58 offset:64032
	s_nop 0
	v_mul_f32_e32 v26, v39, v26
	s_nop 1
	v_cvt_pk_bf16_f32 v26, v26, v1
	v_mfma_f32_16x16x32_bf16 v[30:33], v[34:37], v[30:33], v[48:51]
	s_nop 3
	v_mul_f32_e32 v22, v39, v22
	s_waitcnt lgkmcnt(0)
; #define LAS __attribute__((address_space(3)))
; __device__ __forceinline__ unsigned hwbf(float f) { return cvt_pk_bf16(f, 0.f) & 0xffffu; }
; __device__ __forceinline__ f32x4 mfma16(bf16x8 a, bf16x8 b, f32x4 c) { return __builtin_amdgcn_mfma_f32_16x16x32_bf16(a, b, c, 0, 0, 0); }
; __device__ __forceinline__ void swa_unit(LAS unsigned char* L, bf16_t* Z, const float* sinks, int b, int qb, int kvh) {
;     ...
;         for (int n = 0; n < 9; ++n) { const LAS bf16_t* kb = Ks + (kbase + 16 * n + l15) * 72 + quad * 8; f32x4 a4 = (f32x4){0.f, 0.f, 0.f, 0.f};
;             a4 = mfma16(qa0, *(const LAS bf16x8*)kb, a4); a4 = mfma16(qa1, *(const LAS bf16x8*)(kb + 32), a4); sc[n] = a4; }
;     ...
; #pragma unroll
;         for (int nd = 0; nd < 4; ++nd)
; #pragma unroll
;             for (int j = 0; j < 4; ++j) Z[(rowbase + t0 + kbase + quad * 4 + j) * ZLD + ZSQ + hq * 64 + nd * 16 + l15] = (bf16_t)hwbf(o4[nd][j] * rden[j]);
	v_mfma_f32_16x16x32_bf16 v[18:21], v[34:37], v[44:47], v[18:21]
	v_mad_u64_u32 v[34:35], s[0:1], v43, s74, v[54:55]
	v_mad_i32_i24 v35, s55, v250, v35
	v_lshl_add_u64 v[34:35], v[34:35], 0, v[66:67]
	v_lshl_add_u64 v[34:35], v[34:35], 0, v[0:1]
	v_lshl_add_u64 v[36:37], v[34:35], 0, s[16:17]
	v_add_co_u32_e64 v34, s[0:1], s78, v34
	s_nop 1
	v_mul_f32_e32 v18, v39, v18
	v_addc_co_u32_e64 v35, s[0:1], 0, v35, s[0:1]
	global_store_short v[34:35], v26, off offset:3072
	v_mul_f32_e32 v26, v40, v27
	s_nop 1
	v_cvt_pk_bf16_f32 v44, v26, v1
	v_or_b32_e32 v26, 1, v43
	v_mad_u64_u32 v[26:27], s[0:1], v26, s74, v[54:55]
	v_mad_i32_i24 v27, s55, v250, v27
	v_lshl_add_u64 v[26:27], v[26:27], 0, v[66:67]
	v_lshl_add_u64 v[26:27], v[26:27], 0, v[0:1]
	v_lshl_add_u64 v[34:35], v[26:27], 0, s[16:17]
	v_add_co_u32_e64 v26, s[0:1], s78, v26
	v_or_b32_e32 v51, v78, v60
	s_nop 0
	v_addc_co_u32_e64 v27, s[0:1], 0, v27, s[0:1]
	global_store_short v[26:27], v44, off offset:3072
	v_mul_f32_e32 v26, v41, v28
	s_nop 1
	v_cvt_pk_bf16_f32 v28, v26, v1
	v_or_b32_e32 v26, 2, v43
	v_mad_u64_u32 v[26:27], s[0:1], v26, s74, v[54:55]
	v_mad_i32_i24 v27, s55, v250, v27
	v_lshl_add_u64 v[26:27], v[26:27], 0, v[66:67]
	v_lshl_add_u64 v[26:27], v[26:27], 0, v[0:1]
	v_lshl_add_u64 v[44:45], v[26:27], 0, s[16:17]
	v_add_co_u32_e64 v26, s[0:1], s78, v26
	s_nop 1
	v_addc_co_u32_e64 v27, s[0:1], 0, v27, s[0:1]
	global_store_short v[26:27], v28, off offset:3072
	v_mul_f32_e32 v26, v42, v29
	s_nop 1
	v_cvt_pk_bf16_f32 v46, v26, v1
	v_or_b32_e32 v26, 3, v43
	v_mad_u64_u32 v[26:27], s[0:1], v26, s74, v[54:55]
	v_mad_i32_i24 v27, s55, v250, v27
	v_lshl_add_u64 v[26:27], v[26:27], 0, v[66:67]
	v_lshl_add_u64 v[26:27], v[26:27], 0, v[0:1]
	v_lshl_add_u64 v[28:29], v[26:27], 0, s[16:17]
	v_add_co_u32_e64 v26, s[0:1], s78, v26
	s_nop 1
	v_addc_co_u32_e64 v27, s[0:1], 0, v27, s[0:1]
	global_store_short v[26:27], v46, off offset:3072
	v_mul_f32_e32 v26, v39, v30
	s_nop 1
	v_cvt_pk_bf16_f32 v26, v26, v1
	global_store_short v[36:37], v26, off offset:32
	v_mul_f32_e32 v26, v40, v31
	s_nop 1
	v_cvt_pk_bf16_f32 v26, v26, v1
	global_store_short v[34:35], v26, off offset:32
	v_mul_f32_e32 v26, v41, v32
	s_nop 1
	v_cvt_pk_bf16_f32 v26, v26, v1
	global_store_short v[44:45], v26, off offset:32
	v_mul_f32_e32 v26, v42, v33
	s_nop 1
	v_cvt_pk_bf16_f32 v26, v26, v1
	global_store_short v[28:29], v26, off offset:32
	s_nop 1
	v_cvt_pk_bf16_f32 v22, v22, v1
	global_store_short v[36:37], v22, off offset:64
	v_mul_f32_e32 v22, v40, v23
	s_nop 1
	v_cvt_pk_bf16_f32 v22, v22, v1
	global_store_short v[34:35], v22, off offset:64
	v_mul_f32_e32 v22, v41, v24
	s_nop 1
	v_cvt_pk_bf16_f32 v22, v22, v1
	global_store_short v[44:45], v22, off offset:64
	v_mul_f32_e32 v22, v42, v25
	s_nop 1
	v_cvt_pk_bf16_f32 v22, v22, v1
	global_store_short v[28:29], v22, off offset:64
	s_nop 1
	v_cvt_pk_bf16_f32 v18, v18, v1
	global_store_short v[36:37], v18, off offset:96
	v_mul_f32_e32 v18, v40, v19
	s_nop 1
	v_cvt_pk_bf16_f32 v18, v18, v1
	global_store_short v[34:35], v18, off offset:96
	v_mul_f32_e32 v18, v41, v20
	s_nop 1
	v_cvt_pk_bf16_f32 v18, v18, v1
	global_store_short v[44:45], v18, off offset:96
	v_mul_f32_e32 v18, v42, v21
	s_nop 1
	v_cvt_pk_bf16_f32 v18, v18, v1
	global_store_short v[28:29], v18, off offset:96
	s_waitcnt lgkmcnt(0)
	v_mad_u32_u24 v39, v84, s67, v79
	ds_read_b128 v[18:21], v39
	ds_read_b128 v[22:25], v39 offset:64
	s_waitcnt lgkmcnt(1)
	v_mfma_f32_16x16x32_bf16 v[18:21], v[14:17], v[18:21], 0
	ds_read_b128 v[44:47], v39 offset:16192
	s_waitcnt lgkmcnt(1)
	v_mfma_f32_16x16x32_bf16 v[40:43], v[10:13], v[22:25], v[18:21]
	ds_read_b128 v[22:25], v39 offset:2368
	s_nop 3
	ds_read_b128 v[18:21], v39 offset:2304
	s_waitcnt lgkmcnt(0)
	v_mfma_f32_16x16x32_bf16 v[18:21], v[14:17], v[18:21], 0
	v_mfma_f32_16x16x32_bf16 v[86:89], v[10:13], v[22:25], v[18:21]
	ds_read_b128 v[22:25], v39 offset:4672
	s_nop 5
	ds_read_b128 v[18:21], v39 offset:4608
	s_waitcnt lgkmcnt(0)
	v_mfma_f32_16x16x32_bf16 v[18:21], v[14:17], v[18:21], 0
	v_mfma_f32_16x16x32_bf16 v[90:93], v[10:13], v[22:25], v[18:21]
	ds_read_b128 v[22:25], v39 offset:6976
	s_nop 5
	ds_read_b128 v[18:21], v39 offset:6912
	s_waitcnt lgkmcnt(0)
	v_mfma_f32_16x16x32_bf16 v[18:21], v[14:17], v[18:21], 0
	v_mfma_f32_16x16x32_bf16 v[34:37], v[10:13], v[22:25], v[18:21]
	ds_read_b128 v[22:25], v39 offset:9280
	s_nop 5
	ds_read_b128 v[18:21], v39 offset:9216
	s_waitcnt lgkmcnt(0)
	v_mfma_f32_16x16x32_bf16 v[18:21], v[14:17], v[18:21], 0
	v_mfma_f32_16x16x32_bf16 v[30:33], v[10:13], v[22:25], v[18:21]
	ds_read_b128 v[22:25], v39 offset:11584
	s_nop 5
	ds_read_b128 v[18:21], v39 offset:11520
	s_waitcnt lgkmcnt(0)
	v_mfma_f32_16x16x32_bf16 v[18:21], v[14:17], v[18:21], 0
	v_mfma_f32_16x16x32_bf16 v[26:29], v[10:13], v[22:25], v[18:21]
	ds_read_b128 v[22:25], v39 offset:13888
	s_nop 5
	ds_read_b128 v[18:21], v39 offset:13824
	s_waitcnt lgkmcnt(0)
	v_mfma_f32_16x16x32_bf16 v[18:21], v[14:17], v[18:21], 0
	v_mfma_f32_16x16x32_bf16 v[22:25], v[10:13], v[22:25], v[18:21]
	s_nop 6
	ds_read_b128 v[18:21], v39 offset:16128
	s_waitcnt lgkmcnt(0)
	v_mfma_f32_16x16x32_bf16 v[18:21], v[14:17], v[18:21], 0
	v_mfma_f32_16x16x32_bf16 v[18:21], v[10:13], v[44:47], v[18:21]
	ds_read_b128 v[44:47], v39 offset:18432
	s_waitcnt lgkmcnt(0)
	v_mfma_f32_16x16x32_bf16 v[14:17], v[14:17], v[44:47], 0
	ds_read_b128 v[44:47], v39 offset:18496
	s_waitcnt lgkmcnt(0)
; __device__ __forceinline__ void swa_unit(LAS unsigned char* L, bf16_t* Z, const float* sinks, int b, int qb, int kvh) {
;     ...
;         for (int n = 0; n < 9; ++n)
; #pragma unroll
;             for (int j = 0; j < 4; ++j) { const int qi = kbase + quad * 4 + j, kk = kbase + 16 * n + l15; const int dist = qi + 128 - kk;
;                 const bool valid = ((n >= 1 && n <= 7) || ((dist >= 0) && (dist < 128))) && (kk >= kmin);
;                 const float lg = valid ? sc[n][j] * (0.125f * 1.4426950408889634f) - slope * (float)dist : -INFINITY; sc[n][j] = lg; mx[j] = fmaxf(mx[j], lg); }
; #pragma unroll
;         for (int j = 0; j < 4; ++j) { mx[j] = fmaxf(mx[j], __shfl_xor(mx[j], 1)); mx[j] = fmaxf(mx[j], __shfl_xor(mx[j], 2)); mx[j] = fmaxf(mx[j], __shfl_xor(mx[j], 4)); mx[j] = fmaxf(mx[j], __shfl_xor(mx[j], 8)); }
	v_mfma_f32_16x16x32_bf16 v[10:13], v[10:13], v[44:47], v[14:17]
	v_sub_u32_e32 v46, v51, v59
	s_nop 3
	v_fma_f32 v16, v42, s36, -v83
	v_cndmask_b32_e64 v48, v251, v16, s[48:49]
	v_fma_f32 v16, v43, s36, -v85
	v_cndmask_b32_e64 v47, v251, v16, s[50:51]
	v_sub_u32_e32 v16, v51, v61
	v_cvt_f32_ubyte0_e32 v39, v16
	v_mul_f32_e32 v39, v75, v39
	v_fma_f32 v39, v86, s36, -v39
	v_cndmask_b32_e64 v42, v251, v39, s[42:43]
	v_add_u32_e32 v39, 1, v16
	v_cvt_f32_u32_e32 v39, v39
	v_fma_f32 v14, v40, s36, -v80
	v_cndmask_b32_e64 v50, v251, v14, s[44:45]
	v_max_f32_e32 v14, v77, v50
	v_mul_f32_e32 v39, v75, v39
	v_fma_f32 v39, v87, s36, -v39
	v_cndmask_b32_e64 v45, v251, v39, s[42:43]
	v_add_u32_e32 v39, 2, v16
	v_add_u32_e32 v16, 3, v16
	v_cvt_f32_u32_e32 v16, v16
	v_fma_f32 v15, v41, s36, -v81
	v_cndmask_b32_e64 v49, v251, v15, s[46:47]
	v_max_f32_e32 v15, v77, v49
	v_mul_f32_e32 v16, v75, v16
	v_fma_f32 v16, v89, s36, -v16
	v_cndmask_b32_e64 v44, v251, v16, s[42:43]
	v_cvt_f32_ubyte0_e32 v16, v46
	v_mul_f32_e32 v16, v75, v16
	v_fma_f32 v16, v90, s36, -v16
	v_cndmask_b32_e32 v16, v16, v251, vcc
	v_max3_f32 v52, v14, v42, v16
	v_add_u32_e32 v14, 1, v46
	v_cvt_f32_u32_e32 v14, v14
	v_max_f32_e32 v41, v77, v47
	v_cvt_f32_u32_e32 v39, v39
	v_max_f32_e32 v17, v77, v48
	v_mul_f32_e32 v14, v75, v14
	v_fma_f32 v14, v91, s36, -v14
	v_cndmask_b32_e32 v40, v14, v251, vcc
	v_add_u32_e32 v14, 2, v46
	v_cvt_f32_u32_e32 v14, v14
	v_max3_f32 v53, v15, v45, v40
	v_mul_f32_e32 v39, v75, v39
	v_fma_f32 v39, v88, s36, -v39
	v_mul_f32_e32 v14, v75, v14
	v_fma_f32 v14, v92, s36, -v14
	v_cndmask_b32_e32 v43, v14, v251, vcc
	v_add_u32_e32 v14, 3, v46
	v_cvt_f32_u32_e32 v14, v14
	v_cndmask_b32_e64 v39, v251, v39, s[42:43]
	v_max3_f32 v17, v17, v39, v43
	v_mul_f32_e32 v14, v75, v14
	v_fma_f32 v14, v93, s36, -v14
	v_cndmask_b32_e32 v46, v14, v251, vcc
	v_sub_u32_e32 v14, v51, v64
	v_cvt_f32_ubyte0_e32 v15, v14
	v_mul_f32_e32 v15, v75, v15
	v_fma_f32 v15, v34, s36, -v15
	v_add_u32_e32 v34, 2, v14
	v_max3_f32 v82, v41, v44, v46
	v_cndmask_b32_e32 v41, v15, v251, vcc
	v_add_u32_e32 v15, 1, v14
	v_cvt_f32_u32_e32 v34, v34
	v_add_u32_e32 v14, 3, v14
	v_cvt_f32_u32_e32 v14, v14
	v_cvt_f32_u32_e32 v15, v15
	v_mul_f32_e32 v34, v75, v34
	v_fma_f32 v34, v36, s36, -v34
	v_mul_f32_e32 v14, v75, v14
	v_sub_u32_e32 v36, v51, v62
	v_fma_f32 v14, v37, s36, -v14
	v_add_u32_e32 v37, 1, v36
	v_cvt_f32_i32_e32 v37, v37
	v_mul_f32_e32 v15, v75, v15
	v_fma_f32 v15, v35, s36, -v15
	v_cndmask_b32_e32 v35, v34, v251, vcc
	v_mul_f32_e32 v37, v75, v37
	v_cvt_f32_i32_e32 v34, v36
	v_fma_f32 v31, v31, s36, -v37
	v_add_u32_e32 v37, 2, v36
	v_add_u32_e32 v36, 3, v36
	v_cvt_f32_i32_e32 v36, v36
	v_mul_f32_e32 v34, v75, v34
	v_fma_f32 v30, v30, s36, -v34
	v_cndmask_b32_e32 v15, v15, v251, vcc
	v_mul_f32_e32 v36, v75, v36
	v_fma_f32 v33, v33, s36, -v36
	v_cndmask_b32_e32 v14, v14, v251, vcc
	v_cndmask_b32_e32 v34, v30, v251, vcc
	v_cndmask_b32_e32 v31, v31, v251, vcc
	v_cndmask_b32_e32 v33, v33, v251, vcc
	v_max3_f32 v30, v52, v41, v34
	v_max3_f32 v52, v53, v15, v31
	v_max3_f32 v53, v82, v14, v33
	v_sub_u32_e32 v82, v51, v65
	v_cvt_f32_i32_e32 v36, v82
	v_cvt_f32_i32_e32 v37, v37
	v_mul_f32_e32 v36, v75, v36
	v_mul_f32_e32 v37, v75, v37
	v_fma_f32 v26, v26, s36, -v36
	v_fma_f32 v32, v32, s36, -v37
	v_cndmask_b32_e32 v37, v26, v251, vcc
	v_add_u32_e32 v26, 1, v82
	v_cvt_f32_i32_e32 v26, v26
	v_cndmask_b32_e32 v32, v32, v251, vcc
	v_max3_f32 v17, v17, v35, v32
	v_mul_f32_e32 v26, v75, v26
	v_fma_f32 v26, v27, s36, -v26
	v_cndmask_b32_e32 v27, v26, v251, vcc
	v_add_u32_e32 v26, 2, v82
	v_cvt_f32_i32_e32 v26, v26
	v_mul_f32_e32 v26, v75, v26
	v_fma_f32 v26, v28, s36, -v26
	v_cndmask_b32_e32 v36, v26, v251, vcc
	v_add_u32_e32 v26, 3, v82
	v_sub_u32_e32 v82, v51, v63
	v_cvt_f32_i32_e32 v26, v26
	v_cvt_f32_i32_e32 v28, v82
	v_mul_f32_e32 v26, v75, v26
	v_mul_f32_e32 v28, v75, v28
	v_fma_f32 v26, v29, s36, -v26
	v_fma_f32 v29, v22, s36, -v28
	v_add_u32_e32 v22, 1, v82
	v_cvt_f32_i32_e32 v22, v22
	v_max3_f32 v84, v30, v37, v29
	v_or_b32_e32 v30, 0xa0, v76
	v_cndmask_b32_e32 v26, v26, v251, vcc
	v_mul_f32_e32 v22, v75, v22
	v_fma_f32 v23, v23, s36, -v22
	v_add_u32_e32 v22, 2, v82
	v_cvt_f32_i32_e32 v22, v22
	v_max3_f32 v52, v52, v27, v23
	v_mul_f32_e32 v22, v75, v22
	v_fma_f32 v28, v24, s36, -v22
	v_max3_f32 v86, v17, v36, v28
	v_add_u32_e32 v17, 3, v82
	v_cvt_f32_i32_e32 v17, v17
	v_mul_f32_e32 v17, v75, v17
	v_fma_f32 v22, v25, s36, -v17
	v_sub_u32_e32 v17, v51, v38
	v_cvt_f32_i32_e32 v24, v17
	v_sub_u32_e32 v51, v51, v30
	v_cmp_gt_u32_e64 s[0:1], s20, v51
	v_max3_f32 v25, v53, v26, v22
	v_mul_f32_e32 v24, v75, v24
	v_fma_f32 v24, v18, s36, -v24
	v_add_u32_e32 v18, 1, v17
	v_cvt_f32_i32_e32 v18, v18
	v_mul_f32_e32 v18, v75, v18
	v_fma_f32 v19, v19, s36, -v18
	v_add_u32_e32 v18, 2, v17
	v_cvt_f32_i32_e32 v18, v18
	v_add_u32_e32 v17, 3, v17
	v_cvt_f32_i32_e32 v17, v17
	v_mul_f32_e32 v18, v75, v18
	v_fma_f32 v20, v20, s36, -v18
	v_cvt_f32_i32_e32 v18, v51
	v_mul_f32_e32 v17, v75, v17
	v_fma_f32 v17, v21, s36, -v17
	v_add_u32_e32 v21, 1, v51
	v_mul_f32_e32 v18, v75, v18
	v_fma_f32 v10, v10, s36, -v18
	v_cndmask_b32_e64 v18, v251, v10, s[0:1]
	v_cmp_gt_u32_e64 s[0:1], s20, v21
	v_cvt_f32_i32_e32 v21, v21
	v_max3_f32 v10, v84, v24, v18
	v_mul_f32_e32 v21, v75, v21
	v_fma_f32 v11, v11, s36, -v21
	v_add_u32_e32 v21, 2, v51
	v_cndmask_b32_e64 v11, v251, v11, s[0:1]
	v_cmp_gt_u32_e64 s[0:1], s20, v21
	v_cvt_f32_i32_e32 v21, v21
	v_max3_f32 v52, v52, v19, v11
	v_mul_f32_e32 v21, v75, v21
	v_fma_f32 v12, v12, s36, -v21
	v_cndmask_b32_e64 v21, v251, v12, s[0:1]
	v_add_u32_e32 v12, 3, v51
	v_cmp_gt_u32_e64 s[0:1], s20, v12
	v_cvt_f32_i32_e32 v12, v12
	v_max3_f32 v53, v86, v20, v21
	v_mul_f32_e32 v12, v75, v12
	v_fma_f32 v12, v13, s36, -v12
	v_cndmask_b32_e64 v13, v251, v12, s[0:1]
	s_nop 1
	v_mov_b32_dpp v12, v10 quad_perm:[1,0,3,2] row_mask:0xf bank_mask:0xf
	v_max3_f32 v51, v25, v17, v13
	s_waitcnt lgkmcnt(0)
; __device__ __forceinline__ unsigned hwbf(float f) { return cvt_pk_bf16(f, 0.f) & 0xffffu; }
; __device__ __forceinline__ void swa_unit(LAS unsigned char* L, bf16_t* Z, const float* sinks, int b, int qb, int kvh) {
;     ...
;         for (int j = 0; j < 4; ++j) { mx[j] = fmaxf(mx[j], __shfl_xor(mx[j], 1)); mx[j] = fmaxf(mx[j], __shfl_xor(mx[j], 2)); mx[j] = fmaxf(mx[j], __shfl_xor(mx[j], 4)); mx[j] = fmaxf(mx[j], __shfl_xor(mx[j], 8)); }
;         float sum[4] = {0.f, 0.f, 0.f, 0.f};
; #pragma unroll
;         for (int n = 0; n < 9; ++n)
; #pragma unroll
;             for (int j = 0; j < 4; ++j) { const float p = __builtin_amdgcn_exp2f(sc[n][j] - mx[j]); sum[j] += p; Pw[(quad * 4 + j) * 168 + 16 * n + l15] = (bf16_t)hwbf(p); }
	v_max_f32_e32 v12, v12, v12
	v_max_f32_e32 v10, v10, v12
	s_nop 1
	v_mov_b32_dpp v12, v10 quad_perm:[2,3,0,1] row_mask:0xf bank_mask:0xf
	s_waitcnt lgkmcnt(0)
	v_max_f32_e32 v12, v12, v12
	v_max_f32_e32 v10, v10, v12
	s_nop 1
	v_mov_b32_dpp v12, v10 row_half_mirror row_mask:0xf bank_mask:0xf
	s_waitcnt lgkmcnt(0)
	v_max_f32_e32 v12, v12, v12
	v_max_f32_e32 v10, v10, v12
	s_nop 1
	v_mov_b32_dpp v12, v10 row_mirror row_mask:0xf bank_mask:0xf
	s_waitcnt lgkmcnt(0)
	v_max_f32_e32 v12, v12, v12
	v_max_f32_e32 v10, v10, v12
	s_nop 1
	v_mov_b32_dpp v12, v52 quad_perm:[1,0,3,2] row_mask:0xf bank_mask:0xf
	v_sub_f32_e32 v50, v50, v10
	v_exp_f32_e32 v50, v50
	v_sub_f32_e32 v42, v42, v10
	v_exp_f32_e32 v42, v42
	s_waitcnt lgkmcnt(0)
	v_max_f32_e32 v12, v12, v12
	v_max_f32_e32 v12, v52, v12
	s_nop 1
	v_mov_b32_dpp v25, v12 quad_perm:[2,3,0,1] row_mask:0xf bank_mask:0xf
	v_sub_f32_e32 v16, v16, v10
	v_exp_f32_e32 v16, v16
	s_waitcnt lgkmcnt(0)
	v_max_f32_e32 v25, v25, v25
	v_max_f32_e32 v12, v12, v25
	s_nop 1
	v_mov_b32_dpp v25, v12 row_half_mirror row_mask:0xf bank_mask:0xf
	s_waitcnt lgkmcnt(0)
	v_max_f32_e32 v25, v25, v25
	v_max_f32_e32 v12, v12, v25
	s_nop 1
	v_mov_b32_dpp v25, v12 row_mirror row_mask:0xf bank_mask:0xf
	s_waitcnt lgkmcnt(0)
	v_max_f32_e32 v25, v25, v25
	v_max_f32_e32 v12, v12, v25
	s_nop 1
	v_mov_b32_dpp v25, v53 quad_perm:[1,0,3,2] row_mask:0xf bank_mask:0xf
	v_sub_f32_e32 v49, v49, v12
	v_exp_f32_e32 v49, v49
	v_sub_f32_e32 v15, v15, v12
	v_exp_f32_e32 v15, v15
	s_waitcnt lgkmcnt(0)
	v_max_f32_e32 v25, v25, v25
	v_max_f32_e32 v25, v53, v25
	s_nop 1
	v_mov_b32_dpp v52, v25 quad_perm:[2,3,0,1] row_mask:0xf bank_mask:0xf
	v_sub_f32_e32 v11, v11, v12
	v_exp_f32_e32 v11, v11
	s_waitcnt lgkmcnt(0)
	v_max_f32_e32 v52, v52, v52
	v_max_f32_e32 v25, v25, v52
	s_nop 1
	v_mov_b32_dpp v52, v25 row_half_mirror row_mask:0xf bank_mask:0xf
	s_waitcnt lgkmcnt(0)
	v_max_f32_e32 v52, v52, v52
	v_max_f32_e32 v25, v25, v52
	s_nop 1
	v_mov_b32_dpp v52, v25 row_mirror row_mask:0xf bank_mask:0xf
	s_waitcnt lgkmcnt(0)
	v_max_f32_e32 v52, v52, v52
	v_max_f32_e32 v25, v25, v52
	s_nop 1
	v_mov_b32_dpp v52, v51 quad_perm:[1,0,3,2] row_mask:0xf bank_mask:0xf
	v_sub_f32_e32 v48, v48, v25
	v_exp_f32_e32 v48, v48
	v_sub_f32_e32 v39, v39, v25
	v_exp_f32_e32 v39, v39
	s_waitcnt lgkmcnt(0)
	v_max_f32_e32 v52, v52, v52
	v_max_f32_e32 v51, v51, v52
	s_nop 1
	v_mov_b32_dpp v52, v51 quad_perm:[2,3,0,1] row_mask:0xf bank_mask:0xf
	s_waitcnt lgkmcnt(0)
	v_max_f32_e32 v52, v52, v52
	v_max_f32_e32 v51, v51, v52
	s_nop 1
	v_mov_b32_dpp v52, v51 row_half_mirror row_mask:0xf bank_mask:0xf
	s_waitcnt lgkmcnt(0)
	v_max_f32_e32 v52, v52, v52
	v_max_f32_e32 v51, v51, v52
	s_nop 1
	v_mov_b32_dpp v52, v51 row_mirror row_mask:0xf bank_mask:0xf
	s_waitcnt lgkmcnt(0)
	v_max_f32_e32 v52, v52, v52
	v_max_f32_e32 v51, v51, v52
	v_sub_f32_e32 v47, v47, v51
	v_exp_f32_e32 v47, v47
	v_add_f32_e32 v52, 0, v50
	s_nop 1
	v_cvt_pk_bf16_f32 v50, v50, v1
	ds_write_b16 v57, v50
	v_add_f32_e32 v50, 0, v49
	s_nop 1
	v_cvt_pk_bf16_f32 v49, v49, v1
	ds_write_b16 v57, v49 offset:336
	v_add_f32_e32 v49, 0, v48
	s_nop 1
	v_cvt_pk_bf16_f32 v48, v48, v1
	ds_write_b16 v57, v48 offset:672
	v_add_f32_e32 v48, 0, v47
	s_nop 1
	v_cvt_pk_bf16_f32 v47, v47, v1
	ds_write_b16 v57, v47 offset:1008
	v_add_f32_e32 v47, v42, v52
	s_nop 1
	v_cvt_pk_bf16_f32 v42, v42, v1
	ds_write_b16 v57, v42 offset:32
	v_sub_f32_e32 v42, v45, v12
	v_exp_f32_e32 v42, v42
	v_sub_f32_e32 v14, v14, v51
	v_exp_f32_e32 v14, v14
	v_add_f32_e32 v45, v42, v50
	s_nop 1
	v_cvt_pk_bf16_f32 v42, v42, v1
	ds_write_b16 v57, v42 offset:368
	v_add_f32_e32 v42, v39, v49
	s_nop 1
	v_cvt_pk_bf16_f32 v39, v39, v1
	ds_write_b16 v57, v39 offset:704
	v_sub_f32_e32 v39, v44, v51
	v_exp_f32_e32 v39, v39
	s_nop 0
	v_add_f32_e32 v44, v39, v48
	s_nop 1
	v_cvt_pk_bf16_f32 v39, v39, v1
	ds_write_b16 v57, v39 offset:1040
	v_add_f32_e32 v39, v16, v47
	s_nop 1
	v_cvt_pk_bf16_f32 v16, v16, v1
	ds_write_b16 v57, v16 offset:64
	v_sub_f32_e32 v16, v40, v12
	v_exp_f32_e32 v16, v16
	s_nop 0
	v_add_f32_e32 v40, v16, v45
	s_nop 1
	v_cvt_pk_bf16_f32 v16, v16, v1
	ds_write_b16 v57, v16 offset:400
	v_sub_f32_e32 v16, v43, v25
	v_exp_f32_e32 v16, v16
	s_nop 0
	v_add_f32_e32 v42, v16, v42
	s_nop 1
	v_cvt_pk_bf16_f32 v16, v16, v1
	ds_write_b16 v57, v16 offset:736
	v_sub_f32_e32 v16, v46, v51
	v_exp_f32_e32 v16, v16
	s_nop 0
	v_add_f32_e32 v43, v16, v44
	s_nop 1
	v_cvt_pk_bf16_f32 v16, v16, v1
	ds_write_b16 v57, v16 offset:1072
	v_sub_f32_e32 v16, v41, v10
	v_exp_f32_e32 v16, v16
	s_nop 0
	v_add_f32_e32 v39, v16, v39
	s_nop 1
	v_cvt_pk_bf16_f32 v16, v16, v1
	ds_write_b16 v57, v16 offset:96
	v_add_f32_e32 v16, v15, v40
	s_nop 1
	v_cvt_pk_bf16_f32 v15, v15, v1
	ds_write_b16 v57, v15 offset:432
	v_sub_f32_e32 v15, v35, v25
	v_exp_f32_e32 v15, v15
	s_nop 0
	v_add_f32_e32 v35, v15, v42
	s_nop 1
	v_cvt_pk_bf16_f32 v15, v15, v1
	ds_write_b16 v57, v15 offset:768
	v_add_f32_e32 v15, v14, v43
	s_nop 1
	v_cvt_pk_bf16_f32 v14, v14, v1
	ds_write_b16 v57, v14 offset:1104
	v_sub_f32_e32 v14, v34, v10
	v_exp_f32_e32 v14, v14
	s_nop 0
	v_add_f32_e32 v34, v14, v39
	s_nop 1
	v_cvt_pk_bf16_f32 v14, v14, v1
	ds_write_b16 v57, v14 offset:128
	v_sub_f32_e32 v14, v31, v12
	v_exp_f32_e32 v14, v14
	s_nop 0
	v_add_f32_e32 v16, v14, v16
	s_nop 1
	v_cvt_pk_bf16_f32 v14, v14, v1
	ds_write_b16 v57, v14 offset:464
	v_sub_f32_e32 v14, v32, v25
	v_exp_f32_e32 v14, v14
	s_nop 0
	v_add_f32_e32 v31, v14, v35
	s_nop 1
	v_cvt_pk_bf16_f32 v14, v14, v1
	ds_write_b16 v57, v14 offset:800
	v_sub_f32_e32 v14, v33, v51
	v_exp_f32_e32 v14, v14
	v_or3_b32 v35, v68, v60, s54
	v_add_f32_e32 v15, v14, v15
	s_nop 1
; #define LAS __attribute__((address_space(3)))
; __device__ __forceinline__ unsigned hwbf(float f) { return cvt_pk_bf16(f, 0.f) & 0xffffu; }
; __device__ __forceinline__ f32x4 mfma16(bf16x8 a, bf16x8 b, f32x4 c) { return __builtin_amdgcn_mfma_f32_16x16x32_bf16(a, b, c, 0, 0, 0); }
; __device__ __forceinline__ void swa_unit(LAS unsigned char* L, bf16_t* Z, const float* sinks, int b, int qb, int kvh) {
;     ...
;         for (int n = 0; n < 9; ++n)
; #pragma unroll
;             for (int j = 0; j < 4; ++j) { const float p = __builtin_amdgcn_exp2f(sc[n][j] - mx[j]); sum[j] += p; Pw[(quad * 4 + j) * 168 + 16 * n + l15] = (bf16_t)hwbf(p); }
;         float rden[4];
; #pragma unroll
;         for (int j = 0; j < 4; ++j) { sum[j] += __shfl_xor(sum[j], 1); sum[j] += __shfl_xor(sum[j], 2); sum[j] += __shfl_xor(sum[j], 4); sum[j] += __shfl_xor(sum[j], 8);
;             rden[j] = __builtin_amdgcn_rcpf(sum[j] + __builtin_amdgcn_exp2f(sink - mx[j])); }
;         asm volatile("s_waitcnt lgkmcnt(0)" ::: "memory");
;         f32x4 o4[4];
; #pragma unroll
;         for (int nd = 0; nd < 4; ++nd) o4[nd] = (f32x4){0.f, 0.f, 0.f, 0.f};
; #pragma unroll
;         for (int ks = 0; ks < 5; ++ks) { const bf16x8 a = *(const LAS bf16x8*)(Pw + l15 * 168 + ks * 32 + quad * 8);
; #pragma unroll
;             for (int nd = 0; nd < 4; ++nd) o4[nd] = mfma16(a, *(const LAS bf16x8*)(Vt + (nd * 16 + l15) * 280 + kbase + ks * 32 + quad * 8), o4[nd]); }
	v_cvt_pk_bf16_f32 v14, v14, v1
	ds_write_b16 v57, v14 offset:1136
	v_sub_f32_e32 v14, v37, v10
	v_exp_f32_e32 v14, v14
	s_nop 0
	v_add_f32_e32 v32, v14, v34
	s_nop 1
	v_cvt_pk_bf16_f32 v14, v14, v1
	ds_write_b16 v57, v14 offset:160
	v_sub_f32_e32 v14, v27, v12
	v_exp_f32_e32 v14, v14
	s_nop 0
	v_add_f32_e32 v16, v14, v16
	s_nop 1
	v_cvt_pk_bf16_f32 v14, v14, v1
	ds_write_b16 v57, v14 offset:496
	v_sub_f32_e32 v14, v36, v25
	v_exp_f32_e32 v14, v14
	s_nop 0
	v_add_f32_e32 v27, v14, v31
	s_nop 1
	v_cvt_pk_bf16_f32 v14, v14, v1
	ds_write_b16 v57, v14 offset:832
	v_sub_f32_e32 v14, v26, v51
	v_exp_f32_e32 v14, v14
	s_nop 0
	v_add_f32_e32 v15, v14, v15
	s_nop 1
	v_cvt_pk_bf16_f32 v14, v14, v1
	ds_write_b16 v57, v14 offset:1168
	v_sub_f32_e32 v14, v29, v10
	v_exp_f32_e32 v14, v14
	s_nop 0
	v_add_f32_e32 v26, v14, v32
	s_nop 1
	v_cvt_pk_bf16_f32 v14, v14, v1
	ds_write_b16 v57, v14 offset:192
	v_sub_f32_e32 v14, v23, v12
	v_exp_f32_e32 v14, v14
	s_nop 0
	v_add_f32_e32 v16, v14, v16
	s_nop 1
	v_cvt_pk_bf16_f32 v14, v14, v1
	ds_write_b16 v57, v14 offset:528
	v_sub_f32_e32 v14, v28, v25
	v_exp_f32_e32 v14, v14
	s_nop 0
	v_add_f32_e32 v23, v14, v27
	s_nop 1
	v_cvt_pk_bf16_f32 v14, v14, v1
	ds_write_b16 v57, v14 offset:864
	v_sub_f32_e32 v14, v22, v51
	v_exp_f32_e32 v14, v14
	s_nop 0
	v_add_f32_e32 v15, v14, v15
	s_nop 1
	v_cvt_pk_bf16_f32 v14, v14, v1
	ds_write_b16 v57, v14 offset:1200
	v_sub_f32_e32 v14, v24, v10
	v_exp_f32_e32 v14, v14
	s_nop 0
	v_add_f32_e32 v22, v14, v26
	s_nop 1
	v_cvt_pk_bf16_f32 v14, v14, v1
	ds_write_b16 v57, v14 offset:224
	v_sub_f32_e32 v14, v19, v12
	v_exp_f32_e32 v14, v14
	s_nop 0
	v_add_f32_e32 v16, v14, v16
	s_nop 1
	v_cvt_pk_bf16_f32 v14, v14, v1
	ds_write_b16 v57, v14 offset:560
	v_sub_f32_e32 v14, v20, v25
	v_exp_f32_e32 v14, v14
	s_nop 0
	v_add_f32_e32 v19, v14, v23
	s_nop 1
	v_cvt_pk_bf16_f32 v14, v14, v1
	ds_write_b16 v57, v14 offset:896
	v_sub_f32_e32 v14, v17, v51
	v_exp_f32_e32 v14, v14
	s_nop 0
	v_add_f32_e32 v15, v14, v15
	s_nop 1
	v_cvt_pk_bf16_f32 v14, v14, v1
	ds_write_b16 v57, v14 offset:1232
	v_sub_f32_e32 v14, v18, v10
	v_exp_f32_e32 v14, v14
	v_fma_f32 v10, v70, s34, -v10
	v_exp_f32_e32 v10, v10
	v_add_f32_e32 v17, v14, v22
	s_nop 1
	v_cvt_pk_bf16_f32 v14, v14, v1
	ds_write_b16 v57, v14 offset:256
	v_add_f32_e32 v14, v11, v16
	s_nop 1
	v_cvt_pk_bf16_f32 v11, v11, v1
	ds_write_b16 v57, v11 offset:592
	v_sub_f32_e32 v11, v21, v25
	v_exp_f32_e32 v11, v11
	s_nop 0
	v_add_f32_e32 v16, v11, v19
	s_nop 1
	v_cvt_pk_bf16_f32 v11, v11, v1
	ds_write_b16 v57, v11 offset:928
	v_sub_f32_e32 v11, v13, v51
	v_exp_f32_e32 v11, v11
	s_nop 0
	v_add_f32_e32 v13, v11, v15
	s_nop 1
	v_cvt_pk_bf16_f32 v11, v11, v1
	ds_write_b16 v57, v11 offset:1264
	s_nop 1
	v_mov_b32_dpp v11, v17 quad_perm:[1,0,3,2] row_mask:0xf bank_mask:0xf
	s_waitcnt lgkmcnt(0)
	s_waitcnt lgkmcnt(0)
	v_add_f32_e32 v11, v17, v11
	s_nop 1
	v_mov_b32_dpp v15, v11 quad_perm:[2,3,0,1] row_mask:0xf bank_mask:0xf
	s_waitcnt lgkmcnt(0)
	v_add_f32_e32 v11, v11, v15
	s_nop 1
	v_mov_b32_dpp v15, v11 row_half_mirror row_mask:0xf bank_mask:0xf
	s_waitcnt lgkmcnt(0)
	v_add_f32_e32 v11, v11, v15
	s_nop 1
	v_mov_b32_dpp v15, v11 row_mirror row_mask:0xf bank_mask:0xf
	s_waitcnt lgkmcnt(0)
	v_add_f32_e32 v11, v11, v15
	v_add_f32_e32 v10, v10, v11
	v_rcp_f32_e32 v31, v10
	s_nop 1
	v_mov_b32_dpp v10, v14 quad_perm:[1,0,3,2] row_mask:0xf bank_mask:0xf
	s_waitcnt lgkmcnt(0)
	v_add_f32_e32 v10, v14, v10
	s_nop 1
	v_mov_b32_dpp v11, v10 quad_perm:[2,3,0,1] row_mask:0xf bank_mask:0xf
	s_waitcnt lgkmcnt(0)
	v_add_f32_e32 v10, v10, v11
	s_nop 1
	v_mov_b32_dpp v11, v10 row_half_mirror row_mask:0xf bank_mask:0xf
	s_waitcnt lgkmcnt(0)
	v_add_f32_e32 v10, v10, v11
	s_nop 1
	v_mov_b32_dpp v11, v10 row_mirror row_mask:0xf bank_mask:0xf
	s_waitcnt lgkmcnt(0)
	v_add_f32_e32 v10, v10, v11
	v_fma_f32 v11, v70, s34, -v12
	v_exp_f32_e32 v11, v11
	s_nop 0
	v_add_f32_e32 v10, v11, v10
	v_rcp_f32_e32 v32, v10
	s_nop 1
	v_mov_b32_dpp v10, v16 quad_perm:[1,0,3,2] row_mask:0xf bank_mask:0xf
	s_waitcnt lgkmcnt(0)
	v_add_f32_e32 v10, v16, v10
	s_nop 1
	v_mov_b32_dpp v11, v10 quad_perm:[2,3,0,1] row_mask:0xf bank_mask:0xf
	s_waitcnt lgkmcnt(0)
	v_add_f32_e32 v10, v10, v11
	s_nop 1
	v_mov_b32_dpp v11, v10 row_half_mirror row_mask:0xf bank_mask:0xf
	s_waitcnt lgkmcnt(0)
	v_add_f32_e32 v10, v10, v11
	s_nop 1
	v_mov_b32_dpp v11, v10 row_mirror row_mask:0xf bank_mask:0xf
	s_waitcnt lgkmcnt(0)
	v_add_f32_e32 v10, v10, v11
	v_fma_f32 v11, v70, s34, -v25
	v_exp_f32_e32 v11, v11
	s_nop 0
	v_add_f32_e32 v10, v11, v10
	v_rcp_f32_e32 v33, v10
	s_nop 1
	v_mov_b32_dpp v10, v13 quad_perm:[1,0,3,2] row_mask:0xf bank_mask:0xf
	s_waitcnt lgkmcnt(0)
	v_add_f32_e32 v10, v13, v10
	s_nop 1
	v_mov_b32_dpp v11, v10 quad_perm:[2,3,0,1] row_mask:0xf bank_mask:0xf
	s_waitcnt lgkmcnt(0)
	v_add_f32_e32 v10, v10, v11
	s_nop 1
	v_mov_b32_dpp v11, v10 row_half_mirror row_mask:0xf bank_mask:0xf
	s_waitcnt lgkmcnt(0)
	v_add_f32_e32 v10, v10, v11
	s_nop 1
	v_mov_b32_dpp v11, v10 row_mirror row_mask:0xf bank_mask:0xf
	s_waitcnt lgkmcnt(0)
	v_add_f32_e32 v10, v10, v11
	v_fma_f32 v11, v70, s34, -v51
	v_exp_f32_e32 v11, v11
	s_nop 0
	v_add_f32_e32 v10, v11, v10
	v_rcp_f32_e32 v34, v10
	ds_read_b128 v[10:13], v69
	ds_read_b128 v[14:17], v58 offset:36928
	ds_read_b128 v[18:21], v58 offset:45888
	ds_read_b128 v[22:25], v58 offset:54848
	ds_read_b128 v[26:29], v58 offset:63808
	s_waitcnt lgkmcnt(3)
	v_mfma_f32_16x16x32_bf16 v[14:17], v[10:13], v[14:17], 0
	s_waitcnt lgkmcnt(2)
	v_mfma_f32_16x16x32_bf16 v[18:21], v[10:13], v[18:21], 0
	s_waitcnt lgkmcnt(1)
	v_mfma_f32_16x16x32_bf16 v[22:25], v[10:13], v[22:25], 0
	s_waitcnt lgkmcnt(0)
; #define LAS __attribute__((address_space(3)))
; __device__ __forceinline__ unsigned hwbf(float f) { return cvt_pk_bf16(f, 0.f) & 0xffffu; }
; __device__ __forceinline__ f32x4 mfma16(bf16x8 a, bf16x8 b, f32x4 c) { return __builtin_amdgcn_mfma_f32_16x16x32_bf16(a, b, c, 0, 0, 0); }
; __device__ __forceinline__ void swa_unit(LAS unsigned char* L, bf16_t* Z, const float* sinks, int b, int qb, int kvh) {
;     ...
;         for (int ks = 0; ks < 5; ++ks) { const bf16x8 a = *(const LAS bf16x8*)(Pw + l15 * 168 + ks * 32 + quad * 8);
; #pragma unroll
;             for (int nd = 0; nd < 4; ++nd) o4[nd] = mfma16(a, *(const LAS bf16x8*)(Vt + (nd * 16 + l15) * 280 + kbase + ks * 32 + quad * 8), o4[nd]); }
; #pragma unroll
;         for (int nd = 0; nd < 4; ++nd)
; #pragma unroll
;             for (int j = 0; j < 4; ++j) Z[(rowbase + t0 + kbase + quad * 4 + j) * ZLD + ZSQ + hq * 64 + nd * 16 + l15] = (bf16_t)hwbf(o4[nd][j] * rden[j]);
	v_mfma_f32_16x16x32_bf16 v[10:13], v[10:13], v[26:29], 0
	ds_read_b128 v[26:29], v69 offset:64
	ds_read_b128 v[40:43], v58 offset:36992
	s_waitcnt lgkmcnt(0)
	v_mfma_f32_16x16x32_bf16 v[14:17], v[26:29], v[40:43], v[14:17]
	ds_read_b128 v[40:43], v58 offset:45952
	s_waitcnt lgkmcnt(0)
	v_mfma_f32_16x16x32_bf16 v[18:21], v[26:29], v[40:43], v[18:21]
	ds_read_b128 v[40:43], v58 offset:54912
	s_waitcnt lgkmcnt(0)
	v_mfma_f32_16x16x32_bf16 v[22:25], v[26:29], v[40:43], v[22:25]
	ds_read_b128 v[40:43], v58 offset:63872
	s_waitcnt lgkmcnt(0)
	v_mfma_f32_16x16x32_bf16 v[10:13], v[26:29], v[40:43], v[10:13]
	ds_read_b128 v[26:29], v69 offset:128
	ds_read_b128 v[40:43], v58 offset:37056
	s_waitcnt lgkmcnt(0)
	v_mfma_f32_16x16x32_bf16 v[14:17], v[26:29], v[40:43], v[14:17]
	ds_read_b128 v[40:43], v58 offset:46016
	s_waitcnt lgkmcnt(0)
	v_mfma_f32_16x16x32_bf16 v[18:21], v[26:29], v[40:43], v[18:21]
	ds_read_b128 v[40:43], v58 offset:54976
	s_waitcnt lgkmcnt(0)
	v_mfma_f32_16x16x32_bf16 v[22:25], v[26:29], v[40:43], v[22:25]
	ds_read_b128 v[40:43], v58 offset:63936
	s_waitcnt lgkmcnt(0)
	v_mfma_f32_16x16x32_bf16 v[10:13], v[26:29], v[40:43], v[10:13]
	ds_read_b128 v[26:29], v69 offset:192
	ds_read_b128 v[40:43], v58 offset:37120
	s_waitcnt lgkmcnt(0)
	v_mfma_f32_16x16x32_bf16 v[40:43], v[26:29], v[40:43], v[14:17]
	s_nop 2
	ds_read_b128 v[14:17], v58 offset:46080
	s_waitcnt lgkmcnt(0)
	v_mfma_f32_16x16x32_bf16 v[44:47], v[26:29], v[14:17], v[18:21]
	ds_read_b128 v[14:17], v58 offset:55040
	s_nop 1
	ds_read_b128 v[18:21], v58 offset:64000
	s_waitcnt lgkmcnt(1)
	v_mfma_f32_16x16x32_bf16 v[14:17], v[26:29], v[14:17], v[22:25]
	s_waitcnt lgkmcnt(0)
	v_mfma_f32_16x16x32_bf16 v[10:13], v[26:29], v[18:21], v[10:13]
	ds_read_b128 v[26:29], v69 offset:256
	ds_read_b128 v[18:21], v58 offset:37184
	ds_read_b128 v[22:25], v58 offset:46144
	s_waitcnt lgkmcnt(1)
	v_mfma_f32_16x16x32_bf16 v[18:21], v[26:29], v[18:21], v[40:43]
	s_nop 2
	ds_read_b128 v[40:43], v58 offset:55104
	s_waitcnt lgkmcnt(0)
	v_mfma_f32_16x16x32_bf16 v[14:17], v[26:29], v[40:43], v[14:17]
	ds_read_b128 v[40:43], v58 offset:64064
	s_nop 0
	v_mul_f32_e32 v18, v31, v18
	s_nop 1
	v_cvt_pk_bf16_f32 v18, v18, v1
	v_mfma_f32_16x16x32_bf16 v[22:25], v[26:29], v[22:25], v[44:47]
	s_nop 3
	v_mul_f32_e32 v14, v31, v14
	s_waitcnt lgkmcnt(0)
	v_mfma_f32_16x16x32_bf16 v[10:13], v[26:29], v[40:43], v[10:13]
	v_mad_u64_u32 v[26:27], s[0:1], v35, s74, v[54:55]
	v_mad_i32_i24 v27, s55, v250, v27
	v_lshl_add_u64 v[26:27], v[26:27], 0, v[66:67]
	v_lshl_add_u64 v[26:27], v[26:27], 0, v[0:1]
	v_lshl_add_u64 v[28:29], v[26:27], 0, s[16:17]
	v_add_co_u32_e64 v26, s[0:1], s78, v26
	s_nop 1
	v_mul_f32_e32 v10, v31, v10
	v_addc_co_u32_e64 v27, s[0:1], 0, v27, s[0:1]
	global_store_short v[26:27], v18, off offset:3072
	v_mul_f32_e32 v18, v32, v19
	s_nop 1
	v_cvt_pk_bf16_f32 v36, v18, v1
	v_or_b32_e32 v18, 1, v35
	v_mad_u64_u32 v[18:19], s[0:1], v18, s74, v[54:55]
	v_mad_i32_i24 v19, s55, v250, v19
	v_lshl_add_u64 v[18:19], v[18:19], 0, v[66:67]
	v_lshl_add_u64 v[18:19], v[18:19], 0, v[0:1]
	v_lshl_add_u64 v[26:27], v[18:19], 0, s[16:17]
	v_add_co_u32_e64 v18, s[0:1], s78, v18
	s_nop 1
	v_addc_co_u32_e64 v19, s[0:1], 0, v19, s[0:1]
	global_store_short v[18:19], v36, off offset:3072
	v_mul_f32_e32 v18, v33, v20
	s_nop 1
	v_cvt_pk_bf16_f32 v20, v18, v1
	v_or_b32_e32 v18, 2, v35
	v_mad_u64_u32 v[18:19], s[0:1], v18, s74, v[54:55]
	v_mad_i32_i24 v19, s55, v250, v19
	v_lshl_add_u64 v[18:19], v[18:19], 0, v[66:67]
	v_lshl_add_u64 v[18:19], v[18:19], 0, v[0:1]
	v_lshl_add_u64 v[36:37], v[18:19], 0, s[16:17]
	v_add_co_u32_e64 v18, s[0:1], s78, v18
	s_nop 1
	v_addc_co_u32_e64 v19, s[0:1], 0, v19, s[0:1]
	global_store_short v[18:19], v20, off offset:3072
	v_mul_f32_e32 v18, v34, v21
	s_nop 1
	v_cvt_pk_bf16_f32 v39, v18, v1
	v_or_b32_e32 v18, 3, v35
	v_mad_u64_u32 v[18:19], s[0:1], v18, s74, v[54:55]
	v_mad_i32_i24 v19, s55, v250, v19
	v_lshl_add_u64 v[18:19], v[18:19], 0, v[66:67]
	v_lshl_add_u64 v[18:19], v[18:19], 0, v[0:1]
	v_lshl_add_u64 v[20:21], v[18:19], 0, s[16:17]
	v_add_co_u32_e64 v18, s[0:1], s78, v18
	s_nop 1
	v_addc_co_u32_e64 v19, s[0:1], 0, v19, s[0:1]
	global_store_short v[18:19], v39, off offset:3072
	v_mul_f32_e32 v18, v31, v22
	s_nop 1
	v_cvt_pk_bf16_f32 v18, v18, v1
	global_store_short v[28:29], v18, off offset:32
	v_mul_f32_e32 v18, v32, v23
	s_nop 1
	v_cvt_pk_bf16_f32 v18, v18, v1
	global_store_short v[26:27], v18, off offset:32
	v_mul_f32_e32 v18, v33, v24
	s_nop 1
	v_cvt_pk_bf16_f32 v18, v18, v1
	global_store_short v[36:37], v18, off offset:32
	v_mul_f32_e32 v18, v34, v25
	s_nop 1
	v_cvt_pk_bf16_f32 v18, v18, v1
	global_store_short v[20:21], v18, off offset:32
	s_nop 1
	v_cvt_pk_bf16_f32 v14, v14, v1
	global_store_short v[28:29], v14, off offset:64
	v_mul_f32_e32 v14, v32, v15
	s_nop 1
	v_cvt_pk_bf16_f32 v14, v14, v1
	global_store_short v[26:27], v14, off offset:64
	v_mul_f32_e32 v14, v33, v16
	s_nop 1
	v_cvt_pk_bf16_f32 v14, v14, v1
	global_store_short v[36:37], v14, off offset:64
	v_mul_f32_e32 v14, v34, v17
	s_nop 1
	v_cvt_pk_bf16_f32 v14, v14, v1
	global_store_short v[20:21], v14, off offset:64
	s_nop 1
	v_cvt_pk_bf16_f32 v10, v10, v1
	global_store_short v[28:29], v10, off offset:96
	v_mul_f32_e32 v10, v32, v11
	s_nop 1
	v_cvt_pk_bf16_f32 v10, v10, v1
	global_store_short v[26:27], v10, off offset:96
	v_mul_f32_e32 v10, v33, v12
	s_nop 1
	v_cvt_pk_bf16_f32 v10, v10, v1
	global_store_short v[36:37], v10, off offset:96
	v_mul_f32_e32 v10, v34, v13
	s_nop 1
	v_cvt_pk_bf16_f32 v10, v10, v1
	global_store_short v[20:21], v10, off offset:96
	s_waitcnt lgkmcnt(0)
; #define LAS __attribute__((address_space(3)))
; __device__ __forceinline__ f32x4 mfma16(bf16x8 a, bf16x8 b, f32x4 c) { return __builtin_amdgcn_mfma_f32_16x16x32_bf16(a, b, c, 0, 0, 0); }
; __device__ __forceinline__ void swa_unit(LAS unsigned char* L, bf16_t* Z, const float* sinks, int b, int qb, int kvh) {
;     ...
;         for (int n = 0; n < 9; ++n) { const LAS bf16_t* kb = Ks + (kbase + 16 * n + l15) * 72 + quad * 8; f32x4 a4 = (f32x4){0.f, 0.f, 0.f, 0.f};
;             a4 = mfma16(qa0, *(const LAS bf16x8*)kb, a4); a4 = mfma16(qa1, *(const LAS bf16x8*)(kb + 32), a4); sc[n] = a4; }
;         float mx[4] = {sink, sink, sink, sink};
; #pragma unroll
;         for (int n = 0; n < 9; ++n)
; #pragma unroll
;             for (int j = 0; j < 4; ++j) { const int qi = kbase + quad * 4 + j, kk = kbase + 16 * n + l15; const int dist = qi + 128 - kk;
;                 const bool valid = ((n >= 1 && n <= 7) || ((dist >= 0) && (dist < 128))) && (kk >= kmin);
;                 const float lg = valid ? sc[n][j] * (0.125f * 1.4426950408889634f) - slope * (float)dist : -INFINITY; sc[n][j] = lg; mx[j] = fmaxf(mx[j], lg); }
	v_mad_u32_u24 v31, v61, s67, v79
	ds_read_b128 v[10:13], v31
	ds_read_b128 v[14:17], v31 offset:64
	s_waitcnt lgkmcnt(1)
	v_mfma_f32_16x16x32_bf16 v[10:13], v[6:9], v[10:13], 0
	ds_read_b128 v[40:43], v31 offset:16192
	s_waitcnt lgkmcnt(1)
	v_mfma_f32_16x16x32_bf16 v[32:35], v[2:5], v[14:17], v[10:13]
	ds_read_b128 v[14:17], v31 offset:2368
	s_nop 3
	ds_read_b128 v[10:13], v31 offset:2304
	s_waitcnt lgkmcnt(0)
	v_mfma_f32_16x16x32_bf16 v[10:13], v[6:9], v[10:13], 0
	v_mfma_f32_16x16x32_bf16 v[46:49], v[2:5], v[14:17], v[10:13]
	ds_read_b128 v[14:17], v31 offset:4672
	s_nop 5
	ds_read_b128 v[10:13], v31 offset:4608
	s_waitcnt lgkmcnt(0)
	v_mfma_f32_16x16x32_bf16 v[10:13], v[6:9], v[10:13], 0
	v_mfma_f32_16x16x32_bf16 v[50:53], v[2:5], v[14:17], v[10:13]
	ds_read_b128 v[14:17], v31 offset:6976
	s_nop 5
	ds_read_b128 v[10:13], v31 offset:6912
	s_waitcnt lgkmcnt(0)
	v_mfma_f32_16x16x32_bf16 v[10:13], v[6:9], v[10:13], 0
	v_mfma_f32_16x16x32_bf16 v[26:29], v[2:5], v[14:17], v[10:13]
	ds_read_b128 v[14:17], v31 offset:9280
	s_nop 5
	ds_read_b128 v[10:13], v31 offset:9216
	s_waitcnt lgkmcnt(0)
	v_mfma_f32_16x16x32_bf16 v[10:13], v[6:9], v[10:13], 0
	v_mfma_f32_16x16x32_bf16 v[22:25], v[2:5], v[14:17], v[10:13]
	ds_read_b128 v[14:17], v31 offset:11584
	s_nop 5
	ds_read_b128 v[10:13], v31 offset:11520
	s_waitcnt lgkmcnt(0)
	v_mfma_f32_16x16x32_bf16 v[10:13], v[6:9], v[10:13], 0
	v_mfma_f32_16x16x32_bf16 v[18:21], v[2:5], v[14:17], v[10:13]
	ds_read_b128 v[14:17], v31 offset:13888
	s_nop 5
	ds_read_b128 v[10:13], v31 offset:13824
	s_waitcnt lgkmcnt(0)
	v_mfma_f32_16x16x32_bf16 v[10:13], v[6:9], v[10:13], 0
	v_mfma_f32_16x16x32_bf16 v[14:17], v[2:5], v[14:17], v[10:13]
	s_nop 6
	ds_read_b128 v[10:13], v31 offset:16128
	s_waitcnt lgkmcnt(0)
	v_mfma_f32_16x16x32_bf16 v[10:13], v[6:9], v[10:13], 0
	v_mfma_f32_16x16x32_bf16 v[10:13], v[2:5], v[40:43], v[10:13]
	ds_read_b128 v[40:43], v31 offset:18432
	s_waitcnt lgkmcnt(0)
	v_mfma_f32_16x16x32_bf16 v[6:9], v[6:9], v[40:43], 0
	ds_read_b128 v[40:43], v31 offset:18496
	v_fma_f32 v31, v35, s36, -v85
	s_waitcnt lgkmcnt(0)
	v_mfma_f32_16x16x32_bf16 v[2:5], v[2:5], v[40:43], v[6:9]
	v_cndmask_b32_e64 v41, v251, v31, s[50:51]
	s_nop 2
	v_or_b32_e32 v7, v78, v56
	v_sub_u32_e32 v31, v7, v59
	v_fma_f32 v6, v32, s36, -v80
	v_cvt_f32_ubyte0_e32 v32, v31
	v_mul_f32_e32 v32, v75, v32
	v_fma_f32 v32, v46, s36, -v32
	v_sub_u32_e32 v40, v7, v64
	v_fma_f32 v8, v33, s36, -v81
	v_cndmask_b32_e32 v35, v32, v251, vcc
	v_add_u32_e32 v32, 1, v31
	v_add_u32_e32 v33, 1, v40
	v_cvt_f32_u32_e32 v32, v32
	v_cvt_f32_u32_e32 v33, v33
	v_cndmask_b32_e64 v44, v251, v8, s[46:47]
	v_max_f32_e32 v8, v77, v44
	v_mul_f32_e32 v32, v75, v32
	v_mul_f32_e32 v33, v75, v33
	v_fma_f32 v32, v47, s36, -v32
	v_fma_f32 v33, v51, s36, -v33
	v_cndmask_b32_e32 v39, v32, v251, vcc
	v_cndmask_b32_e32 v33, v33, v251, vcc
	v_max3_f32 v42, v8, v39, v33
	v_add_u32_e32 v8, 2, v40
	v_cvt_f32_u32_e32 v8, v8
	v_add_u32_e32 v32, 2, v31
	v_add_u32_e32 v31, 3, v31
	v_cvt_f32_u32_e32 v31, v31
	v_mul_f32_e32 v8, v75, v8
	v_fma_f32 v8, v52, s36, -v8
	v_cndmask_b32_e32 v36, v8, v251, vcc
	v_add_u32_e32 v8, 3, v40
	v_cvt_f32_u32_e32 v8, v8
	v_mul_f32_e32 v31, v75, v31
	v_fma_f32 v31, v49, s36, -v31
	v_fma_f32 v9, v34, s36, -v83
	v_mul_f32_e32 v8, v75, v8
	v_fma_f32 v8, v53, s36, -v8
	v_max_f32_e32 v34, v77, v41
	v_cndmask_b32_e32 v37, v31, v251, vcc
	v_cvt_f32_ubyte0_e32 v31, v40
	v_cndmask_b32_e32 v40, v8, v251, vcc
	v_sub_u32_e32 v8, v7, v62
	v_max3_f32 v46, v34, v37, v40
	v_cvt_f32_ubyte0_e32 v34, v8
	v_mul_f32_e32 v34, v75, v34
	v_fma_f32 v26, v26, s36, -v34
	v_cndmask_b32_e32 v34, v26, v251, vcc
	v_add_u32_e32 v26, 1, v8
	v_cvt_f32_u32_e32 v26, v26
	v_cvt_f32_u32_e32 v32, v32
	v_mul_f32_e32 v31, v75, v31
	v_cndmask_b32_e64 v45, v251, v6, s[44:45]
	v_mul_f32_e32 v26, v75, v26
	v_fma_f32 v26, v27, s36, -v26
	v_add_u32_e32 v27, 2, v8
	v_cvt_f32_u32_e32 v27, v27
	v_add_u32_e32 v8, 3, v8
	v_cvt_f32_u32_e32 v8, v8
	v_mul_f32_e32 v32, v75, v32
	v_mul_f32_e32 v27, v75, v27
	v_fma_f32 v27, v28, s36, -v27
	v_mul_f32_e32 v8, v75, v8
	v_sub_u32_e32 v28, v7, v65
	v_fma_f32 v8, v29, s36, -v8
	v_cvt_f32_i32_e32 v29, v28
	v_fma_f32 v32, v48, s36, -v32
	v_sub_u32_e32 v48, v7, v63
	v_cndmask_b32_e32 v26, v26, v251, vcc
	v_mul_f32_e32 v29, v75, v29
	v_fma_f32 v22, v22, s36, -v29
	v_add_u32_e32 v29, 1, v28
	v_cvt_f32_i32_e32 v29, v29
	v_fma_f32 v31, v50, s36, -v31
	v_max_f32_e32 v6, v77, v45
	v_cndmask_b32_e32 v31, v31, v251, vcc
	v_mul_f32_e32 v29, v75, v29
	v_fma_f32 v23, v23, s36, -v29
	v_add_u32_e32 v29, 2, v28
	v_add_u32_e32 v28, 3, v28
	v_cvt_f32_i32_e32 v28, v28
	v_cvt_f32_i32_e32 v29, v29
	v_cndmask_b32_e32 v23, v23, v251, vcc
	v_max3_f32 v47, v42, v26, v23
	v_mul_f32_e32 v28, v75, v28
	v_mul_f32_e32 v29, v75, v29
	v_fma_f32 v25, v25, s36, -v28
	v_fma_f32 v24, v24, s36, -v29
	v_cndmask_b32_e32 v29, v25, v251, vcc
	v_cvt_f32_i32_e32 v25, v48
	v_max3_f32 v6, v6, v35, v31
	v_cndmask_b32_e32 v22, v22, v251, vcc
	v_max3_f32 v6, v6, v34, v22
	v_mul_f32_e32 v25, v75, v25
	v_fma_f32 v42, v18, s36, -v25
	v_add_u32_e32 v18, 1, v48
	v_cvt_f32_i32_e32 v18, v18
	v_cndmask_b32_e64 v43, v251, v9, s[48:49]
	v_max_f32_e32 v9, v77, v43
	v_cndmask_b32_e32 v32, v32, v251, vcc
	v_mul_f32_e32 v18, v75, v18
	v_fma_f32 v25, v19, s36, -v18
	v_add_u32_e32 v18, 2, v48
	v_cvt_f32_i32_e32 v18, v18
	v_max3_f32 v9, v9, v32, v36
	v_cndmask_b32_e32 v27, v27, v251, vcc
	v_cndmask_b32_e32 v24, v24, v251, vcc
	v_mul_f32_e32 v18, v75, v18
	v_fma_f32 v28, v20, s36, -v18
	v_add_u32_e32 v18, 3, v48
	v_cvt_f32_i32_e32 v18, v18
	v_max3_f32 v9, v9, v27, v24
	v_cndmask_b32_e32 v8, v8, v251, vcc
	v_max3_f32 v46, v46, v8, v29
; __device__ __forceinline__ void swa_unit(LAS unsigned char* L, bf16_t* Z, const float* sinks, int b, int qb, int kvh) {
;     ...
;         for (int n = 0; n < 9; ++n)
; #pragma unroll
;             for (int j = 0; j < 4; ++j) { const int qi = kbase + quad * 4 + j, kk = kbase + 16 * n + l15; const int dist = qi + 128 - kk;
;                 const bool valid = ((n >= 1 && n <= 7) || ((dist >= 0) && (dist < 128))) && (kk >= kmin);
;                 const float lg = valid ? sc[n][j] * (0.125f * 1.4426950408889634f) - slope * (float)dist : -INFINITY; sc[n][j] = lg; mx[j] = fmaxf(mx[j], lg); }
; #pragma unroll
;         for (int j = 0; j < 4; ++j) { mx[j] = fmaxf(mx[j], __shfl_xor(mx[j], 1)); mx[j] = fmaxf(mx[j], __shfl_xor(mx[j], 2)); mx[j] = fmaxf(mx[j], __shfl_xor(mx[j], 4)); mx[j] = fmaxf(mx[j], __shfl_xor(mx[j], 8)); }
	v_mul_f32_e32 v18, v75, v18
	v_fma_f32 v18, v21, s36, -v18
	v_sub_u32_e32 v21, v7, v38
	v_cvt_f32_i32_e32 v19, v21
	v_mul_f32_e32 v19, v75, v19
	v_fma_f32 v20, v14, s36, -v19
	v_max3_f32 v38, v6, v42, v20
	v_add_u32_e32 v6, 1, v21
	v_cvt_f32_i32_e32 v6, v6
	v_mul_f32_e32 v6, v75, v6
	v_fma_f32 v15, v15, s36, -v6
	v_add_u32_e32 v6, 2, v21
	v_cvt_f32_i32_e32 v6, v6
	v_max3_f32 v47, v47, v25, v15
	v_mul_f32_e32 v6, v75, v6
	v_fma_f32 v19, v16, s36, -v6
	v_add_u32_e32 v6, 3, v21
	v_cvt_f32_i32_e32 v6, v6
	v_max3_f32 v48, v9, v28, v19
	v_mul_f32_e32 v6, v75, v6
	v_fma_f32 v14, v17, s36, -v6
	v_sub_u32_e32 v6, v7, v30
	v_cvt_f32_i32_e32 v9, v6
	v_max3_f32 v17, v46, v18, v14
	v_mul_f32_e32 v9, v75, v9
	v_fma_f32 v16, v10, s36, -v9
	v_add_u32_e32 v9, 1, v6
	v_cvt_f32_i32_e32 v9, v9
	v_add_u32_e32 v10, 2, v6
	v_cvt_f32_i32_e32 v10, v10
	v_add_u32_e32 v6, 3, v6
	v_mul_f32_e32 v9, v75, v9
	v_fma_f32 v9, v11, s36, -v9
	v_mul_f32_e32 v10, v75, v10
	v_or_b32_e32 v11, 0xb0, v76
	v_fma_f32 v10, v12, s36, -v10
	v_sub_u32_e32 v12, v7, v11
	v_cvt_f32_i32_e32 v7, v12
	v_cmp_gt_u32_e32 vcc, s20, v12
	v_add_u32_e32 v11, 1, v12
	v_cvt_f32_i32_e32 v6, v6
	v_mul_f32_e32 v7, v75, v7
	v_fma_f32 v2, v2, s36, -v7
	v_cndmask_b32_e32 v7, v251, v2, vcc
	v_cmp_gt_u32_e32 vcc, s20, v11
	v_cvt_f32_i32_e32 v11, v11
	v_max3_f32 v2, v38, v16, v7
	v_mul_f32_e32 v6, v75, v6
	v_fma_f32 v6, v13, s36, -v6
	v_mul_f32_e32 v11, v75, v11
	v_fma_f32 v3, v3, s36, -v11
	v_add_u32_e32 v11, 2, v12
	v_cndmask_b32_e32 v3, v251, v3, vcc
	v_cmp_gt_u32_e32 vcc, s20, v11
	v_cvt_f32_i32_e32 v11, v11
	v_max3_f32 v13, v47, v9, v3
	v_mul_f32_e32 v11, v75, v11
	v_fma_f32 v4, v4, s36, -v11
	v_cndmask_b32_e32 v11, v251, v4, vcc
	v_add_u32_e32 v4, 3, v12
	v_cmp_gt_u32_e32 vcc, s20, v4
	v_cvt_f32_i32_e32 v4, v4
	v_max3_f32 v21, v48, v10, v11
	v_mul_f32_e32 v4, v75, v4
	v_fma_f32 v4, v5, s36, -v4
	v_cndmask_b32_e32 v5, v251, v4, vcc
	s_nop 1
	v_mov_b32_dpp v4, v2 quad_perm:[1,0,3,2] row_mask:0xf bank_mask:0xf
	v_max3_f32 v17, v17, v6, v5
	s_waitcnt lgkmcnt(0)
	v_max_f32_e32 v4, v4, v4
	v_max_f32_e32 v2, v2, v4
	s_nop 1
	v_mov_b32_dpp v4, v2 quad_perm:[2,3,0,1] row_mask:0xf bank_mask:0xf
	s_waitcnt lgkmcnt(0)
	v_max_f32_e32 v4, v4, v4
	v_max_f32_e32 v2, v2, v4
	s_nop 1
	v_mov_b32_dpp v4, v2 row_half_mirror row_mask:0xf bank_mask:0xf
	s_waitcnt lgkmcnt(0)
	v_max_f32_e32 v4, v4, v4
	v_max_f32_e32 v2, v2, v4
	s_nop 1
	v_mov_b32_dpp v4, v2 row_mirror row_mask:0xf bank_mask:0xf
	s_waitcnt lgkmcnt(0)
	v_max_f32_e32 v4, v4, v4
	v_max_f32_e32 v2, v2, v4
	s_nop 1
	v_mov_b32_dpp v4, v13 quad_perm:[1,0,3,2] row_mask:0xf bank_mask:0xf
	s_waitcnt lgkmcnt(0)
	v_max_f32_e32 v4, v4, v4
	v_max_f32_e32 v4, v13, v4
	s_nop 1
	v_mov_b32_dpp v12, v4 quad_perm:[2,3,0,1] row_mask:0xf bank_mask:0xf
	s_waitcnt lgkmcnt(0)
	v_max_f32_e32 v12, v12, v12
	v_max_f32_e32 v4, v4, v12
	s_nop 1
	v_mov_b32_dpp v12, v4 row_half_mirror row_mask:0xf bank_mask:0xf
	s_waitcnt lgkmcnt(0)
	v_max_f32_e32 v12, v12, v12
	v_max_f32_e32 v4, v4, v12
	s_nop 1
	v_mov_b32_dpp v12, v4 row_mirror row_mask:0xf bank_mask:0xf
	s_waitcnt lgkmcnt(0)
	v_max_f32_e32 v12, v12, v12
	v_max_f32_e32 v4, v4, v12
	s_nop 1
	v_mov_b32_dpp v12, v21 quad_perm:[1,0,3,2] row_mask:0xf bank_mask:0xf
	v_sub_f32_e32 v3, v3, v4
	v_exp_f32_e32 v3, v3
	s_waitcnt lgkmcnt(0)
	v_max_f32_e32 v12, v12, v12
	v_max_f32_e32 v12, v21, v12
	s_nop 1
	v_mov_b32_dpp v13, v12 quad_perm:[2,3,0,1] row_mask:0xf bank_mask:0xf
	s_waitcnt lgkmcnt(0)
	v_max_f32_e32 v13, v13, v13
	v_max_f32_e32 v12, v12, v13
	s_nop 1
	v_mov_b32_dpp v13, v12 row_half_mirror row_mask:0xf bank_mask:0xf
	s_waitcnt lgkmcnt(0)
	v_max_f32_e32 v13, v13, v13
	v_max_f32_e32 v12, v12, v13
	s_nop 1
	v_mov_b32_dpp v13, v12 row_mirror row_mask:0xf bank_mask:0xf
	s_waitcnt lgkmcnt(0)
	v_max_f32_e32 v13, v13, v13
	v_max_f32_e32 v12, v12, v13
	s_nop 1
	v_mov_b32_dpp v13, v17 quad_perm:[1,0,3,2] row_mask:0xf bank_mask:0xf
	s_waitcnt lgkmcnt(0)
	v_max_f32_e32 v13, v13, v13
	v_max_f32_e32 v13, v17, v13
	s_nop 1
	v_mov_b32_dpp v17, v13 quad_perm:[2,3,0,1] row_mask:0xf bank_mask:0xf
	s_waitcnt lgkmcnt(0)
	v_max_f32_e32 v17, v17, v17
	v_max_f32_e32 v13, v13, v17
	s_nop 1
	v_mov_b32_dpp v17, v13 row_half_mirror row_mask:0xf bank_mask:0xf
	s_waitcnt lgkmcnt(0)
	v_max_f32_e32 v17, v17, v17
	v_max_f32_e32 v13, v13, v17
	s_nop 1
	v_mov_b32_dpp v17, v13 row_mirror row_mask:0xf bank_mask:0xf
	s_waitcnt lgkmcnt(0)
; __device__ __forceinline__ unsigned hwbf(float f) { return cvt_pk_bf16(f, 0.f) & 0xffffu; }
; __device__ __forceinline__ void swa_unit(LAS unsigned char* L, bf16_t* Z, const float* sinks, int b, int qb, int kvh) {
;     ...
;         float sum[4] = {0.f, 0.f, 0.f, 0.f};
; #pragma unroll
;         for (int n = 0; n < 9; ++n)
; #pragma unroll
;             for (int j = 0; j < 4; ++j) { const float p = __builtin_amdgcn_exp2f(sc[n][j] - mx[j]); sum[j] += p; Pw[(quad * 4 + j) * 168 + 16 * n + l15] = (bf16_t)hwbf(p); }
	v_max_f32_e32 v17, v17, v17
	v_max_f32_e32 v13, v13, v17
	v_sub_f32_e32 v17, v45, v2
	v_exp_f32_e32 v17, v17
	v_sub_f32_e32 v8, v8, v13
	v_exp_f32_e32 v8, v8
	v_sub_f32_e32 v6, v6, v13
	v_add_f32_e32 v21, 0, v17
	s_nop 1
	v_cvt_pk_bf16_f32 v17, v17, v1
	ds_write_b16 v57, v17
	v_sub_f32_e32 v17, v44, v4
	v_exp_f32_e32 v17, v17
	v_exp_f32_e32 v6, v6
	v_add_f32_e32 v30, 0, v17
	s_nop 1
	v_cvt_pk_bf16_f32 v17, v17, v1
	ds_write_b16 v57, v17 offset:336
	v_sub_f32_e32 v17, v43, v12
	v_exp_f32_e32 v17, v17
	s_nop 0
	v_add_f32_e32 v38, 0, v17
	s_nop 1
	v_cvt_pk_bf16_f32 v17, v17, v1
	ds_write_b16 v57, v17 offset:672
	v_sub_f32_e32 v17, v41, v13
	v_exp_f32_e32 v17, v17
	s_nop 0
	v_add_f32_e32 v41, 0, v17
	s_nop 1
	v_cvt_pk_bf16_f32 v17, v17, v1
	ds_write_b16 v57, v17 offset:1008
	v_sub_f32_e32 v17, v35, v2
	v_exp_f32_e32 v17, v17
	s_nop 0
	v_add_f32_e32 v21, v17, v21
	s_nop 1
	v_cvt_pk_bf16_f32 v17, v17, v1
	ds_write_b16 v57, v17 offset:32
	v_sub_f32_e32 v17, v39, v4
	v_exp_f32_e32 v17, v17
	s_nop 0
	v_add_f32_e32 v30, v17, v30
	s_nop 1
	v_cvt_pk_bf16_f32 v17, v17, v1
	ds_write_b16 v57, v17 offset:368
	v_sub_f32_e32 v17, v32, v12
	v_exp_f32_e32 v17, v17
	s_nop 0
	v_add_f32_e32 v32, v17, v38
	s_nop 1
	v_cvt_pk_bf16_f32 v17, v17, v1
	ds_write_b16 v57, v17 offset:704
	v_sub_f32_e32 v17, v37, v13
	v_exp_f32_e32 v17, v17
	s_nop 0
	v_add_f32_e32 v35, v17, v41
	s_nop 1
	v_cvt_pk_bf16_f32 v17, v17, v1
	ds_write_b16 v57, v17 offset:1040
	v_sub_f32_e32 v17, v31, v2
	v_exp_f32_e32 v17, v17
	s_nop 0
	v_add_f32_e32 v21, v17, v21
	s_nop 1
	v_cvt_pk_bf16_f32 v17, v17, v1
	ds_write_b16 v57, v17 offset:64
	v_sub_f32_e32 v17, v33, v4
	v_exp_f32_e32 v17, v17
	s_nop 0
	v_add_f32_e32 v30, v17, v30
	s_nop 1
	v_cvt_pk_bf16_f32 v17, v17, v1
	ds_write_b16 v57, v17 offset:400
	v_sub_f32_e32 v17, v36, v12
	v_exp_f32_e32 v17, v17
	s_nop 0
	v_add_f32_e32 v31, v17, v32
	s_nop 1
	v_cvt_pk_bf16_f32 v17, v17, v1
	ds_write_b16 v57, v17 offset:736
	v_sub_f32_e32 v17, v40, v13
	v_exp_f32_e32 v17, v17
	s_nop 0
	v_add_f32_e32 v32, v17, v35
	s_nop 1
	v_cvt_pk_bf16_f32 v17, v17, v1
	ds_write_b16 v57, v17 offset:1072
	v_sub_f32_e32 v17, v34, v2
	v_exp_f32_e32 v17, v17
	s_nop 0
	v_add_f32_e32 v21, v17, v21
	s_nop 1
	v_cvt_pk_bf16_f32 v17, v17, v1
	ds_write_b16 v57, v17 offset:96
	v_sub_f32_e32 v17, v26, v4
	v_exp_f32_e32 v17, v17
	s_nop 0
	v_add_f32_e32 v26, v17, v30
	s_nop 1
	v_cvt_pk_bf16_f32 v17, v17, v1
	ds_write_b16 v57, v17 offset:432
	v_sub_f32_e32 v17, v27, v12
	v_exp_f32_e32 v17, v17
	s_nop 0
	v_add_f32_e32 v27, v17, v31
	s_nop 1
	v_cvt_pk_bf16_f32 v17, v17, v1
	ds_write_b16 v57, v17 offset:768
	v_add_f32_e32 v17, v8, v32
	s_nop 1
	v_cvt_pk_bf16_f32 v8, v8, v1
	ds_write_b16 v57, v8 offset:1104
	v_sub_f32_e32 v8, v22, v2
	v_exp_f32_e32 v8, v8
	s_nop 0
	v_add_f32_e32 v21, v8, v21
	s_nop 1
	v_cvt_pk_bf16_f32 v8, v8, v1
	ds_write_b16 v57, v8 offset:128
	v_sub_f32_e32 v8, v23, v4
	v_exp_f32_e32 v8, v8
	s_nop 0
	v_add_f32_e32 v22, v8, v26
	s_nop 1
	v_cvt_pk_bf16_f32 v8, v8, v1
	ds_write_b16 v57, v8 offset:464
	v_sub_f32_e32 v8, v24, v12
	v_exp_f32_e32 v8, v8
	s_nop 0
	v_add_f32_e32 v23, v8, v27
	s_nop 1
	v_cvt_pk_bf16_f32 v8, v8, v1
	ds_write_b16 v57, v8 offset:800
	v_sub_f32_e32 v8, v29, v13
	v_exp_f32_e32 v8, v8
	s_nop 0
	v_add_f32_e32 v17, v8, v17
	s_nop 1
	v_cvt_pk_bf16_f32 v8, v8, v1
	ds_write_b16 v57, v8 offset:1136
	v_sub_f32_e32 v8, v42, v2
	v_exp_f32_e32 v8, v8
	s_nop 0
	v_add_f32_e32 v21, v8, v21
	s_nop 1
	v_cvt_pk_bf16_f32 v8, v8, v1
	ds_write_b16 v57, v8 offset:160
	v_sub_f32_e32 v8, v25, v4
	v_exp_f32_e32 v8, v8
	s_nop 0
	v_add_f32_e32 v22, v8, v22
	s_nop 1
	v_cvt_pk_bf16_f32 v8, v8, v1
	ds_write_b16 v57, v8 offset:496
	v_sub_f32_e32 v8, v28, v12
	v_exp_f32_e32 v8, v8
	s_nop 0
	v_add_f32_e32 v23, v8, v23
	s_nop 1
	v_cvt_pk_bf16_f32 v8, v8, v1
	ds_write_b16 v57, v8 offset:832
	v_sub_f32_e32 v8, v18, v13
	v_exp_f32_e32 v8, v8
	s_nop 0
	v_add_f32_e32 v17, v8, v17
	s_nop 1
	v_cvt_pk_bf16_f32 v8, v8, v1
	ds_write_b16 v57, v8 offset:1168
	v_sub_f32_e32 v8, v20, v2
	v_exp_f32_e32 v8, v8
	s_nop 0
	v_add_f32_e32 v18, v8, v21
	s_nop 1
	v_cvt_pk_bf16_f32 v8, v8, v1
	ds_write_b16 v57, v8 offset:192
	v_sub_f32_e32 v8, v15, v4
	v_exp_f32_e32 v8, v8
	s_nop 0
	v_add_f32_e32 v15, v8, v22
	s_nop 1
	v_cvt_pk_bf16_f32 v8, v8, v1
	ds_write_b16 v57, v8 offset:528
	v_sub_f32_e32 v8, v19, v12
	v_exp_f32_e32 v8, v8
	s_nop 0
	v_add_f32_e32 v19, v8, v23
	s_nop 1
	v_cvt_pk_bf16_f32 v8, v8, v1
	ds_write_b16 v57, v8 offset:864
	v_sub_f32_e32 v8, v14, v13
	v_exp_f32_e32 v8, v8
	s_nop 0
	v_add_f32_e32 v14, v8, v17
	s_nop 1
	v_cvt_pk_bf16_f32 v8, v8, v1
	ds_write_b16 v57, v8 offset:1200
	v_sub_f32_e32 v8, v16, v2
	v_exp_f32_e32 v8, v8
	s_nop 0
	v_add_f32_e32 v16, v8, v18
	s_nop 1
	v_cvt_pk_bf16_f32 v8, v8, v1
	ds_write_b16 v57, v8 offset:224
	v_sub_f32_e32 v8, v9, v4
	v_exp_f32_e32 v8, v8
	s_nop 0
	v_add_f32_e32 v9, v8, v15
	s_nop 1
	v_cvt_pk_bf16_f32 v8, v8, v1
	ds_write_b16 v57, v8 offset:560
	v_sub_f32_e32 v8, v10, v12
	v_exp_f32_e32 v8, v8
	s_nop 0
	v_add_f32_e32 v10, v8, v19
	s_nop 1
	v_cvt_pk_bf16_f32 v8, v8, v1
	ds_write_b16 v57, v8 offset:896
	v_add_f32_e32 v8, v6, v14
	s_nop 1
	v_cvt_pk_bf16_f32 v6, v6, v1
	ds_write_b16 v57, v6 offset:1232
	v_sub_f32_e32 v6, v7, v2
	v_exp_f32_e32 v6, v6
	v_fma_f32 v2, v70, s34, -v2
	v_exp_f32_e32 v2, v2
	v_add_f32_e32 v7, v6, v16
	s_nop 1
	v_cvt_pk_bf16_f32 v6, v6, v1
	ds_write_b16 v57, v6 offset:256
	v_add_f32_e32 v6, v3, v9
	s_nop 1
	v_cvt_pk_bf16_f32 v3, v3, v1
	ds_write_b16 v57, v3 offset:592
	v_sub_f32_e32 v3, v11, v12
	v_exp_f32_e32 v3, v3
	s_nop 0
	v_add_f32_e32 v9, v3, v10
	s_nop 1
	v_cvt_pk_bf16_f32 v3, v3, v1
	ds_write_b16 v57, v3 offset:928
	v_sub_f32_e32 v3, v5, v13
	v_exp_f32_e32 v3, v3
	s_nop 0
	v_add_f32_e32 v5, v3, v8
	s_nop 1
	v_cvt_pk_bf16_f32 v3, v3, v1
	ds_write_b16 v57, v3 offset:1264
	s_nop 1
	v_mov_b32_dpp v3, v7 quad_perm:[1,0,3,2] row_mask:0xf bank_mask:0xf
	s_waitcnt lgkmcnt(0)
; #define LAS __attribute__((address_space(3)))
; __device__ __forceinline__ f32x4 mfma16(bf16x8 a, bf16x8 b, f32x4 c) { return __builtin_amdgcn_mfma_f32_16x16x32_bf16(a, b, c, 0, 0, 0); }
; __device__ __forceinline__ void swa_unit(LAS unsigned char* L, bf16_t* Z, const float* sinks, int b, int qb, int kvh) {
;     ...
;         for (int j = 0; j < 4; ++j) { sum[j] += __shfl_xor(sum[j], 1); sum[j] += __shfl_xor(sum[j], 2); sum[j] += __shfl_xor(sum[j], 4); sum[j] += __shfl_xor(sum[j], 8);
;             rden[j] = __builtin_amdgcn_rcpf(sum[j] + __builtin_amdgcn_exp2f(sink - mx[j])); }
;         asm volatile("s_waitcnt lgkmcnt(0)" ::: "memory");
;         f32x4 o4[4];
; #pragma unroll
;         for (int nd = 0; nd < 4; ++nd) o4[nd] = (f32x4){0.f, 0.f, 0.f, 0.f};
; #pragma unroll
;         for (int ks = 0; ks < 5; ++ks) { const bf16x8 a = *(const LAS bf16x8*)(Pw + l15 * 168 + ks * 32 + quad * 8);
; #pragma unroll
;             for (int nd = 0; nd < 4; ++nd) o4[nd] = mfma16(a, *(const LAS bf16x8*)(Vt + (nd * 16 + l15) * 280 + kbase + ks * 32 + quad * 8), o4[nd]); }
	s_waitcnt lgkmcnt(0)
	v_add_f32_e32 v3, v7, v3
	s_nop 1
	v_mov_b32_dpp v7, v3 quad_perm:[2,3,0,1] row_mask:0xf bank_mask:0xf
	s_waitcnt lgkmcnt(0)
	v_add_f32_e32 v3, v3, v7
	s_nop 1
	v_mov_b32_dpp v7, v3 row_half_mirror row_mask:0xf bank_mask:0xf
	s_waitcnt lgkmcnt(0)
	v_add_f32_e32 v3, v3, v7
	s_nop 1
	v_mov_b32_dpp v7, v3 row_mirror row_mask:0xf bank_mask:0xf
	s_waitcnt lgkmcnt(0)
	v_add_f32_e32 v3, v3, v7
	v_add_f32_e32 v2, v2, v3
	v_rcp_f32_e32 v22, v2
	s_nop 1
	v_mov_b32_dpp v2, v6 quad_perm:[1,0,3,2] row_mask:0xf bank_mask:0xf
	s_waitcnt lgkmcnt(0)
	v_add_f32_e32 v2, v6, v2
	s_nop 1
	v_mov_b32_dpp v3, v2 quad_perm:[2,3,0,1] row_mask:0xf bank_mask:0xf
	s_waitcnt lgkmcnt(0)
	v_add_f32_e32 v2, v2, v3
	s_nop 1
	v_mov_b32_dpp v3, v2 row_half_mirror row_mask:0xf bank_mask:0xf
	s_waitcnt lgkmcnt(0)
	v_add_f32_e32 v2, v2, v3
	s_nop 1
	v_mov_b32_dpp v3, v2 row_mirror row_mask:0xf bank_mask:0xf
	s_waitcnt lgkmcnt(0)
	v_add_f32_e32 v2, v2, v3
	v_fma_f32 v3, v70, s34, -v4
	v_exp_f32_e32 v3, v3
	s_nop 0
	v_add_f32_e32 v2, v3, v2
	v_rcp_f32_e32 v23, v2
	s_nop 1
	v_mov_b32_dpp v2, v9 quad_perm:[1,0,3,2] row_mask:0xf bank_mask:0xf
	s_waitcnt lgkmcnt(0)
	v_add_f32_e32 v2, v9, v2
	s_nop 1
	v_mov_b32_dpp v3, v2 quad_perm:[2,3,0,1] row_mask:0xf bank_mask:0xf
	s_waitcnt lgkmcnt(0)
	v_add_f32_e32 v2, v2, v3
	s_nop 1
	v_mov_b32_dpp v3, v2 row_half_mirror row_mask:0xf bank_mask:0xf
	s_waitcnt lgkmcnt(0)
	v_add_f32_e32 v2, v2, v3
	s_nop 1
	v_mov_b32_dpp v3, v2 row_mirror row_mask:0xf bank_mask:0xf
	s_waitcnt lgkmcnt(0)
	v_add_f32_e32 v2, v2, v3
	v_fma_f32 v3, v70, s34, -v12
	v_exp_f32_e32 v3, v3
	s_nop 0
	v_add_f32_e32 v2, v3, v2
	v_rcp_f32_e32 v24, v2
	s_nop 1
	v_mov_b32_dpp v2, v5 quad_perm:[1,0,3,2] row_mask:0xf bank_mask:0xf
	s_waitcnt lgkmcnt(0)
	v_add_f32_e32 v2, v5, v2
	s_nop 1
	v_mov_b32_dpp v3, v2 quad_perm:[2,3,0,1] row_mask:0xf bank_mask:0xf
	s_waitcnt lgkmcnt(0)
	v_add_f32_e32 v2, v2, v3
	s_nop 1
	v_mov_b32_dpp v3, v2 row_half_mirror row_mask:0xf bank_mask:0xf
	s_waitcnt lgkmcnt(0)
	v_add_f32_e32 v2, v2, v3
	s_nop 1
	v_mov_b32_dpp v3, v2 row_mirror row_mask:0xf bank_mask:0xf
	s_waitcnt lgkmcnt(0)
	v_add_f32_e32 v2, v2, v3
	v_fma_f32 v3, v70, s34, -v13
	v_exp_f32_e32 v3, v3
	s_nop 0
	v_add_f32_e32 v2, v3, v2
	v_rcp_f32_e32 v25, v2
	ds_read_b128 v[2:5], v69
	ds_read_b128 v[6:9], v58 offset:36960
	ds_read_b128 v[10:13], v58 offset:45920
	ds_read_b128 v[14:17], v58 offset:54880
	ds_read_b128 v[18:21], v58 offset:63840
	s_waitcnt lgkmcnt(3)
	v_mfma_f32_16x16x32_bf16 v[6:9], v[2:5], v[6:9], 0
	s_waitcnt lgkmcnt(2)
	v_mfma_f32_16x16x32_bf16 v[10:13], v[2:5], v[10:13], 0
	s_waitcnt lgkmcnt(1)
	v_mfma_f32_16x16x32_bf16 v[14:17], v[2:5], v[14:17], 0
	s_waitcnt lgkmcnt(0)
	v_mfma_f32_16x16x32_bf16 v[2:5], v[2:5], v[18:21], 0
	ds_read_b128 v[18:21], v69 offset:64
	ds_read_b128 v[26:29], v58 offset:37024
	s_waitcnt lgkmcnt(0)
	v_mfma_f32_16x16x32_bf16 v[6:9], v[18:21], v[26:29], v[6:9]
	ds_read_b128 v[26:29], v58 offset:45984
	s_waitcnt lgkmcnt(0)
	v_mfma_f32_16x16x32_bf16 v[10:13], v[18:21], v[26:29], v[10:13]
	ds_read_b128 v[26:29], v58 offset:54944
	s_waitcnt lgkmcnt(0)
	v_mfma_f32_16x16x32_bf16 v[14:17], v[18:21], v[26:29], v[14:17]
	ds_read_b128 v[26:29], v58 offset:63904
	s_waitcnt lgkmcnt(0)
	v_mfma_f32_16x16x32_bf16 v[2:5], v[18:21], v[26:29], v[2:5]
	ds_read_b128 v[18:21], v69 offset:128
	ds_read_b128 v[26:29], v58 offset:37088
	s_waitcnt lgkmcnt(0)
	v_mfma_f32_16x16x32_bf16 v[6:9], v[18:21], v[26:29], v[6:9]
	ds_read_b128 v[26:29], v58 offset:46048
	s_waitcnt lgkmcnt(0)
	v_mfma_f32_16x16x32_bf16 v[10:13], v[18:21], v[26:29], v[10:13]
	ds_read_b128 v[26:29], v58 offset:55008
	s_waitcnt lgkmcnt(0)
	v_mfma_f32_16x16x32_bf16 v[14:17], v[18:21], v[26:29], v[14:17]
	ds_read_b128 v[26:29], v58 offset:63968
	s_waitcnt lgkmcnt(0)
	v_mfma_f32_16x16x32_bf16 v[2:5], v[18:21], v[26:29], v[2:5]
	ds_read_b128 v[18:21], v69 offset:192
	ds_read_b128 v[26:29], v58 offset:37152
	s_waitcnt lgkmcnt(0)
	v_mfma_f32_16x16x32_bf16 v[26:29], v[18:21], v[26:29], v[6:9]
	s_nop 2
	ds_read_b128 v[6:9], v58 offset:46112
	s_waitcnt lgkmcnt(0)
; #define LAS __attribute__((address_space(3)))
; __device__ __forceinline__ unsigned hwbf(float f) { return cvt_pk_bf16(f, 0.f) & 0xffffu; }
; __device__ __forceinline__ f32x4 mfma16(bf16x8 a, bf16x8 b, f32x4 c) { return __builtin_amdgcn_mfma_f32_16x16x32_bf16(a, b, c, 0, 0, 0); }
; __device__ __forceinline__ void swa_unit(LAS unsigned char* L, bf16_t* Z, const float* sinks, int b, int qb, int kvh) {
;     ...
;         for (int ks = 0; ks < 5; ++ks) { const bf16x8 a = *(const LAS bf16x8*)(Pw + l15 * 168 + ks * 32 + quad * 8);
; #pragma unroll
;             for (int nd = 0; nd < 4; ++nd) o4[nd] = mfma16(a, *(const LAS bf16x8*)(Vt + (nd * 16 + l15) * 280 + kbase + ks * 32 + quad * 8), o4[nd]); }
; #pragma unroll
;         for (int nd = 0; nd < 4; ++nd)
; #pragma unroll
;             for (int j = 0; j < 4; ++j) Z[(rowbase + t0 + kbase + quad * 4 + j) * ZLD + ZSQ + hq * 64 + nd * 16 + l15] = (bf16_t)hwbf(o4[nd][j] * rden[j]);
;         asm volatile("s_waitcnt lgkmcnt(0)" ::: "memory");
;     }
;     __syncthreads();
	v_mfma_f32_16x16x32_bf16 v[30:33], v[18:21], v[6:9], v[10:13]
	ds_read_b128 v[6:9], v58 offset:55072
	s_nop 1
	ds_read_b128 v[10:13], v58 offset:64032
	s_waitcnt lgkmcnt(1)
	v_mfma_f32_16x16x32_bf16 v[6:9], v[18:21], v[6:9], v[14:17]
	s_waitcnt lgkmcnt(0)
	v_mfma_f32_16x16x32_bf16 v[2:5], v[18:21], v[10:13], v[2:5]
	ds_read_b128 v[18:21], v69 offset:256
	ds_read_b128 v[10:13], v58 offset:37216
	ds_read_b128 v[14:17], v58 offset:46176
	s_waitcnt lgkmcnt(1)
	v_mfma_f32_16x16x32_bf16 v[10:13], v[18:21], v[10:13], v[26:29]
	s_nop 2
	ds_read_b128 v[26:29], v58 offset:55136
	s_waitcnt lgkmcnt(0)
	v_mfma_f32_16x16x32_bf16 v[6:9], v[18:21], v[26:29], v[6:9]
	ds_read_b128 v[26:29], v58 offset:64096
	s_nop 0
	v_mul_f32_e32 v10, v22, v10
	s_nop 1
	v_cvt_pk_bf16_f32 v10, v10, v1
	s_waitcnt lgkmcnt(0)
	v_mfma_f32_16x16x32_bf16 v[2:5], v[18:21], v[26:29], v[2:5]
	v_or3_b32 v28, v68, v56, s54
	v_mfma_f32_16x16x32_bf16 v[14:17], v[18:21], v[14:17], v[30:33]
	v_mad_u64_u32 v[18:19], s[0:1], v28, s74, v[54:55]
	v_mad_i32_i24 v19, s55, v250, v19
	v_lshl_add_u64 v[18:19], v[18:19], 0, v[66:67]
	v_lshl_add_u64 v[18:19], v[18:19], 0, v[0:1]
	v_lshl_add_u64 v[20:21], v[18:19], 0, s[16:17]
	v_add_co_u32_e32 v18, vcc, s78, v18
	s_nop 1
	v_addc_co_u32_e32 v19, vcc, 0, v19, vcc
	global_store_short v[18:19], v10, off offset:3072
	v_mul_f32_e32 v10, v23, v11
	s_nop 1
	v_cvt_pk_bf16_f32 v26, v10, v1
	v_or_b32_e32 v10, 1, v28
	v_mad_u64_u32 v[10:11], s[0:1], v10, s74, v[54:55]
	v_mad_i32_i24 v11, s55, v250, v11
	v_lshl_add_u64 v[10:11], v[10:11], 0, v[66:67]
	v_lshl_add_u64 v[10:11], v[10:11], 0, v[0:1]
	v_lshl_add_u64 v[18:19], v[10:11], 0, s[16:17]
	v_add_co_u32_e32 v10, vcc, s78, v10
	s_nop 1
	v_addc_co_u32_e32 v11, vcc, 0, v11, vcc
	global_store_short v[10:11], v26, off offset:3072
	v_mul_f32_e32 v10, v24, v12
	s_nop 1
	v_cvt_pk_bf16_f32 v12, v10, v1
	v_or_b32_e32 v10, 2, v28
	v_mad_u64_u32 v[10:11], s[0:1], v10, s74, v[54:55]
	v_mad_i32_i24 v11, s55, v250, v11
	v_lshl_add_u64 v[10:11], v[10:11], 0, v[66:67]
	v_lshl_add_u64 v[10:11], v[10:11], 0, v[0:1]
	v_lshl_add_u64 v[26:27], v[10:11], 0, s[16:17]
	v_add_co_u32_e32 v10, vcc, s78, v10
	s_nop 1
	v_addc_co_u32_e32 v11, vcc, 0, v11, vcc
	global_store_short v[10:11], v12, off offset:3072
	v_mul_f32_e32 v10, v25, v13
	s_nop 1
	v_cvt_pk_bf16_f32 v29, v10, v1
	v_or_b32_e32 v10, 3, v28
	v_mad_u64_u32 v[10:11], s[0:1], v10, s74, v[54:55]
	v_mad_i32_i24 v11, s55, v250, v11
	v_lshl_add_u64 v[10:11], v[10:11], 0, v[66:67]
	v_lshl_add_u64 v[10:11], v[10:11], 0, v[0:1]
	v_lshl_add_u64 v[12:13], v[10:11], 0, s[16:17]
	v_add_co_u32_e32 v10, vcc, s78, v10
	v_mul_f32_e32 v0, v22, v14
	s_nop 0
	v_addc_co_u32_e32 v11, vcc, 0, v11, vcc
	global_store_short v[10:11], v29, off offset:3072
	s_nop 1
	v_cvt_pk_bf16_f32 v0, v0, v1
	global_store_short v[20:21], v0, off offset:32
	v_mul_f32_e32 v0, v23, v15
	s_nop 1
	v_cvt_pk_bf16_f32 v0, v0, v1
	global_store_short v[18:19], v0, off offset:32
	v_mul_f32_e32 v0, v24, v16
	s_nop 1
	v_cvt_pk_bf16_f32 v0, v0, v1
	global_store_short v[26:27], v0, off offset:32
	v_mul_f32_e32 v0, v25, v17
	s_nop 1
	v_cvt_pk_bf16_f32 v0, v0, v1
	global_store_short v[12:13], v0, off offset:32
	v_mul_f32_e32 v0, v22, v6
	s_nop 1
	v_cvt_pk_bf16_f32 v0, v0, v1
	global_store_short v[20:21], v0, off offset:64
	v_mul_f32_e32 v0, v23, v7
	s_nop 1
	v_cvt_pk_bf16_f32 v0, v0, v1
	global_store_short v[18:19], v0, off offset:64
	v_mul_f32_e32 v0, v24, v8
	s_nop 1
	v_cvt_pk_bf16_f32 v0, v0, v1
	global_store_short v[26:27], v0, off offset:64
	v_mul_f32_e32 v0, v25, v9
	s_nop 1
	v_cvt_pk_bf16_f32 v0, v0, v1
	global_store_short v[12:13], v0, off offset:64
	v_mul_f32_e32 v0, v22, v2
	s_nop 1
	v_cvt_pk_bf16_f32 v0, v0, v1
	global_store_short v[20:21], v0, off offset:96
	v_mul_f32_e32 v0, v23, v3
	s_nop 1
	v_cvt_pk_bf16_f32 v0, v0, v1
	global_store_short v[18:19], v0, off offset:96
	v_mul_f32_e32 v0, v24, v4
	s_nop 1
	v_cvt_pk_bf16_f32 v0, v0, v1
	global_store_short v[26:27], v0, off offset:96
	v_mul_f32_e32 v0, v25, v5
	s_nop 1
	v_cvt_pk_bf16_f32 v0, v0, v1
	global_store_short v[12:13], v0, off offset:96
	s_waitcnt lgkmcnt(0)
	s_waitcnt vmcnt(63) expcnt(7) lgkmcnt(15)
	s_barrier
	s_cbranch_scc1 .LBB0_560

; #define LAS __attribute__((address_space(3)))
; __device__ __forceinline__ unsigned cvt_pk_bf16(float lo, float hi) { unsigned r; asm volatile("s_nop 1\n\tv_cvt_pk_bf16_f32 %0, %1, %2" : "=v"(r) : "v"(lo), "v"(hi)); return r; }
;     __device__ __forceinline__ void operator()(f32x4 (&acc)[2][2][4][2], const Unit& u, int wr, int wc, int fr, int fq) const {
;     ...
;                 for (int m = 0; m < 4; ++m) {
;                     f32x4 t1[2], t2[2];
;                     if (m > 0) {
; #pragma unroll
;                         for (int bj = 0; bj < 2; ++bj)
; #pragma unroll
;                             for (int e = 0; e < 4; ++e) { const float pv = acc[ai][bj][m - 1][n][e]; t1[bj][e] = DPPF(pv, 0x10F); t2[bj][e] = DPPF(pv, 0x10E); }
;                     } else {
;                         const bool has_pred = (wr == 1) || (ai == 1);
;                         const int pai = (wr == 1) ? ai : 0, pwr = (wr == 1) ? 0 : 1;
;                         const LAS float* p14 = X + ((((pai * 2 + pwr) * 4 + wc) * 2 + 0) * 4 + fq) * 16; const LAS float* p15 = p14 + 64;
; #pragma unroll
;                         for (int bj = 0; bj < 2; ++bj) { const f32x4 r14 = *(const LAS f32x4*)(p14 + bj * 8 + n * 4), r15 = *(const LAS f32x4*)(p15 + bj * 8 + n * 4);
; #pragma unroll
;                             for (int e = 0; e < 4; ++e) { t1[bj][e] = (has_pred && fr == 0) ? r15[e] : 0.f; t2[bj][e] = has_pred ? (fr == 0 ? r14[e] : (fr == 1 ? r15[e] : 0.f)) : 0.f; } }
;                     }
;                     float h[2][4];
; #pragma unroll
;                     for (int bj = 0; bj < 2; ++bj)
; #pragma unroll
;                         for (int e = 0; e < 4; ++e) { const float cur = acc[ai][bj][m][n][e];
;                             const float p1 = DPPF(cur, 0x111) + t1[bj][e], p2 = DPPF(cur, 0x112) + t2[bj][e];
;                             h[bj][e] = w[0][bj][e] * p2 + w[1][bj][e] * p1 + w[2][bj][e] * cur; }
;                     float r4[4];
; #pragma unroll
;                     for (int c = 0; c < 4; ++c) r4[c] = siluf_(h[0][c]) * h[1][c];
;                     const bool skip = (ai == 0) && (m == 0) && (wr == 0) && (fr < 2);
;                     if (!skip) { u32x2 o; o.x = cvt_pk_bf16(r4[0], r4[1]); o.y = cvt_pk_bf16(r4[2], r4[3]);
;                         *(u32x2*)(ACT + (size_t)(u.pm * BM + ai * HALF + wr * 64 + m * 16 + fr) * DFF + chb + 4 * n) = o; }
.LBB0_1107:
	s_xor_b64 s[60:61], s[10:11], -1
	s_and_b64 s[50:51], s[42:43], s[62:63]
	v_lshl_or_b32 v0, s55, 6, v0
	v_mov_b32_dpp v230, v130 row_shr:1 row_mask:0xf bank_mask:0xf bound_ctrl:1
	v_mov_b32_dpp v232, v130 row_shr:2 row_mask:0xf bank_mask:0xf bound_ctrl:1
	v_mov_b32_dpp v234, v131 row_shr:1 row_mask:0xf bank_mask:0xf bound_ctrl:1
	v_mov_b32_dpp v236, v131 row_shr:2 row_mask:0xf bank_mask:0xf bound_ctrl:1
	v_mov_b32_dpp v238, v132 row_shr:1 row_mask:0xf bank_mask:0xf bound_ctrl:1
	v_mov_b32_dpp v240, v132 row_shr:2 row_mask:0xf bank_mask:0xf bound_ctrl:1
	v_mov_b32_dpp v242, v133 row_shr:1 row_mask:0xf bank_mask:0xf bound_ctrl:1
	v_mov_b32_dpp v244, v133 row_shr:2 row_mask:0xf bank_mask:0xf bound_ctrl:1
	v_mov_b32_dpp v231, v122 row_shr:1 row_mask:0xf bank_mask:0xf bound_ctrl:1
	v_mov_b32_dpp v233, v122 row_shr:2 row_mask:0xf bank_mask:0xf bound_ctrl:1
	v_mov_b32_dpp v235, v123 row_shr:1 row_mask:0xf bank_mask:0xf bound_ctrl:1
	v_mov_b32_dpp v237, v123 row_shr:2 row_mask:0xf bank_mask:0xf bound_ctrl:1
	v_mov_b32_dpp v239, v124 row_shr:1 row_mask:0xf bank_mask:0xf bound_ctrl:1
	v_mov_b32_dpp v241, v124 row_shr:2 row_mask:0xf bank_mask:0xf bound_ctrl:1
	v_mov_b32_dpp v243, v125 row_shr:1 row_mask:0xf bank_mask:0xf bound_ctrl:1
	v_mov_b32_dpp v245, v125 row_shr:2 row_mask:0xf bank_mask:0xf bound_ctrl:1
	s_waitcnt vmcnt(0)
	v_mov_b32_e32 v210, v142
	v_mov_b32_e32 v211, v154
	v_mov_b32_e32 v212, v138
	v_mov_b32_e32 v213, v146
	v_mov_b32_e32 v214, v134
	v_mov_b32_e32 v215, v150
	v_mov_b32_e32 v204, v143
	v_mov_b32_e32 v205, v155
	v_mov_b32_e32 v208, v139
	v_mov_b32_e32 v209, v147
	v_mov_b32_e32 v206, v135
	v_mov_b32_e32 v207, v151
	v_mov_b32_e32 v216, v144
	v_mov_b32_e32 v217, v156
	v_mov_b32_e32 v218, v140
	v_mov_b32_e32 v219, v148
	v_mov_b32_e32 v220, v136
	v_mov_b32_e32 v221, v152
	s_waitcnt lgkmcnt(1)
	v_mov_b32_e32 v162, v145
	v_mov_b32_e32 v163, v157
	v_mov_b32_e32 v202, v141
	v_mov_b32_e32 v203, v149
	v_mov_b32_e32 v164, v137
	v_mov_b32_e32 v165, v153
	s_and_saveexec_b64 s[10:11], s[60:61]
	s_xor_b64 s[10:11], exec, s[10:11]
	s_cbranch_execz .LBB0_1109
	s_waitcnt lgkmcnt(0)
	v_cndmask_b32_e64 v161, 0, v161, s[50:51]
	v_cndmask_b32_e64 v173, 0, v160, s[50:51]
	v_cndmask_b32_e64 v160, 0, v129, s[50:51]
	v_cndmask_b32_e64 v172, 0, v128, s[50:51]
	v_pk_add_f32 v[128:129], v[228:229], v[244:245]
	v_mov_b32_e32 v164, v137
	v_mov_b32_e32 v165, v153
	v_pk_mul_f32 v[128:129], v[164:165], v[128:129]
	v_pk_add_f32 v[160:161], v[160:161], v[242:243]
	v_mov_b32_e32 v202, v141
	v_mov_b32_e32 v203, v149
	v_cndmask_b32_e64 v211, 0, v158, s[50:51]
	v_cndmask_b32_e64 v158, 0, v127, s[50:51]
	v_cndmask_b32_e64 v210, 0, v126, s[50:51]
	v_mov_b32_e32 v162, v145
	v_mov_b32_e32 v163, v157
	v_mov_b32_e32 v126, v133
	v_mov_b32_e32 v127, v125
	v_pk_fma_f32 v[128:129], v[202:203], v[160:161], v[128:129]
	v_mov_b32_e32 v137, v152
	v_pk_fma_f32 v[126:127], v[162:163], v[126:127], v[128:129]
	v_pk_add_f32 v[152:153], v[172:173], v[238:239]
	v_mul_f32_e32 v128, 0xbfb8aa3b, v126
	v_exp_f32_e32 v128, v128
	v_mov_b32_e32 v141, v148
	v_mov_b32_e32 v145, v156
	v_cndmask_b32_e64 v159, 0, v159, s[50:51]
	v_add_f32_e32 v128, 1.0, v128
	v_rcp_f32_e32 v128, v128
	v_mov_b32_e32 v206, v135
	v_mov_b32_e32 v207, v151
	v_pk_add_f32 v[148:149], v[158:159], v[234:235]
	v_mul_f32_e32 v126, v126, v128
	v_pk_add_f32 v[128:129], v[226:227], v[240:241]
	v_mul_f32_e32 v157, v126, v127
	v_pk_mul_f32 v[128:129], v[136:137], v[128:129]
	v_mov_b32_e32 v126, v132
	v_mov_b32_e32 v127, v124
	v_pk_fma_f32 v[128:129], v[140:141], v[152:153], v[128:129]
	v_mov_b32_e32 v208, v139
	v_pk_fma_f32 v[126:127], v[144:145], v[126:127], v[128:129]
	v_mov_b32_e32 v209, v147
	v_mul_f32_e32 v128, 0xbfb8aa3b, v126
	v_exp_f32_e32 v128, v128
	v_mov_b32_e32 v204, v143
	v_mov_b32_e32 v205, v155
	v_mov_b32_e32 v135, v150
	v_add_f32_e32 v128, 1.0, v128
	v_rcp_f32_e32 v128, v128
	v_mov_b32_e32 v139, v146
	v_mov_b32_e32 v143, v154
	s_lshl_b32 s9, s8, 8
	v_mul_f32_e32 v126, v126, v128
	v_pk_add_f32 v[128:129], v[224:225], v[236:237]
	v_mul_f32_e32 v152, v126, v127
	v_pk_mul_f32 v[128:129], v[206:207], v[128:129]
	v_mov_b32_e32 v126, v131
	v_mov_b32_e32 v127, v123
	v_pk_fma_f32 v[128:129], v[208:209], v[148:149], v[128:129]
	v_pk_add_f32 v[148:149], v[210:211], v[230:231]
	v_pk_fma_f32 v[126:127], v[204:205], v[126:127], v[128:129]
	v_add_u32_e32 v146, s9, v0
	v_mul_f32_e32 v128, 0xbfb8aa3b, v126
	v_exp_f32_e32 v128, v128
	s_movk_i32 s55, 0x1600
	v_mov_b64_e32 v[220:221], v[136:137]
	v_mov_b64_e32 v[218:219], v[140:141]
	v_add_f32_e32 v128, 1.0, v128
	v_rcp_f32_e32 v128, v128
	v_mov_b64_e32 v[216:217], v[144:145]
	v_mov_b64_e32 v[214:215], v[134:135]
	v_mov_b64_e32 v[212:213], v[138:139]
	v_mul_f32_e32 v126, v126, v128
	v_pk_add_f32 v[128:129], v[222:223], v[232:233]
	v_mul_f32_e32 v147, v126, v127
	v_pk_mul_f32 v[128:129], v[134:135], v[128:129]
	v_mov_b32_e32 v126, v130
	v_mov_b32_e32 v127, v122
	v_pk_fma_f32 v[128:129], v[138:139], v[148:149], v[128:129]
	v_mov_b64_e32 v[210:211], v[142:143]
	v_pk_fma_f32 v[126:127], v[142:143], v[126:127], v[128:129]
	s_nop 0
	v_mul_f32_e32 v128, 0xbfb8aa3b, v126
	v_exp_f32_e32 v128, v128
	s_nop 0
	v_add_f32_e32 v128, 1.0, v128
	v_rcp_f32_e32 v128, v128
	s_nop 0
	v_mul_f32_e32 v126, v126, v128
	v_mov_b64_e32 v[128:129], s[68:69]
	v_mad_i64_i32 v[128:129], vcc, v146, s55, v[128:129]
	v_mul_f32_e32 v126, v126, v127
	v_lshl_add_u64 v[128:129], v[188:189], 1, v[128:129]
	s_nop 1
	v_cvt_pk_bf16_f32 v126, v126, v147
	s_nop 1
	v_cvt_pk_bf16_f32 v127, v152, v157
	s_nop 0
	v_mov_b32_e32 v222, v126
	v_mov_b32_e32 v223, v127
; #define LAS __attribute__((address_space(3)))
; __device__ __forceinline__ float siluf_(float x) { return x * __builtin_amdgcn_rcpf(1.0f + __expf(-x)); }
; #define DPPF(v, ctrl) __builtin_bit_cast(float, __builtin_amdgcn_update_dpp(0, __builtin_bit_cast(int, (v)), (ctrl), 0xf, 0xf, true))
;     __device__ __forceinline__ void operator()(f32x4 (&acc)[2][2][4][2], const Unit& u, int wr, int wc, int fr, int fq) const {
;     ...
;                 for (int m = 0; m < 4; ++m) { const float rs = RS[ai * HALF + wr * 64 + m * 16 + fr];
; #pragma unroll
;                     for (int bj = 0; bj < 2; ++bj)
; #pragma unroll
;                         for (int n = 0; n < 2; ++n) acc[ai][bj][m][n] = acc[ai][bj][m][n] * rs; }
;     ...
;                     if (m > 0) {
; #pragma unroll
;                         for (int bj = 0; bj < 2; ++bj)
; #pragma unroll
;                             for (int e = 0; e < 4; ++e) { const float pv = acc[ai][bj][m - 1][n][e]; t1[bj][e] = DPPF(pv, 0x10F); t2[bj][e] = DPPF(pv, 0x10E); }
;                     } else {
;                         const bool has_pred = (wr == 1) || (ai == 1);
;                         const int pai = (wr == 1) ? ai : 0, pwr = (wr == 1) ? 0 : 1;
;                         const LAS float* p14 = X + ((((pai * 2 + pwr) * 4 + wc) * 2 + 0) * 4 + fq) * 16; const LAS float* p15 = p14 + 64;
; #pragma unroll
;                         for (int bj = 0; bj < 2; ++bj) { const f32x4 r14 = *(const LAS f32x4*)(p14 + bj * 8 + n * 4), r15 = *(const LAS f32x4*)(p15 + bj * 8 + n * 4);
; #pragma unroll
;                             for (int e = 0; e < 4; ++e) { t1[bj][e] = (has_pred && fr == 0) ? r15[e] : 0.f; t2[bj][e] = has_pred ? (fr == 0 ? r14[e] : (fr == 1 ? r15[e] : 0.f)) : 0.f; } }
;                     }
;                     float h[2][4];
; #pragma unroll
;                     for (int bj = 0; bj < 2; ++bj)
; #pragma unroll
;                         for (int e = 0; e < 4; ++e) { const float cur = acc[ai][bj][m][n][e];
;                             const float p1 = DPPF(cur, 0x111) + t1[bj][e], p2 = DPPF(cur, 0x112) + t2[bj][e];
;                             h[bj][e] = w[0][bj][e] * p2 + w[1][bj][e] * p1 + w[2][bj][e] * cur; }
;                     float r4[4];
; #pragma unroll
;                     for (int c = 0; c < 4; ++c) r4[c] = siluf_(h[0][c]) * h[1][c];
.LBB0_1109:
	s_or_saveexec_b64 s[10:11], s[10:11]
	v_mov_b32_e32 v126, s9
	s_xor_b64 exec, exec, s[10:11]
	s_lshl_b32 s8, s8, 8
	v_mov_b32_e32 v126, s8
	s_or_b64 exec, exec, s[10:11]
	v_mov_b32_e32 v128, v195
	v_pk_mul_f32 v[134:135], v[112:113], v[128:129] op_sel_hi:[1,0]
	v_pk_mul_f32 v[136:137], v[110:111], v[128:129] op_sel_hi:[1,0]
	v_pk_mul_f32 v[104:105], v[104:105], v[128:129] op_sel_hi:[1,0]
	v_pk_mul_f32 v[128:129], v[102:103], v[128:129] op_sel_hi:[1,0]
	v_mov_b32_e32 v102, v197
	v_pk_mul_f32 v[112:113], v[106:107], v[192:193] op_sel_hi:[1,0]
	v_pk_mul_f32 v[106:107], v[100:101], v[192:193] op_sel_hi:[1,0]
	v_pk_mul_f32 v[100:101], v[94:95], v[196:197] op_sel_hi:[1,0]
	v_pk_mul_f32 v[94:95], v[80:81], v[196:197] op_sel_hi:[1,0]
	v_pk_mul_f32 v[80:81], v[88:89], v[102:103] op_sel_hi:[1,0]
	v_pk_mul_f32 v[88:89], v[86:87], v[102:103] op_sel_hi:[1,0]
	v_pk_mul_f32 v[86:87], v[70:71], v[102:103] op_sel_hi:[1,0]
	v_pk_mul_f32 v[70:71], v[76:77], v[190:191] op_sel_hi:[1,0]
	v_mov_b32_dpp v76, v130 row_shl:14 row_mask:0xf bank_mask:0xf bound_ctrl:1
	v_mov_b32_dpp v140, v133 row_shl:15 row_mask:0xf bank_mask:0xf bound_ctrl:1
	v_mov_b32_dpp v142, v133 row_shl:14 row_mask:0xf bank_mask:0xf bound_ctrl:1
	v_mov_b32_dpp v77, v122 row_shl:14 row_mask:0xf bank_mask:0xf bound_ctrl:1
	v_mov_b32_dpp v139, v124 row_shl:15 row_mask:0xf bank_mask:0xf bound_ctrl:1
	v_mov_b32_dpp v133, v124 row_shl:14 row_mask:0xf bank_mask:0xf bound_ctrl:1
	v_mov_b32_dpp v141, v125 row_shl:15 row_mask:0xf bank_mask:0xf bound_ctrl:1
	v_mov_b32_dpp v143, v125 row_shl:14 row_mask:0xf bank_mask:0xf bound_ctrl:1
	v_mov_b32_dpp v124, v136 row_shr:2 row_mask:0xf bank_mask:0xf bound_ctrl:1
	v_mov_b32_dpp v125, v128 row_shr:2 row_mask:0xf bank_mask:0xf bound_ctrl:1
	v_pk_mul_f32 v[110:111], v[98:99], v[192:193] op_sel_hi:[1,0]
	v_pk_mul_f32 v[98:99], v[78:79], v[196:197] op_sel_hi:[1,0]
	v_pk_mul_f32 v[78:79], v[72:73], v[102:103] op_sel_hi:[1,0]
	v_pk_mul_f32 v[72:73], v[74:75], v[190:191] op_sel_hi:[1,0]
	v_mov_b32_dpp v74, v130 row_shl:15 row_mask:0xf bank_mask:0xf bound_ctrl:1
	v_mov_b32_dpp v102, v131 row_shl:15 row_mask:0xf bank_mask:0xf bound_ctrl:1
	v_mov_b32_dpp v130, v131 row_shl:14 row_mask:0xf bank_mask:0xf bound_ctrl:1
	v_mov_b32_dpp v138, v132 row_shl:15 row_mask:0xf bank_mask:0xf bound_ctrl:1
	v_mov_b32_dpp v132, v132 row_shl:14 row_mask:0xf bank_mask:0xf bound_ctrl:1
	v_mov_b32_dpp v75, v122 row_shl:15 row_mask:0xf bank_mask:0xf bound_ctrl:1
	v_mov_b32_dpp v103, v123 row_shl:15 row_mask:0xf bank_mask:0xf bound_ctrl:1
	v_mov_b32_dpp v131, v123 row_shl:14 row_mask:0xf bank_mask:0xf bound_ctrl:1
	v_mov_b32_dpp v122, v136 row_shr:1 row_mask:0xf bank_mask:0xf bound_ctrl:1
	v_mov_b32_dpp v146, v137 row_shr:2 row_mask:0xf bank_mask:0xf bound_ctrl:1
	v_mov_b32_dpp v150, v134 row_shr:2 row_mask:0xf bank_mask:0xf bound_ctrl:1
	v_mov_b32_dpp v123, v128 row_shr:1 row_mask:0xf bank_mask:0xf bound_ctrl:1
	v_mov_b32_dpp v151, v104 row_shr:2 row_mask:0xf bank_mask:0xf bound_ctrl:1
	v_mov_b32_dpp v147, v129 row_shr:2 row_mask:0xf bank_mask:0xf bound_ctrl:1
	v_pk_add_f32 v[76:77], v[76:77], v[124:125]
	v_mov_b32_dpp v144, v137 row_shr:1 row_mask:0xf bank_mask:0xf bound_ctrl:1
	v_mov_b32_dpp v148, v134 row_shr:1 row_mask:0xf bank_mask:0xf bound_ctrl:1
	v_mov_b32_dpp v154, v135 row_shr:2 row_mask:0xf bank_mask:0xf bound_ctrl:1
	v_mov_b32_dpp v155, v105 row_shr:2 row_mask:0xf bank_mask:0xf bound_ctrl:1
	v_mov_b32_dpp v145, v129 row_shr:1 row_mask:0xf bank_mask:0xf bound_ctrl:1
	v_mov_b32_dpp v149, v104 row_shr:1 row_mask:0xf bank_mask:0xf bound_ctrl:1
	v_pk_add_f32 v[132:133], v[132:133], v[150:151]
	v_pk_add_f32 v[130:131], v[130:131], v[146:147]
	v_pk_mul_f32 v[76:77], v[214:215], v[76:77]
	v_pk_add_f32 v[74:75], v[74:75], v[122:123]
	v_mov_b32_dpp v152, v135 row_shr:1 row_mask:0xf bank_mask:0xf bound_ctrl:1
	v_mov_b32_dpp v153, v105 row_shr:1 row_mask:0xf bank_mask:0xf bound_ctrl:1
	v_pk_add_f32 v[142:143], v[142:143], v[154:155]
	v_pk_mul_f32 v[132:133], v[220:221], v[132:133]
	v_pk_add_f32 v[138:139], v[138:139], v[148:149]
	v_pk_mul_f32 v[130:131], v[206:207], v[130:131]
	v_pk_add_f32 v[102:103], v[102:103], v[144:145]
	v_pk_fma_f32 v[74:75], v[212:213], v[74:75], v[76:77]
	v_mov_b32_e32 v76, v136
	v_mov_b32_e32 v77, v128
	v_pk_mul_f32 v[142:143], v[164:165], v[142:143]
	v_pk_add_f32 v[140:141], v[140:141], v[152:153]
	v_pk_fma_f32 v[132:133], v[218:219], v[138:139], v[132:133]
	v_mov_b32_e32 v138, v134
	v_mov_b32_e32 v139, v104
	v_pk_fma_f32 v[102:103], v[208:209], v[102:103], v[130:131]
	v_mov_b32_e32 v130, v137
	v_mov_b32_e32 v131, v129
	v_pk_fma_f32 v[74:75], v[210:211], v[76:77], v[74:75]
	v_pk_fma_f32 v[140:141], v[202:203], v[140:141], v[142:143]
	v_mov_b32_e32 v142, v135
	v_mov_b32_e32 v143, v105
	v_pk_fma_f32 v[132:133], v[216:217], v[138:139], v[132:133]
	v_pk_fma_f32 v[102:103], v[204:205], v[130:131], v[102:103]
	v_mul_f32_e32 v76, 0xbfb8aa3b, v74
	v_pk_fma_f32 v[140:141], v[162:163], v[142:143], v[140:141]
	v_mul_f32_e32 v138, 0xbfb8aa3b, v132
	v_mul_f32_e32 v130, 0xbfb8aa3b, v102
	v_exp_f32_e32 v76, v76
	v_mul_f32_e32 v127, 0xbfb8aa3b, v140
	v_exp_f32_e32 v138, v138
	v_exp_f32_e32 v130, v130
	v_exp_f32_e32 v127, v127
	v_add_f32_e32 v76, 1.0, v76
	v_add_f32_e32 v138, 1.0, v138
	v_add_f32_e32 v122, 1.0, v130
	v_rcp_f32_e32 v76, v76
	v_add_f32_e32 v127, 1.0, v127
	v_rcp_f32_e32 v138, v138
	v_rcp_f32_e32 v122, v122
	v_rcp_f32_e32 v127, v127
	v_mul_f32_e32 v74, v74, v76
	v_mul_f32_e32 v77, v132, v138
	v_mul_f32_e32 v102, v102, v122
	v_mul_f32_e32 v74, v74, v75
	s_waitcnt lgkmcnt(0)
; __device__ __forceinline__ unsigned cvt_pk_bf16(float lo, float hi) { unsigned r; asm volatile("s_nop 1\n\tv_cvt_pk_bf16_f32 %0, %1, %2" : "=v"(r) : "v"(lo), "v"(hi)); return r; }
; __device__ __forceinline__ float siluf_(float x) { return x * __builtin_amdgcn_rcpf(1.0f + __expf(-x)); }
; #define DPPF(v, ctrl) __builtin_bit_cast(float, __builtin_amdgcn_update_dpp(0, __builtin_bit_cast(int, (v)), (ctrl), 0xf, 0xf, true))
;     __device__ __forceinline__ void operator()(f32x4 (&acc)[2][2][4][2], const Unit& u, int wr, int wc, int fr, int fq) const {
;     ...
;                         for (int e = 0; e < 4; ++e) { const float cur = acc[ai][bj][m][n][e];
;                             const float p1 = DPPF(cur, 0x111) + t1[bj][e], p2 = DPPF(cur, 0x112) + t2[bj][e];
;                             h[bj][e] = w[0][bj][e] * p2 + w[1][bj][e] * p1 + w[2][bj][e] * cur; }
;                     float r4[4];
; #pragma unroll
;                     for (int c = 0; c < 4; ++c) r4[c] = siluf_(h[0][c]) * h[1][c];
;                     const bool skip = (ai == 0) && (m == 0) && (wr == 0) && (fr < 2);
;                     if (!skip) { u32x2 o; o.x = cvt_pk_bf16(r4[0], r4[1]); o.y = cvt_pk_bf16(r4[2], r4[3]);
;                         *(u32x2*)(ACT + (size_t)(u.pm * BM + ai * HALF + wr * 64 + m * 16 + fr) * DFF + chb + 4 * n) = o; }
	v_add_u32_e32 v160, v0, v126
	v_mul_f32_e32 v127, v140, v127
	v_mul_f32_e32 v77, v77, v133
	v_mul_f32_e32 v102, v102, v103
	s_nop 1
	v_cvt_pk_bf16_f32 v122, v74, v102
	v_add_u32_e32 v0, 16, v160
	v_mov_b64_e32 v[74:75], s[68:69]
	s_movk_i32 s55, 0x1600
	v_mul_f32_e32 v127, v127, v141
	s_nop 1
	v_cvt_pk_bf16_f32 v123, v77, v127
	v_mad_i64_i32 v[102:103], s[10:11], v0, s55, v[74:75]
	v_lshlrev_b64 v[76:77], 1, v[188:189]
	v_pk_mul_f32 v[108:109], v[108:109], v[192:193] op_sel_hi:[1,0]
	v_lshl_add_u64 v[102:103], v[102:103], 0, v[76:77]
	s_nop 0
	v_mov_b32_e32 v232, v122
	v_mov_b32_e32 v233, v123
	v_mov_b32_dpp v122, v136 row_shl:15 row_mask:0xf bank_mask:0xf bound_ctrl:1
	v_mov_b32_dpp v124, v136 row_shl:14 row_mask:0xf bank_mask:0xf bound_ctrl:1
	v_mov_b32_dpp v132, v134 row_shl:15 row_mask:0xf bank_mask:0xf bound_ctrl:1
	v_mov_b32_dpp v134, v134 row_shl:14 row_mask:0xf bank_mask:0xf bound_ctrl:1
	v_mov_b32_dpp v136, v135 row_shl:15 row_mask:0xf bank_mask:0xf bound_ctrl:1
	v_mov_b32_dpp v138, v135 row_shl:14 row_mask:0xf bank_mask:0xf bound_ctrl:1
	v_mov_b32_dpp v135, v104 row_shl:14 row_mask:0xf bank_mask:0xf bound_ctrl:1
	v_mov_b32_dpp v146, v108 row_shr:2 row_mask:0xf bank_mask:0xf bound_ctrl:1
	v_mov_b32_dpp v147, v106 row_shr:2 row_mask:0xf bank_mask:0xf bound_ctrl:1
	v_mov_b32_dpp v133, v104 row_shl:15 row_mask:0xf bank_mask:0xf bound_ctrl:1
	v_mov_b32_dpp v144, v108 row_shr:1 row_mask:0xf bank_mask:0xf bound_ctrl:1
	v_mov_b32_dpp v145, v106 row_shr:1 row_mask:0xf bank_mask:0xf bound_ctrl:1
	v_pk_add_f32 v[134:135], v[134:135], v[146:147]
	v_pk_add_f32 v[132:133], v[132:133], v[144:145]
	v_pk_mul_f32 v[134:135], v[220:221], v[134:135]
	v_mov_b32_dpp v130, v137 row_shl:14 row_mask:0xf bank_mask:0xf bound_ctrl:1
	v_pk_fma_f32 v[132:133], v[218:219], v[132:133], v[134:135]
	v_mov_b32_e32 v134, v108
	v_mov_b32_e32 v135, v106
	v_pk_fma_f32 v[132:133], v[216:217], v[134:135], v[132:133]
	v_mov_b32_dpp v131, v129 row_shl:14 row_mask:0xf bank_mask:0xf bound_ctrl:1
	v_mul_f32_e32 v134, 0xbfb8aa3b, v132
	v_mov_b32_dpp v142, v113 row_shr:2 row_mask:0xf bank_mask:0xf bound_ctrl:1
	v_exp_f32_e32 v134, v134
	v_mov_b32_dpp v143, v111 row_shr:2 row_mask:0xf bank_mask:0xf bound_ctrl:1
	v_mov_b32_dpp v126, v137 row_shl:15 row_mask:0xf bank_mask:0xf bound_ctrl:1
	v_mov_b32_dpp v127, v129 row_shl:15 row_mask:0xf bank_mask:0xf bound_ctrl:1
	v_mov_b32_dpp v140, v113 row_shr:1 row_mask:0xf bank_mask:0xf bound_ctrl:1
	v_mov_b32_dpp v141, v111 row_shr:1 row_mask:0xf bank_mask:0xf bound_ctrl:1
	v_pk_add_f32 v[130:131], v[130:131], v[142:143]
	v_pk_add_f32 v[126:127], v[126:127], v[140:141]
	v_pk_mul_f32 v[130:131], v[206:207], v[130:131]
	v_mov_b32_dpp v139, v105 row_shl:14 row_mask:0xf bank_mask:0xf bound_ctrl:1
	v_mov_b32_dpp v150, v109 row_shr:2 row_mask:0xf bank_mask:0xf bound_ctrl:1
	v_mov_b32_dpp v151, v107 row_shr:2 row_mask:0xf bank_mask:0xf bound_ctrl:1
	v_pk_fma_f32 v[126:127], v[208:209], v[126:127], v[130:131]
	v_mov_b32_e32 v130, v113
	v_mov_b32_e32 v131, v111
	v_mov_b32_dpp v123, v128 row_shl:15 row_mask:0xf bank_mask:0xf bound_ctrl:1
	v_mov_b32_dpp v125, v128 row_shl:14 row_mask:0xf bank_mask:0xf bound_ctrl:1
	v_mov_b32_dpp v137, v105 row_shl:15 row_mask:0xf bank_mask:0xf bound_ctrl:1
	v_mov_b32_dpp v128, v112 row_shr:2 row_mask:0xf bank_mask:0xf bound_ctrl:1
	v_mov_b32_dpp v148, v109 row_shr:1 row_mask:0xf bank_mask:0xf bound_ctrl:1
	v_mov_b32_dpp v129, v110 row_shr:2 row_mask:0xf bank_mask:0xf bound_ctrl:1
	v_mov_b32_dpp v149, v107 row_shr:1 row_mask:0xf bank_mask:0xf bound_ctrl:1
	v_pk_add_f32 v[138:139], v[138:139], v[150:151]
	v_add_f32_e32 v134, 1.0, v134
	v_pk_fma_f32 v[126:127], v[204:205], v[130:131], v[126:127]
	v_mov_b32_dpp v104, v112 row_shr:1 row_mask:0xf bank_mask:0xf bound_ctrl:1
	v_mov_b32_dpp v105, v110 row_shr:1 row_mask:0xf bank_mask:0xf bound_ctrl:1
	v_pk_mul_f32 v[138:139], v[164:165], v[138:139]
	v_pk_add_f32 v[136:137], v[136:137], v[148:149]
	v_rcp_f32_e32 v134, v134
	v_mul_f32_e32 v130, 0xbfb8aa3b, v126
	v_pk_add_f32 v[124:125], v[124:125], v[128:129]
	v_pk_fma_f32 v[136:137], v[202:203], v[136:137], v[138:139]
	v_mov_b32_e32 v138, v109
	v_mov_b32_e32 v139, v107
	v_exp_f32_e32 v130, v130
	v_pk_mul_f32 v[124:125], v[214:215], v[124:125]
	v_pk_add_f32 v[104:105], v[122:123], v[104:105]
	v_pk_fma_f32 v[136:137], v[162:163], v[138:139], v[136:137]
	v_pk_fma_f32 v[104:105], v[212:213], v[104:105], v[124:125]
	v_mov_b32_e32 v122, v112
	v_mov_b32_e32 v123, v110
	v_mul_f32_e32 v0, 0xbfb8aa3b, v136
	v_pk_fma_f32 v[104:105], v[210:211], v[122:123], v[104:105]
	v_exp_f32_e32 v0, v0
	v_mul_f32_e32 v122, 0xbfb8aa3b, v104
	v_mul_f32_e32 v123, v132, v134
	v_exp_f32_e32 v122, v122
	v_add_f32_e32 v124, 1.0, v130
	v_mul_f32_e32 v123, v123, v133
	v_mov_b32_dpp v128, v108 row_shl:15 row_mask:0xf bank_mask:0xf bound_ctrl:1
	v_mov_b32_dpp v108, v108 row_shl:14 row_mask:0xf bank_mask:0xf bound_ctrl:1
	v_mov_b32_dpp v130, v109 row_shl:15 row_mask:0xf bank_mask:0xf bound_ctrl:1
	v_mov_b32_dpp v132, v109 row_shl:14 row_mask:0xf bank_mask:0xf bound_ctrl:1
	v_mov_b32_dpp v109, v106 row_shl:14 row_mask:0xf bank_mask:0xf bound_ctrl:1
	v_mov_b32_dpp v133, v107 row_shl:14 row_mask:0xf bank_mask:0xf bound_ctrl:1
	v_mov_b32_dpp v140, v116 row_shr:2 row_mask:0xf bank_mask:0xf bound_ctrl:1
	v_mov_b32_dpp v144, v117 row_shr:2 row_mask:0xf bank_mask:0xf bound_ctrl:1
	v_mov_b32_dpp v145, v121 row_shr:2 row_mask:0xf bank_mask:0xf bound_ctrl:1
	v_mov_b32_dpp v141, v120 row_shr:2 row_mask:0xf bank_mask:0xf bound_ctrl:1
	v_mov_b32_dpp v129, v106 row_shl:15 row_mask:0xf bank_mask:0xf bound_ctrl:1
	v_mov_b32_dpp v131, v107 row_shl:15 row_mask:0xf bank_mask:0xf bound_ctrl:1
; #define LAS __attribute__((address_space(3)))
; __device__ __forceinline__ unsigned cvt_pk_bf16(float lo, float hi) { unsigned r; asm volatile("s_nop 1\n\tv_cvt_pk_bf16_f32 %0, %1, %2" : "=v"(r) : "v"(lo), "v"(hi)); return r; }
;     __device__ __forceinline__ void operator()(f32x4 (&acc)[2][2][4][2], const Unit& u, int wr, int wc, int fr, int fq) const {
;     ...
;                 for (int m = 0; m < 4; ++m) {
;                     f32x4 t1[2], t2[2];
;                     if (m > 0) {
; #pragma unroll
;                         for (int bj = 0; bj < 2; ++bj)
; #pragma unroll
;                             for (int e = 0; e < 4; ++e) { const float pv = acc[ai][bj][m - 1][n][e]; t1[bj][e] = DPPF(pv, 0x10F); t2[bj][e] = DPPF(pv, 0x10E); }
;                     } else {
;                         const bool has_pred = (wr == 1) || (ai == 1);
;                         const int pai = (wr == 1) ? ai : 0, pwr = (wr == 1) ? 0 : 1;
;                         const LAS float* p14 = X + ((((pai * 2 + pwr) * 4 + wc) * 2 + 0) * 4 + fq) * 16; const LAS float* p15 = p14 + 64;
; #pragma unroll
;                         for (int bj = 0; bj < 2; ++bj) { const f32x4 r14 = *(const LAS f32x4*)(p14 + bj * 8 + n * 4), r15 = *(const LAS f32x4*)(p15 + bj * 8 + n * 4);
; #pragma unroll
;                             for (int e = 0; e < 4; ++e) { t1[bj][e] = (has_pred && fr == 0) ? r15[e] : 0.f; t2[bj][e] = has_pred ? (fr == 0 ? r14[e] : (fr == 1 ? r15[e] : 0.f)) : 0.f; } }
;                     }
;                     float h[2][4];
; #pragma unroll
;                     for (int bj = 0; bj < 2; ++bj)
; #pragma unroll
;                         for (int e = 0; e < 4; ++e) { const float cur = acc[ai][bj][m][n][e];
;                             const float p1 = DPPF(cur, 0x111) + t1[bj][e], p2 = DPPF(cur, 0x112) + t2[bj][e];
;                             h[bj][e] = w[0][bj][e] * p2 + w[1][bj][e] * p1 + w[2][bj][e] * cur; }
;                     float r4[4];
; #pragma unroll
;                     for (int c = 0; c < 4; ++c) r4[c] = siluf_(h[0][c]) * h[1][c];
;                     const bool skip = (ai == 0) && (m == 0) && (wr == 0) && (fr < 2);
;                     if (!skip) { u32x2 o; o.x = cvt_pk_bf16(r4[0], r4[1]); o.y = cvt_pk_bf16(r4[2], r4[3]);
;                         *(u32x2*)(ACT + (size_t)(u.pm * BM + ai * HALF + wr * 64 + m * 16 + fr) * DFF + chb + 4 * n) = o; }
	v_mov_b32_dpp v138, v116 row_shr:1 row_mask:0xf bank_mask:0xf bound_ctrl:1
	v_mov_b32_dpp v142, v117 row_shr:1 row_mask:0xf bank_mask:0xf bound_ctrl:1
	v_mov_b32_dpp v143, v121 row_shr:1 row_mask:0xf bank_mask:0xf bound_ctrl:1
	v_pk_add_f32 v[132:133], v[132:133], v[144:145]
	v_mov_b32_dpp v139, v120 row_shr:1 row_mask:0xf bank_mask:0xf bound_ctrl:1
	v_pk_add_f32 v[108:109], v[108:109], v[140:141]
	v_pk_mul_f32 v[132:133], v[164:165], v[132:133]
	v_pk_add_f32 v[130:131], v[130:131], v[142:143]
	v_pk_mul_f32 v[108:109], v[220:221], v[108:109]
	v_pk_add_f32 v[128:129], v[128:129], v[138:139]
	v_add_f32_e32 v0, 1.0, v0
	v_pk_fma_f32 v[130:131], v[202:203], v[130:131], v[132:133]
	v_mov_b32_e32 v132, v117
	v_pk_fma_f32 v[108:109], v[218:219], v[128:129], v[108:109]
	v_mov_b32_e32 v117, v120
	v_rcp_f32_e32 v0, v0
	v_add_f32_e32 v122, 1.0, v122
	v_pk_fma_f32 v[108:109], v[216:217], v[116:117], v[108:109]
	v_rcp_f32_e32 v124, v124
	v_rcp_f32_e32 v122, v122
	v_mul_f32_e32 v116, 0xbfb8aa3b, v108
	v_exp_f32_e32 v116, v116
	v_mul_f32_e32 v0, v136, v0
	v_mul_f32_e32 v0, v0, v137
	v_mul_f32_e32 v124, v126, v124
	v_mul_f32_e32 v104, v104, v122
	v_mul_f32_e32 v124, v124, v127
	v_mul_f32_e32 v104, v104, v105
	s_nop 1
	v_cvt_pk_bf16_f32 v122, v104, v124
	s_nop 1
	v_cvt_pk_bf16_f32 v123, v123, v0
	v_add_u32_e32 v0, 32, v160
	v_mov_b32_dpp v126, v113 row_shl:14 row_mask:0xf bank_mask:0xf bound_ctrl:1
	v_mov_b32_dpp v127, v111 row_shl:14 row_mask:0xf bank_mask:0xf bound_ctrl:1
	v_mov_b32_dpp v136, v115 row_shr:2 row_mask:0xf bank_mask:0xf bound_ctrl:1
	v_mov_b32_dpp v137, v119 row_shr:2 row_mask:0xf bank_mask:0xf bound_ctrl:1
	v_add_f32_e32 v116, 1.0, v116
	v_mad_i64_i32 v[104:105], s[10:11], v0, s55, v[74:75]
	v_mov_b32_dpp v124, v113 row_shl:15 row_mask:0xf bank_mask:0xf bound_ctrl:1
	v_mov_b32_dpp v125, v111 row_shl:15 row_mask:0xf bank_mask:0xf bound_ctrl:1
	v_mov_b32_dpp v134, v115 row_shr:1 row_mask:0xf bank_mask:0xf bound_ctrl:1
	v_mov_b32_dpp v135, v119 row_shr:1 row_mask:0xf bank_mask:0xf bound_ctrl:1
	v_rcp_f32_e32 v128, v116
	v_pk_add_f32 v[116:117], v[126:127], v[136:137]
	v_lshl_add_u64 v[104:105], v[104:105], 0, v[76:77]
	v_mov_b32_e32 v133, v121
	v_pk_mul_f32 v[116:117], v[206:207], v[116:117]
	v_pk_add_f32 v[120:121], v[124:125], v[134:135]
	s_nop 0
	v_mov_b32_e32 v236, v122
	v_mov_b32_e32 v237, v123
	v_mov_b32_dpp v122, v112 row_shl:15 row_mask:0xf bank_mask:0xf bound_ctrl:1
	v_mov_b32_dpp v112, v112 row_shl:14 row_mask:0xf bank_mask:0xf bound_ctrl:1
	v_mov_b32_dpp v123, v110 row_shl:15 row_mask:0xf bank_mask:0xf bound_ctrl:1
	v_mov_b32_dpp v113, v110 row_shl:14 row_mask:0xf bank_mask:0xf bound_ctrl:1
	v_mov_b32_dpp v110, v114 row_shr:2 row_mask:0xf bank_mask:0xf bound_ctrl:1
	v_mov_b32_dpp v111, v118 row_shr:2 row_mask:0xf bank_mask:0xf bound_ctrl:1
	v_pk_fma_f32 v[116:117], v[208:209], v[120:121], v[116:117]
	v_mov_b32_e32 v120, v115
	v_mov_b32_e32 v121, v119
	v_mov_b32_dpp v106, v114 row_shr:1 row_mask:0xf bank_mask:0xf bound_ctrl:1
	v_mov_b32_dpp v107, v118 row_shr:1 row_mask:0xf bank_mask:0xf bound_ctrl:1
	v_pk_fma_f32 v[116:117], v[204:205], v[120:121], v[116:117]
	v_pk_add_f32 v[110:111], v[112:113], v[110:111]
	v_mul_f32_e32 v115, 0xbfb8aa3b, v116
	v_pk_mul_f32 v[110:111], v[214:215], v[110:111]
	v_pk_add_f32 v[106:107], v[122:123], v[106:107]
	v_pk_fma_f32 v[130:131], v[162:163], v[132:133], v[130:131]
	v_exp_f32_e32 v119, v115
	v_pk_fma_f32 v[106:107], v[212:213], v[106:107], v[110:111]
	v_mov_b32_e32 v115, v118
	v_mul_f32_e32 v0, 0xbfb8aa3b, v130
	v_pk_fma_f32 v[106:107], v[210:211], v[114:115], v[106:107]
	v_exp_f32_e32 v0, v0
	v_mul_f32_e32 v110, 0xbfb8aa3b, v106
	v_exp_f32_e32 v110, v110
	v_add_f32_e32 v111, 1.0, v119
	v_add_f32_e32 v0, 1.0, v0
	v_rcp_f32_e32 v0, v0
	v_rcp_f32_e32 v111, v111
	v_add_f32_e32 v110, 1.0, v110
	v_rcp_f32_e32 v110, v110
	v_mul_f32_e32 v108, v108, v128
	v_mul_f32_e32 v0, v130, v0
	v_mul_f32_e32 v109, v108, v109
	v_mul_f32_e32 v108, v116, v111
	v_mul_f32_e32 v0, v0, v131
	v_mul_f32_e32 v108, v108, v117
	v_mul_f32_e32 v106, v106, v110
	s_xor_b64 s[8:9], s[62:63], -1
	v_mul_f32_e32 v106, v106, v107
	s_nop 1
	v_cvt_pk_bf16_f32 v108, v106, v108
	s_nop 1
	v_cvt_pk_bf16_f32 v109, v109, v0
	v_add_u32_e32 v0, 48, v160
	v_cndmask_b32_e64 v156, 0, 1, s[8:9]
	v_mad_i64_i32 v[106:107], s[10:11], v0, s55, v[74:75]
	s_and_b64 s[10:11], s[62:63], exec
	s_cselect_b32 s10, 2, 0
	v_readfirstlane_b32 s11, v156
	s_or_b32 s10, s10, s11
	s_lshl_b32 s10, s10, 11
	s_add_i32 s10, s10, 0
	s_add_i32 s10, s10, s53
	v_lshl_add_u64 v[106:107], v[106:107], 0, v[76:77]
	s_add_i32 s10, s10, 0x20000
	s_nop 0
	v_mov_b32_e32 v240, v108
	v_mov_b32_e32 v241, v109
	v_add_u32_e32 v0, s10, v191
	ds_read_b128 v[108:111], v0
	ds_read_b128 v[112:115], v0 offset:32
	ds_read_b128 v[116:119], v0 offset:256
	ds_read_b128 v[120:123], v0 offset:288
	v_pk_mul_f32 v[96:97], v[96:97], v[196:197] op_sel_hi:[1,0]
	v_mov_b32_dpp v139, v95 row_shr:2 row_mask:0xf bank_mask:0xf bound_ctrl:1
	v_mov_b32_dpp v137, v95 row_shr:1 row_mask:0xf bank_mask:0xf bound_ctrl:1
	s_waitcnt lgkmcnt(1)
	v_cndmask_b32_e64 v140, 0, v119, s[42:43]
	s_waitcnt lgkmcnt(0)
; #define LAS __attribute__((address_space(3)))
; __device__ __forceinline__ unsigned cvt_pk_bf16(float lo, float hi) { unsigned r; asm volatile("s_nop 1\n\tv_cvt_pk_bf16_f32 %0, %1, %2" : "=v"(r) : "v"(lo), "v"(hi)); return r; }
; __device__ __forceinline__ float siluf_(float x) { return x * __builtin_amdgcn_rcpf(1.0f + __expf(-x)); }
; #define DPPF(v, ctrl) __builtin_bit_cast(float, __builtin_amdgcn_update_dpp(0, __builtin_bit_cast(int, (v)), (ctrl), 0xf, 0xf, true))
;     __device__ __forceinline__ void operator()(f32x4 (&acc)[2][2][4][2], const Unit& u, int wr, int wc, int fr, int fq) const {
;     ...
;                         const bool has_pred = (wr == 1) || (ai == 1);
;                         const int pai = (wr == 1) ? ai : 0, pwr = (wr == 1) ? 0 : 1;
;                         const LAS float* p14 = X + ((((pai * 2 + pwr) * 4 + wc) * 2 + 0) * 4 + fq) * 16; const LAS float* p15 = p14 + 64;
; #pragma unroll
;                         for (int bj = 0; bj < 2; ++bj) { const f32x4 r14 = *(const LAS f32x4*)(p14 + bj * 8 + n * 4), r15 = *(const LAS f32x4*)(p15 + bj * 8 + n * 4);
; #pragma unroll
;                             for (int e = 0; e < 4; ++e) { t1[bj][e] = (has_pred && fr == 0) ? r15[e] : 0.f; t2[bj][e] = has_pred ? (fr == 0 ? r14[e] : (fr == 1 ? r15[e] : 0.f)) : 0.f; } }
;                     }
;                     float h[2][4];
; #pragma unroll
;                     for (int bj = 0; bj < 2; ++bj)
; #pragma unroll
;                         for (int e = 0; e < 4; ++e) { const float cur = acc[ai][bj][m][n][e];
;                             const float p1 = DPPF(cur, 0x111) + t1[bj][e], p2 = DPPF(cur, 0x112) + t2[bj][e];
;                             h[bj][e] = w[0][bj][e] * p2 + w[1][bj][e] * p1 + w[2][bj][e] * cur; }
;                     float r4[4];
; #pragma unroll
;                     for (int c = 0; c < 4; ++c) r4[c] = siluf_(h[0][c]) * h[1][c];
;                     const bool skip = (ai == 0) && (m == 0) && (wr == 0) && (fr < 2);
;                     if (!skip) { u32x2 o; o.x = cvt_pk_bf16(r4[0], r4[1]); o.y = cvt_pk_bf16(r4[2], r4[3]);
;                         *(u32x2*)(ACT + (size_t)(u.pm * BM + ai * HALF + wr * 64 + m * 16 + fr) * DFF + chb + 4 * n) = o; }
	v_cndmask_b32_e64 v141, 0, v123, s[42:43]
	v_cndmask_b32_e64 v119, 0, v119, s[44:45]
	v_cndmask_b32_e64 v123, 0, v123, s[44:45]
	v_mov_b32_dpp v138, v97 row_shr:2 row_mask:0xf bank_mask:0xf bound_ctrl:1
	v_cndmask_b32_e64 v143, v123, v115, s[42:43]
	v_cndmask_b32_e64 v142, v119, v111, s[42:43]
	v_mov_b32_dpp v136, v97 row_shr:1 row_mask:0xf bank_mask:0xf bound_ctrl:1
	v_pk_add_f32 v[138:139], v[142:143], v[138:139]
	v_pk_add_f32 v[136:137], v[140:141], v[136:137]
	v_pk_mul_f32 v[138:139], v[164:165], v[138:139]
	v_cndmask_b32_e64 v115, 0, v118, s[44:45]
	v_pk_fma_f32 v[136:137], v[202:203], v[136:137], v[138:139]
	v_mov_b32_e32 v138, v97
	v_mov_b32_e32 v139, v95
	v_pk_fma_f32 v[136:137], v[162:163], v[138:139], v[136:137]
	v_mov_b32_dpp v134, v96 row_shr:2 row_mask:0xf bank_mask:0xf bound_ctrl:1
	v_mul_f32_e32 v111, 0xbfb8aa3b, v136
	v_exp_f32_e32 v111, v111
	v_mov_b32_dpp v135, v94 row_shr:2 row_mask:0xf bank_mask:0xf bound_ctrl:1
	v_cndmask_b32_e64 v110, v115, v110, s[42:43]
	v_mov_b32_dpp v132, v96 row_shr:1 row_mask:0xf bank_mask:0xf bound_ctrl:1
	v_add_f32_e32 v111, 1.0, v111
	v_rcp_f32_e32 v119, v111
	v_cndmask_b32_e64 v111, 0, v122, s[44:45]
	v_cndmask_b32_e64 v111, v111, v114, s[42:43]
	v_mov_b32_dpp v133, v94 row_shr:1 row_mask:0xf bank_mask:0xf bound_ctrl:1
	v_cndmask_b32_e64 v139, 0, v122, s[42:43]
	v_cndmask_b32_e64 v138, 0, v118, s[42:43]
	v_pk_add_f32 v[110:111], v[110:111], v[134:135]
	v_pk_add_f32 v[114:115], v[138:139], v[132:133]
	v_pk_mul_f32 v[110:111], v[220:221], v[110:111]
	v_cndmask_b32_e64 v118, 0, v121, s[44:45]
	v_pk_fma_f32 v[110:111], v[218:219], v[114:115], v[110:111]
	v_mov_b32_e32 v114, v96
	v_mov_b32_e32 v115, v94
	v_pk_fma_f32 v[110:111], v[216:217], v[114:115], v[110:111]
	v_mov_b32_dpp v130, v101 row_shr:2 row_mask:0xf bank_mask:0xf bound_ctrl:1
	v_mul_f32_e32 v114, 0xbfb8aa3b, v110
	v_exp_f32_e32 v114, v114
	v_mov_b32_dpp v131, v99 row_shr:2 row_mask:0xf bank_mask:0xf bound_ctrl:1
	v_mul_f32_e32 v115, v136, v119
	v_cndmask_b32_e64 v119, v118, v113, s[42:43]
	v_add_f32_e32 v114, 1.0, v114
	v_rcp_f32_e32 v123, v114
	v_cndmask_b32_e64 v114, 0, v117, s[42:43]
	v_cndmask_b32_e64 v117, 0, v117, s[44:45]
	v_cndmask_b32_e64 v118, v117, v109, s[42:43]
	v_mov_b32_dpp v128, v101 row_shr:1 row_mask:0xf bank_mask:0xf bound_ctrl:1
	v_mov_b32_dpp v129, v99 row_shr:1 row_mask:0xf bank_mask:0xf bound_ctrl:1
	v_mul_f32_e32 v122, v115, v137
	v_cndmask_b32_e64 v115, 0, v121, s[42:43]
	v_pk_add_f32 v[118:119], v[118:119], v[130:131]
	v_pk_add_f32 v[114:115], v[114:115], v[128:129]
	v_pk_mul_f32 v[118:119], v[206:207], v[118:119]
	v_cndmask_b32_e64 v113, 0, v116, s[44:45]
	v_pk_fma_f32 v[114:115], v[208:209], v[114:115], v[118:119]
	v_mov_b32_e32 v118, v101
	v_mov_b32_e32 v119, v99
	v_pk_fma_f32 v[114:115], v[204:205], v[118:119], v[114:115]
	v_mov_b32_dpp v126, v100 row_shr:2 row_mask:0xf bank_mask:0xf bound_ctrl:1
	v_mul_f32_e32 v109, 0xbfb8aa3b, v114
	v_exp_f32_e32 v117, v109
	v_cndmask_b32_e64 v109, 0, v120, s[44:45]
	v_mov_b32_dpp v127, v98 row_shr:2 row_mask:0xf bank_mask:0xf bound_ctrl:1
	v_cndmask_b32_e64 v109, v109, v112, s[42:43]
	v_cndmask_b32_e64 v108, v113, v108, s[42:43]
	v_mov_b32_dpp v124, v100 row_shr:1 row_mask:0xf bank_mask:0xf bound_ctrl:1
	v_mov_b32_dpp v125, v98 row_shr:1 row_mask:0xf bank_mask:0xf bound_ctrl:1
	v_cndmask_b32_e64 v119, 0, v120, s[42:43]
	v_cndmask_b32_e64 v118, 0, v116, s[42:43]
	v_pk_add_f32 v[108:109], v[108:109], v[126:127]
	v_pk_add_f32 v[112:113], v[118:119], v[124:125]
	v_pk_mul_f32 v[108:109], v[214:215], v[108:109]
	v_mul_f32_e32 v110, v110, v123
	v_pk_fma_f32 v[108:109], v[212:213], v[112:113], v[108:109]
	v_mov_b32_e32 v112, v100
	v_mov_b32_e32 v113, v98
	v_pk_fma_f32 v[108:109], v[210:211], v[112:113], v[108:109]
	v_add_f32_e32 v113, 1.0, v117
	v_mul_f32_e32 v112, 0xbfb8aa3b, v108
	v_exp_f32_e32 v112, v112
	v_rcp_f32_e32 v113, v113
	v_mul_f32_e32 v111, v110, v111
	v_mov_b32_dpp v116, v96 row_shl:15 row_mask:0xf bank_mask:0xf bound_ctrl:1
	v_add_f32_e32 v112, 1.0, v112
	v_rcp_f32_e32 v112, v112
	v_mul_f32_e32 v110, v114, v113
	v_mul_f32_e32 v110, v110, v115
	v_mov_b32_dpp v114, v101 row_shl:14 row_mask:0xf bank_mask:0xf bound_ctrl:1
	v_mul_f32_e32 v108, v108, v112
	v_mul_f32_e32 v108, v108, v109
	s_nop 1
	v_cvt_pk_bf16_f32 v110, v108, v110
	v_add_u32_e32 v108, 0x80, v160
	v_mad_i64_i32 v[108:109], s[10:11], v108, s55, v[74:75]
	s_nop 1
	v_cvt_pk_bf16_f32 v111, v111, v122
	v_lshl_add_u64 v[108:109], v[108:109], 0, v[76:77]
	s_nop 0
	v_mov_b32_e32 v244, v110
	v_mov_b32_e32 v245, v111
	v_mov_b32_dpp v110, v100 row_shl:15 row_mask:0xf bank_mask:0xf bound_ctrl:1
	v_mov_b32_dpp v100, v100 row_shl:14 row_mask:0xf bank_mask:0xf bound_ctrl:1
	v_mov_b32_dpp v112, v101 row_shl:15 row_mask:0xf bank_mask:0xf bound_ctrl:1
	v_mov_b32_dpp v96, v96 row_shl:14 row_mask:0xf bank_mask:0xf bound_ctrl:1
	v_mov_b32_dpp v118, v97 row_shl:15 row_mask:0xf bank_mask:0xf bound_ctrl:1
	v_mov_b32_dpp v120, v97 row_shl:14 row_mask:0xf bank_mask:0xf bound_ctrl:1
	v_mov_b32_dpp v111, v98 row_shl:15 row_mask:0xf bank_mask:0xf bound_ctrl:1
	v_mov_b32_dpp v101, v98 row_shl:14 row_mask:0xf bank_mask:0xf bound_ctrl:1
	v_mov_b32_dpp v113, v99 row_shl:15 row_mask:0xf bank_mask:0xf bound_ctrl:1
	v_mov_b32_dpp v115, v99 row_shl:14 row_mask:0xf bank_mask:0xf bound_ctrl:1
	v_mov_b32_dpp v97, v94 row_shl:14 row_mask:0xf bank_mask:0xf bound_ctrl:1
	v_mov_b32_dpp v98, v88 row_shr:2 row_mask:0xf bank_mask:0xf bound_ctrl:1
	v_mov_b32_dpp v128, v80 row_shr:2 row_mask:0xf bank_mask:0xf bound_ctrl:1
	v_mov_b32_dpp v99, v86 row_shr:2 row_mask:0xf bank_mask:0xf bound_ctrl:1
	v_mov_b32_dpp v129, v78 row_shr:2 row_mask:0xf bank_mask:0xf bound_ctrl:1
; #define LAS __attribute__((address_space(3)))
; __device__ __forceinline__ unsigned cvt_pk_bf16(float lo, float hi) { unsigned r; asm volatile("s_nop 1\n\tv_cvt_pk_bf16_f32 %0, %1, %2" : "=v"(r) : "v"(lo), "v"(hi)); return r; }
; __device__ __forceinline__ float siluf_(float x) { return x * __builtin_amdgcn_rcpf(1.0f + __expf(-x)); }
;     __device__ __forceinline__ void operator()(f32x4 (&acc)[2][2][4][2], const Unit& u, int wr, int wc, int fr, int fq) const {
;     ...
;                     if (m > 0) {
; #pragma unroll
;                         for (int bj = 0; bj < 2; ++bj)
; #pragma unroll
;                             for (int e = 0; e < 4; ++e) { const float pv = acc[ai][bj][m - 1][n][e]; t1[bj][e] = DPPF(pv, 0x10F); t2[bj][e] = DPPF(pv, 0x10E); }
;                     } else {
;                         const bool has_pred = (wr == 1) || (ai == 1);
;                         const int pai = (wr == 1) ? ai : 0, pwr = (wr == 1) ? 0 : 1;
;                         const LAS float* p14 = X + ((((pai * 2 + pwr) * 4 + wc) * 2 + 0) * 4 + fq) * 16; const LAS float* p15 = p14 + 64;
; #pragma unroll
;                         for (int bj = 0; bj < 2; ++bj) { const f32x4 r14 = *(const LAS f32x4*)(p14 + bj * 8 + n * 4), r15 = *(const LAS f32x4*)(p15 + bj * 8 + n * 4);
; #pragma unroll
;                             for (int e = 0; e < 4; ++e) { t1[bj][e] = (has_pred && fr == 0) ? r15[e] : 0.f; t2[bj][e] = has_pred ? (fr == 0 ? r14[e] : (fr == 1 ? r15[e] : 0.f)) : 0.f; } }
;                     }
;                     float h[2][4];
; #pragma unroll
;                     for (int bj = 0; bj < 2; ++bj)
; #pragma unroll
;                         for (int e = 0; e < 4; ++e) { const float cur = acc[ai][bj][m][n][e];
;                             const float p1 = DPPF(cur, 0x111) + t1[bj][e], p2 = DPPF(cur, 0x112) + t2[bj][e];
;                             h[bj][e] = w[0][bj][e] * p2 + w[1][bj][e] * p1 + w[2][bj][e] * cur; }
;                     float r4[4];
; #pragma unroll
;                     for (int c = 0; c < 4; ++c) r4[c] = siluf_(h[0][c]) * h[1][c];
;                     const bool skip = (ai == 0) && (m == 0) && (wr == 0) && (fr < 2);
;                     if (!skip) { u32x2 o; o.x = cvt_pk_bf16(r4[0], r4[1]); o.y = cvt_pk_bf16(r4[2], r4[3]);
;                         *(u32x2*)(ACT + (size_t)(u.pm * BM + ai * HALF + wr * 64 + m * 16 + fr) * DFF + chb + 4 * n) = o; }
	v_mov_b32_dpp v117, v94 row_shl:15 row_mask:0xf bank_mask:0xf bound_ctrl:1
	v_mov_b32_dpp v119, v95 row_shl:15 row_mask:0xf bank_mask:0xf bound_ctrl:1
	v_mov_b32_dpp v121, v95 row_shl:14 row_mask:0xf bank_mask:0xf bound_ctrl:1
	v_mov_b32_dpp v94, v88 row_shr:1 row_mask:0xf bank_mask:0xf bound_ctrl:1
	v_mov_b32_dpp v124, v89 row_shr:2 row_mask:0xf bank_mask:0xf bound_ctrl:1
	v_mov_b32_dpp v126, v80 row_shr:1 row_mask:0xf bank_mask:0xf bound_ctrl:1
	v_mov_b32_dpp v132, v81 row_shr:2 row_mask:0xf bank_mask:0xf bound_ctrl:1
	v_mov_b32_dpp v95, v86 row_shr:1 row_mask:0xf bank_mask:0xf bound_ctrl:1
	v_mov_b32_dpp v133, v79 row_shr:2 row_mask:0xf bank_mask:0xf bound_ctrl:1
	v_mov_b32_dpp v127, v78 row_shr:1 row_mask:0xf bank_mask:0xf bound_ctrl:1
	v_pk_add_f32 v[96:97], v[96:97], v[128:129]
	v_mov_b32_dpp v125, v87 row_shr:2 row_mask:0xf bank_mask:0xf bound_ctrl:1
	v_pk_add_f32 v[98:99], v[100:101], v[98:99]
	v_mov_b32_dpp v122, v89 row_shr:1 row_mask:0xf bank_mask:0xf bound_ctrl:1
	v_mov_b32_dpp v130, v81 row_shr:1 row_mask:0xf bank_mask:0xf bound_ctrl:1
	v_mov_b32_dpp v131, v79 row_shr:1 row_mask:0xf bank_mask:0xf bound_ctrl:1
	v_pk_add_f32 v[120:121], v[120:121], v[132:133]
	v_mov_b32_dpp v123, v87 row_shr:1 row_mask:0xf bank_mask:0xf bound_ctrl:1
	v_pk_mul_f32 v[96:97], v[220:221], v[96:97]
	v_pk_add_f32 v[116:117], v[116:117], v[126:127]
	v_pk_add_f32 v[114:115], v[114:115], v[124:125]
	v_pk_mul_f32 v[98:99], v[214:215], v[98:99]
	v_pk_add_f32 v[94:95], v[110:111], v[94:95]
	v_pk_mul_f32 v[120:121], v[164:165], v[120:121]
	v_pk_add_f32 v[118:119], v[118:119], v[130:131]
	v_pk_fma_f32 v[96:97], v[218:219], v[116:117], v[96:97]
	v_mov_b32_e32 v116, v80
	v_mov_b32_e32 v117, v78
	v_pk_mul_f32 v[114:115], v[206:207], v[114:115]
	v_pk_add_f32 v[112:113], v[112:113], v[122:123]
	v_pk_fma_f32 v[94:95], v[212:213], v[94:95], v[98:99]
	v_mov_b32_e32 v98, v88
	v_mov_b32_e32 v99, v86
	v_pk_fma_f32 v[118:119], v[202:203], v[118:119], v[120:121]
	v_mov_b32_e32 v120, v81
	v_mov_b32_e32 v121, v79
	v_pk_fma_f32 v[96:97], v[216:217], v[116:117], v[96:97]
	v_pk_fma_f32 v[112:113], v[208:209], v[112:113], v[114:115]
	v_mov_b32_e32 v114, v89
	v_mov_b32_e32 v115, v87
	v_pk_fma_f32 v[94:95], v[210:211], v[98:99], v[94:95]
	v_pk_fma_f32 v[118:119], v[162:163], v[120:121], v[118:119]
	v_mul_f32_e32 v116, 0xbfb8aa3b, v96
	v_pk_fma_f32 v[112:113], v[204:205], v[114:115], v[112:113]
	v_mul_f32_e32 v98, 0xbfb8aa3b, v94
	v_mul_f32_e32 v120, 0xbfb8aa3b, v118
	v_exp_f32_e32 v116, v116
	v_mul_f32_e32 v114, 0xbfb8aa3b, v112
	v_exp_f32_e32 v98, v98
	v_exp_f32_e32 v120, v120
	v_exp_f32_e32 v114, v114
	v_add_f32_e32 v116, 1.0, v116
	v_add_f32_e32 v98, 1.0, v98
	v_add_f32_e32 v120, 1.0, v120
	v_rcp_f32_e32 v116, v116
	v_add_f32_e32 v99, 1.0, v114
	v_rcp_f32_e32 v98, v98
	v_rcp_f32_e32 v120, v120
	v_rcp_f32_e32 v99, v99
	v_mul_f32_e32 v96, v96, v116
	v_mul_f32_e32 v94, v94, v98
	v_pk_mul_f32 v[68:69], v[68:69], v[190:191] op_sel_hi:[1,0]
	v_mul_f32_e32 v117, v118, v120
	v_mul_f32_e32 v96, v96, v97
	v_mul_f32_e32 v97, v112, v99
	v_mul_f32_e32 v94, v94, v95
	v_pk_mul_f32 v[66:67], v[66:67], v[190:191] op_sel_hi:[1,0]
	v_mul_f32_e32 v117, v117, v119
	v_mul_f32_e32 v97, v97, v113
	s_nop 1
	v_cvt_pk_bf16_f32 v94, v94, v97
	s_nop 1
	v_cvt_pk_bf16_f32 v95, v96, v117
	v_add_u32_e32 v96, 0x90, v160
	v_mov_b32_dpp v100, v80 row_shl:15 row_mask:0xf bank_mask:0xf bound_ctrl:1
	v_mov_b32_dpp v80, v80 row_shl:14 row_mask:0xf bank_mask:0xf bound_ctrl:1
	v_mov_b32_dpp v112, v81 row_shl:15 row_mask:0xf bank_mask:0xf bound_ctrl:1
	v_mov_b32_dpp v114, v81 row_shl:14 row_mask:0xf bank_mask:0xf bound_ctrl:1
	v_mov_b32_dpp v81, v78 row_shl:14 row_mask:0xf bank_mask:0xf bound_ctrl:1
	v_mov_b32_dpp v122, v70 row_shr:2 row_mask:0xf bank_mask:0xf bound_ctrl:1
	v_mov_b32_dpp v123, v68 row_shr:2 row_mask:0xf bank_mask:0xf bound_ctrl:1
	v_mad_i64_i32 v[96:97], s[10:11], v96, s55, v[74:75]
	v_mov_b32_dpp v98, v89 row_shl:14 row_mask:0xf bank_mask:0xf bound_ctrl:1
	v_mov_b32_dpp v99, v87 row_shl:14 row_mask:0xf bank_mask:0xf bound_ctrl:1
	v_mov_b32_dpp v101, v78 row_shl:15 row_mask:0xf bank_mask:0xf bound_ctrl:1
	v_mov_b32_dpp v118, v73 row_shr:2 row_mask:0xf bank_mask:0xf bound_ctrl:1
	v_mov_b32_dpp v120, v70 row_shr:1 row_mask:0xf bank_mask:0xf bound_ctrl:1
	v_mov_b32_dpp v121, v68 row_shr:1 row_mask:0xf bank_mask:0xf bound_ctrl:1
	v_pk_add_f32 v[80:81], v[80:81], v[122:123]
	v_mov_b32_dpp v119, v67 row_shr:2 row_mask:0xf bank_mask:0xf bound_ctrl:1
	v_lshl_add_u64 v[110:111], v[96:97], 0, v[76:77]
	v_mov_b32_dpp v96, v89 row_shl:15 row_mask:0xf bank_mask:0xf bound_ctrl:1
	v_mov_b32_dpp v97, v87 row_shl:15 row_mask:0xf bank_mask:0xf bound_ctrl:1
	v_mov_b32_dpp v116, v73 row_shr:1 row_mask:0xf bank_mask:0xf bound_ctrl:1
	v_mov_b32_dpp v117, v67 row_shr:1 row_mask:0xf bank_mask:0xf bound_ctrl:1
	v_pk_mul_f32 v[80:81], v[220:221], v[80:81]
	v_pk_add_f32 v[100:101], v[100:101], v[120:121]
	v_pk_add_f32 v[98:99], v[98:99], v[118:119]
	v_pk_fma_f32 v[80:81], v[218:219], v[100:101], v[80:81]
	v_mov_b32_e32 v100, v70
	v_mov_b32_e32 v101, v68
	v_pk_mul_f32 v[98:99], v[206:207], v[98:99]
	v_pk_add_f32 v[96:97], v[96:97], v[116:117]
	v_pk_fma_f32 v[80:81], v[216:217], v[100:101], v[80:81]
	v_pk_fma_f32 v[96:97], v[208:209], v[96:97], v[98:99]
	v_mov_b32_e32 v98, v73
	v_mov_b32_e32 v99, v67
	v_mul_f32_e32 v100, 0xbfb8aa3b, v80
	v_pk_fma_f32 v[96:97], v[204:205], v[98:99], v[96:97]
	v_exp_f32_e32 v100, v100
	v_mul_f32_e32 v98, 0xbfb8aa3b, v96
	s_nop 0
	v_mov_b32_e32 v172, v94
	v_mov_b32_e32 v173, v95
	v_mov_b32_dpp v94, v88 row_shl:15 row_mask:0xf bank_mask:0xf bound_ctrl:1
	v_mov_b32_dpp v88, v88 row_shl:14 row_mask:0xf bank_mask:0xf bound_ctrl:1
; #define LAS __attribute__((address_space(3)))
; __device__ __forceinline__ float siluf_(float x) { return x * __builtin_amdgcn_rcpf(1.0f + __expf(-x)); }
; #define DPPF(v, ctrl) __builtin_bit_cast(float, __builtin_amdgcn_update_dpp(0, __builtin_bit_cast(int, (v)), (ctrl), 0xf, 0xf, true))
;     __device__ __forceinline__ void operator()(f32x4 (&acc)[2][2][4][2], const Unit& u, int wr, int wc, int fr, int fq) const {
;     ...
;                     if (m > 0) {
; #pragma unroll
;                         for (int bj = 0; bj < 2; ++bj)
; #pragma unroll
;                             for (int e = 0; e < 4; ++e) { const float pv = acc[ai][bj][m - 1][n][e]; t1[bj][e] = DPPF(pv, 0x10F); t2[bj][e] = DPPF(pv, 0x10E); }
;                     } else {
;                         const bool has_pred = (wr == 1) || (ai == 1);
;                         const int pai = (wr == 1) ? ai : 0, pwr = (wr == 1) ? 0 : 1;
;                         const LAS float* p14 = X + ((((pai * 2 + pwr) * 4 + wc) * 2 + 0) * 4 + fq) * 16; const LAS float* p15 = p14 + 64;
; #pragma unroll
;                         for (int bj = 0; bj < 2; ++bj) { const f32x4 r14 = *(const LAS f32x4*)(p14 + bj * 8 + n * 4), r15 = *(const LAS f32x4*)(p15 + bj * 8 + n * 4);
; #pragma unroll
;                             for (int e = 0; e < 4; ++e) { t1[bj][e] = (has_pred && fr == 0) ? r15[e] : 0.f; t2[bj][e] = has_pred ? (fr == 0 ? r14[e] : (fr == 1 ? r15[e] : 0.f)) : 0.f; } }
;                     }
;                     float h[2][4];
; #pragma unroll
;                     for (int bj = 0; bj < 2; ++bj)
; #pragma unroll
;                         for (int e = 0; e < 4; ++e) { const float cur = acc[ai][bj][m][n][e];
;                             const float p1 = DPPF(cur, 0x111) + t1[bj][e], p2 = DPPF(cur, 0x112) + t2[bj][e];
;                             h[bj][e] = w[0][bj][e] * p2 + w[1][bj][e] * p1 + w[2][bj][e] * cur; }
;                     float r4[4];
; #pragma unroll
;                     for (int c = 0; c < 4; ++c) r4[c] = siluf_(h[0][c]) * h[1][c];
	v_mov_b32_dpp v95, v86 row_shl:15 row_mask:0xf bank_mask:0xf bound_ctrl:1
	v_mov_b32_dpp v89, v86 row_shl:14 row_mask:0xf bank_mask:0xf bound_ctrl:1
	v_mov_b32_dpp v86, v72 row_shr:2 row_mask:0xf bank_mask:0xf bound_ctrl:1
	v_mov_b32_dpp v87, v66 row_shr:2 row_mask:0xf bank_mask:0xf bound_ctrl:1
	v_exp_f32_e32 v98, v98
	v_mov_b32_dpp v113, v79 row_shl:15 row_mask:0xf bank_mask:0xf bound_ctrl:1
	v_mov_b32_dpp v115, v79 row_shl:14 row_mask:0xf bank_mask:0xf bound_ctrl:1
	v_mov_b32_dpp v78, v72 row_shr:1 row_mask:0xf bank_mask:0xf bound_ctrl:1
	v_mov_b32_dpp v79, v66 row_shr:1 row_mask:0xf bank_mask:0xf bound_ctrl:1
	v_pk_add_f32 v[86:87], v[88:89], v[86:87]
	v_pk_add_f32 v[78:79], v[94:95], v[78:79]
	v_pk_mul_f32 v[86:87], v[214:215], v[86:87]
	v_add_f32_e32 v100, 1.0, v100
	v_pk_fma_f32 v[78:79], v[212:213], v[78:79], v[86:87]
	v_mov_b32_e32 v86, v72
	v_mov_b32_e32 v87, v66
	v_mov_b32_dpp v126, v71 row_shr:2 row_mask:0xf bank_mask:0xf bound_ctrl:1
	v_mov_b32_dpp v127, v69 row_shr:2 row_mask:0xf bank_mask:0xf bound_ctrl:1
	v_rcp_f32_e32 v100, v100
	v_pk_fma_f32 v[78:79], v[210:211], v[86:87], v[78:79]
	v_add_f32_e32 v87, 1.0, v98
	v_mov_b32_dpp v124, v71 row_shr:1 row_mask:0xf bank_mask:0xf bound_ctrl:1
	v_mov_b32_dpp v125, v69 row_shr:1 row_mask:0xf bank_mask:0xf bound_ctrl:1
	v_pk_add_f32 v[114:115], v[114:115], v[126:127]
	v_rcp_f32_e32 v87, v87
	v_pk_mul_f32 v[114:115], v[164:165], v[114:115]
	v_pk_add_f32 v[112:113], v[112:113], v[124:125]
	v_mul_f32_e32 v80, v80, v100
	v_pk_fma_f32 v[112:113], v[202:203], v[112:113], v[114:115]
	v_mov_b32_e32 v114, v71
	v_mov_b32_e32 v115, v69
	v_pk_fma_f32 v[112:113], v[162:163], v[114:115], v[112:113]
	v_mul_f32_e32 v80, v80, v81
	v_mul_f32_e32 v114, 0xbfb8aa3b, v112
	v_mul_f32_e32 v81, v96, v87
	v_exp_f32_e32 v114, v114
	v_mul_f32_e32 v81, v81, v97
	v_mov_b32_dpp v96, v71 row_shl:14 row_mask:0xf bank_mask:0xf bound_ctrl:1
	v_mov_b32_dpp v97, v69 row_shl:14 row_mask:0xf bank_mask:0xf bound_ctrl:1
	v_mov_b32_dpp v120, v85 row_shr:2 row_mask:0xf bank_mask:0xf bound_ctrl:1
	v_mov_b32_dpp v121, v93 row_shr:2 row_mask:0xf bank_mask:0xf bound_ctrl:1
	v_mov_b32_dpp v94, v71 row_shl:15 row_mask:0xf bank_mask:0xf bound_ctrl:1
	v_mov_b32_dpp v95, v69 row_shl:15 row_mask:0xf bank_mask:0xf bound_ctrl:1
	v_mov_b32_dpp v118, v85 row_shr:1 row_mask:0xf bank_mask:0xf bound_ctrl:1
	v_mov_b32_dpp v119, v93 row_shr:1 row_mask:0xf bank_mask:0xf bound_ctrl:1
	v_pk_add_f32 v[96:97], v[96:97], v[120:121]
	v_pk_add_f32 v[94:95], v[94:95], v[118:119]
	v_pk_mul_f32 v[96:97], v[164:165], v[96:97]
	v_add_f32_e32 v114, 1.0, v114
	v_pk_fma_f32 v[94:95], v[202:203], v[94:95], v[96:97]
	v_mov_b32_e32 v96, v85
	v_mov_b32_e32 v97, v93
	v_pk_fma_f32 v[94:95], v[162:163], v[96:97], v[94:95]
	v_rcp_f32_e32 v114, v114
	v_mul_f32_e32 v86, 0xbfb8aa3b, v78
	v_mul_f32_e32 v85, 0xbfb8aa3b, v94
	v_exp_f32_e32 v86, v86
	v_exp_f32_e32 v85, v85
	v_mov_b32_dpp v88, v70 row_shl:15 row_mask:0xf bank_mask:0xf bound_ctrl:1
	v_mov_b32_dpp v70, v70 row_shl:14 row_mask:0xf bank_mask:0xf bound_ctrl:1
	v_mov_b32_dpp v71, v68 row_shl:14 row_mask:0xf bank_mask:0xf bound_ctrl:1
	v_mov_b32_dpp v116, v84 row_shr:2 row_mask:0xf bank_mask:0xf bound_ctrl:1
	v_mov_b32_dpp v117, v92 row_shr:2 row_mask:0xf bank_mask:0xf bound_ctrl:1
	v_mul_f32_e32 v101, v112, v114
	v_mov_b32_dpp v89, v68 row_shl:15 row_mask:0xf bank_mask:0xf bound_ctrl:1
	v_mov_b32_dpp v114, v84 row_shr:1 row_mask:0xf bank_mask:0xf bound_ctrl:1
	v_mov_b32_dpp v115, v92 row_shr:1 row_mask:0xf bank_mask:0xf bound_ctrl:1
	v_pk_add_f32 v[70:71], v[70:71], v[116:117]
	v_add_f32_e32 v86, 1.0, v86
	v_add_f32_e32 v85, 1.0, v85
	v_pk_mul_f32 v[70:71], v[220:221], v[70:71]
	v_pk_add_f32 v[88:89], v[88:89], v[114:115]
	v_rcp_f32_e32 v86, v86
	v_rcp_f32_e32 v93, v85
	v_pk_fma_f32 v[70:71], v[218:219], v[88:89], v[70:71]
	v_mov_b32_e32 v85, v92
	v_pk_fma_f32 v[70:71], v[216:217], v[84:85], v[70:71]
	v_mul_f32_e32 v78, v78, v86
;     __device__ __forceinline__ void operator()(f32x4 (&acc)[2][2][4][2], const Unit& u, int wr, int wc, int fr, int fq) const {
;     ...
;                 for (int bj = 0; bj < 2; ++bj) w[k][bj] = (n == 0) ? wq[k][bj] : *(const f32x4*)(fw + k * DFF2 + bj * DFF + chb + 4);
; #pragma unroll
;             for (int ai = 0; ai < 2; ++ai)
; #pragma unroll
;                 for (int m = 0; m < 4; ++m) {
;                     f32x4 t1[2], t2[2];
;                     if (m > 0) {
; #pragma unroll
;                         for (int bj = 0; bj < 2; ++bj)
; #pragma unroll
;                             for (int e = 0; e < 4; ++e) { const float pv = acc[ai][bj][m - 1][n][e]; t1[bj][e] = DPPF(pv, 0x10F); t2[bj][e] = DPPF(pv, 0x10E); }
;                     } else {
;                         const bool has_pred = (wr == 1) || (ai == 1);
;                         const int pai = (wr == 1) ? ai : 0, pwr = (wr == 1) ? 0 : 1;
;                         const LAS float* p14 = X + ((((pai * 2 + pwr) * 4 + wc) * 2 + 0) * 4 + fq) * 16; const LAS float* p15 = p14 + 64;
; #pragma unroll
;                         for (int bj = 0; bj < 2; ++bj) { const f32x4 r14 = *(const LAS f32x4*)(p14 + bj * 8 + n * 4), r15 = *(const LAS f32x4*)(p15 + bj * 8 + n * 4);
; #pragma unroll
;                             for (int e = 0; e < 4; ++e) { t1[bj][e] = (has_pred && fr == 0) ? r15[e] : 0.f; t2[bj][e] = has_pred ? (fr == 0 ? r14[e] : (fr == 1 ? r15[e] : 0.f)) : 0.f; } }
;                     }
;                     float h[2][4];
; #pragma unroll
;                     for (int bj = 0; bj < 2; ++bj)
; #pragma unroll
;                         for (int e = 0; e < 4; ++e) { const float cur = acc[ai][bj][m][n][e];
;                             const float p1 = DPPF(cur, 0x111) + t1[bj][e], p2 = DPPF(cur, 0x112) + t2[bj][e];
;                             h[bj][e] = w[0][bj][e] * p2 + w[1][bj][e] * p1 + w[2][bj][e] * cur; }
;                     float r4[4];
; #pragma unroll
;                     for (int c = 0; c < 4; ++c) r4[c] = siluf_(h[0][c]) * h[1][c];
;                     const bool skip = (ai == 0) && (m == 0) && (wr == 0) && (fr < 2);
;                     if (!skip) { u32x2 o; o.x = cvt_pk_bf16(r4[0], r4[1]); o.y = cvt_pk_bf16(r4[2], r4[3]);
;                         *(u32x2*)(ACT + (size_t)(u.pm * BM + ai * HALF + wr * 64 + m * 16 + fr) * DFF + chb + 4 * n) = o; }
	v_mul_f32_e32 v84, 0xbfb8aa3b, v70
	v_exp_f32_e32 v84, v84
	v_mul_f32_e32 v78, v78, v79
	v_mul_f32_e32 v101, v101, v113
	s_nop 1
	v_cvt_pk_bf16_f32 v78, v78, v81
	s_nop 1
	v_cvt_pk_bf16_f32 v79, v80, v101
	v_add_u32_e32 v80, 0xa0, v160
	v_mad_i64_i32 v[80:81], s[10:11], v80, s55, v[74:75]
	v_mov_b32_dpp v86, v73 row_shl:14 row_mask:0xf bank_mask:0xf bound_ctrl:1
	v_mov_b32_dpp v87, v67 row_shl:14 row_mask:0xf bank_mask:0xf bound_ctrl:1
	v_mov_b32_dpp v100, v83 row_shr:2 row_mask:0xf bank_mask:0xf bound_ctrl:1
	v_mov_b32_dpp v101, v91 row_shr:2 row_mask:0xf bank_mask:0xf bound_ctrl:1
	v_mul_f32_e32 v85, v94, v93
	v_add_f32_e32 v84, 1.0, v84
	v_lshl_add_u64 v[112:113], v[80:81], 0, v[76:77]
	v_mov_b32_dpp v80, v73 row_shl:15 row_mask:0xf bank_mask:0xf bound_ctrl:1
	v_mov_b32_dpp v81, v67 row_shl:15 row_mask:0xf bank_mask:0xf bound_ctrl:1
	v_mov_b32_dpp v98, v83 row_shr:1 row_mask:0xf bank_mask:0xf bound_ctrl:1
	v_mov_b32_dpp v99, v91 row_shr:1 row_mask:0xf bank_mask:0xf bound_ctrl:1
	v_mul_f32_e32 v88, v85, v95
	v_rcp_f32_e32 v89, v84
	v_pk_add_f32 v[84:85], v[86:87], v[100:101]
	v_pk_add_f32 v[80:81], v[80:81], v[98:99]
	v_pk_mul_f32 v[84:85], v[206:207], v[84:85]
	s_nop 0
	v_mov_b32_e32 v216, v78
	v_mov_b32_e32 v217, v79
	v_mov_b32_dpp v78, v72 row_shl:15 row_mask:0xf bank_mask:0xf bound_ctrl:1
	v_mov_b32_dpp v72, v72 row_shl:14 row_mask:0xf bank_mask:0xf bound_ctrl:1
	v_mov_b32_dpp v73, v66 row_shl:14 row_mask:0xf bank_mask:0xf bound_ctrl:1
	v_mov_b32_dpp v68, v82 row_shr:2 row_mask:0xf bank_mask:0xf bound_ctrl:1
	v_mov_b32_dpp v69, v90 row_shr:2 row_mask:0xf bank_mask:0xf bound_ctrl:1
	v_pk_fma_f32 v[80:81], v[208:209], v[80:81], v[84:85]
	v_mov_b32_e32 v84, v83
	v_mov_b32_e32 v85, v91
	v_mov_b32_dpp v79, v66 row_shl:15 row_mask:0xf bank_mask:0xf bound_ctrl:1
	v_mov_b32_dpp v66, v82 row_shr:1 row_mask:0xf bank_mask:0xf bound_ctrl:1
	v_mov_b32_dpp v67, v90 row_shr:1 row_mask:0xf bank_mask:0xf bound_ctrl:1
	v_pk_fma_f32 v[80:81], v[204:205], v[84:85], v[80:81]
	v_pk_add_f32 v[68:69], v[72:73], v[68:69]
	v_mul_f32_e32 v83, 0xbfb8aa3b, v80
	v_pk_mul_f32 v[68:69], v[214:215], v[68:69]
	v_pk_add_f32 v[66:67], v[78:79], v[66:67]
	v_exp_f32_e32 v84, v83
	v_pk_fma_f32 v[66:67], v[212:213], v[66:67], v[68:69]
	v_mov_b32_e32 v83, v90
	v_pk_fma_f32 v[66:67], v[210:211], v[82:83], v[66:67]
	v_mul_f32_e32 v69, v70, v89
	v_mul_f32_e32 v68, 0xbfb8aa3b, v66
	v_exp_f32_e32 v68, v68
	v_add_f32_e32 v70, 1.0, v84
	v_rcp_f32_e32 v70, v70
	v_mul_f32_e32 v69, v69, v71
	v_add_f32_e32 v68, 1.0, v68
	v_rcp_f32_e32 v68, v68
	v_mul_f32_e32 v70, v80, v70
	v_mul_f32_e32 v70, v70, v81
	v_mov_b32_e32 v140, 0
	v_mul_f32_e32 v66, v66, v68
	v_mul_f32_e32 v66, v66, v67
	s_nop 1
	v_cvt_pk_bf16_f32 v66, v66, v70
	v_add_co_u32_e32 v70, vcc, s81, v198
	v_add_u32_e32 v68, 0xb0, v160
	s_nop 0
	v_addc_co_u32_e32 v71, vcc, 0, v199, vcc
	s_nop 1
	v_cvt_pk_bf16_f32 v67, v69, v88
	v_mad_i64_i32 v[68:69], s[10:11], v68, s55, v[74:75]
	v_add_co_u32_e32 v74, vcc, s64, v198
	v_lshl_add_u64 v[114:115], v[68:69], 0, v[76:77]
	s_nop 0
	v_addc_co_u32_e32 v75, vcc, 0, v199, vcc
	v_add_co_u32_e32 v76, vcc, 0xb000, v198
	s_nop 0
	v_mov_b32_e32 v218, v66
	v_mov_b32_e32 v219, v67
	s_nop 0
	v_addc_co_u32_e32 v77, vcc, 0, v199, vcc
	v_add_co_u32_e32 v86, vcc, 0xd000, v198
	global_load_dwordx4 v[66:69], v[198:199], off offset:16
	s_nop 0
	v_addc_co_u32_e32 v87, vcc, 0, v199, vcc
	global_load_dwordx4 v[78:81], v[200:201], off offset:3088
	s_nop 0
	global_load_dwordx4 v[70:73], v[70:71], off offset:2064
	s_nop 0
	global_load_dwordx4 v[82:85], v[74:75], off offset:1040
	s_nop 0
	global_load_dwordx4 v[74:77], v[76:77], off offset:16
	s_and_b64 vcc, exec, s[8:9]
	global_load_dwordx4 v[86:89], v[86:87], off offset:3088
	ds_read_b128 v[94:97], v167 offset:16
	ds_read_b128 v[90:93], v167 offset:272
	v_mov_b32_e32 v136, 0
	s_cbranch_vccz .LBB0_1119
	s_and_b64 vcc, exec, s[48:49]
	v_mov_b32_e32 v138, 0
	s_cbranch_vccz .LBB0_1122

; #define LAS __attribute__((address_space(3)))
; __device__ __forceinline__ unsigned cvt_pk_bf16(float lo, float hi) { unsigned r; asm volatile("s_nop 1\n\tv_cvt_pk_bf16_f32 %0, %1, %2" : "=v"(r) : "v"(lo), "v"(hi)); return r; }
; __device__ __forceinline__ float siluf_(float x) { return x * __builtin_amdgcn_rcpf(1.0f + __expf(-x)); }
; #define DPPF(v, ctrl) __builtin_bit_cast(float, __builtin_amdgcn_update_dpp(0, __builtin_bit_cast(int, (v)), (ctrl), 0xf, 0xf, true))
;     __device__ __forceinline__ void operator()(f32x4 (&acc)[2][2][4][2], const Unit& u, int wr, int wc, int fr, int fq) const {
;     ...
;                         const bool has_pred = (wr == 1) || (ai == 1);
;                         const int pai = (wr == 1) ? ai : 0, pwr = (wr == 1) ? 0 : 1;
;                         const LAS float* p14 = X + ((((pai * 2 + pwr) * 4 + wc) * 2 + 0) * 4 + fq) * 16; const LAS float* p15 = p14 + 64;
; #pragma unroll
;                         for (int bj = 0; bj < 2; ++bj) { const f32x4 r14 = *(const LAS f32x4*)(p14 + bj * 8 + n * 4), r15 = *(const LAS f32x4*)(p15 + bj * 8 + n * 4);
; #pragma unroll
;                             for (int e = 0; e < 4; ++e) { t1[bj][e] = (has_pred && fr == 0) ? r15[e] : 0.f; t2[bj][e] = has_pred ? (fr == 0 ? r14[e] : (fr == 1 ? r15[e] : 0.f)) : 0.f; } }
;                     }
;                     float h[2][4];
; #pragma unroll
;                     for (int bj = 0; bj < 2; ++bj)
; #pragma unroll
;                         for (int e = 0; e < 4; ++e) { const float cur = acc[ai][bj][m][n][e];
;                             const float p1 = DPPF(cur, 0x111) + t1[bj][e], p2 = DPPF(cur, 0x112) + t2[bj][e];
;                             h[bj][e] = w[0][bj][e] * p2 + w[1][bj][e] * p1 + w[2][bj][e] * cur; }
;                     float r4[4];
; #pragma unroll
;                     for (int c = 0; c < 4; ++c) r4[c] = siluf_(h[0][c]) * h[1][c];
;                     const bool skip = (ai == 0) && (m == 0) && (wr == 0) && (fr < 2);
;                     if (!skip) { u32x2 o; o.x = cvt_pk_bf16(r4[0], r4[1]); o.y = cvt_pk_bf16(r4[2], r4[3]);
;                         *(u32x2*)(ACT + (size_t)(u.pm * BM + ai * HALF + wr * 64 + m * 16 + fr) * DFF + chb + 4 * n) = o; }
.LBB0_1143:
	v_mov_b32_dpp v142, v58 row_shr:1 row_mask:0xf bank_mask:0xf bound_ctrl:1
	v_mov_b32_dpp v144, v58 row_shr:2 row_mask:0xf bank_mask:0xf bound_ctrl:1
	v_mov_b32_dpp v148, v59 row_shr:1 row_mask:0xf bank_mask:0xf bound_ctrl:1
	v_mov_b32_dpp v150, v59 row_shr:2 row_mask:0xf bank_mask:0xf bound_ctrl:1
	v_mov_b32_dpp v152, v60 row_shr:1 row_mask:0xf bank_mask:0xf bound_ctrl:1
	v_mov_b32_dpp v154, v60 row_shr:2 row_mask:0xf bank_mask:0xf bound_ctrl:1
	v_mov_b32_dpp v156, v61 row_shr:1 row_mask:0xf bank_mask:0xf bound_ctrl:1
	v_mov_b32_dpp v158, v61 row_shr:2 row_mask:0xf bank_mask:0xf bound_ctrl:1
	v_mov_b32_dpp v143, v62 row_shr:1 row_mask:0xf bank_mask:0xf bound_ctrl:1
	v_mov_b32_dpp v145, v62 row_shr:2 row_mask:0xf bank_mask:0xf bound_ctrl:1
	v_mov_b32_dpp v149, v63 row_shr:1 row_mask:0xf bank_mask:0xf bound_ctrl:1
	v_mov_b32_dpp v151, v63 row_shr:2 row_mask:0xf bank_mask:0xf bound_ctrl:1
	v_mov_b32_dpp v153, v64 row_shr:1 row_mask:0xf bank_mask:0xf bound_ctrl:1
	v_mov_b32_dpp v155, v64 row_shr:2 row_mask:0xf bank_mask:0xf bound_ctrl:1
	v_mov_b32_dpp v157, v65 row_shr:1 row_mask:0xf bank_mask:0xf bound_ctrl:1
	v_mov_b32_dpp v159, v65 row_shr:2 row_mask:0xf bank_mask:0xf bound_ctrl:1
	s_waitcnt vmcnt(1)
	v_mov_b32_e32 v124, v74
	s_waitcnt vmcnt(0)
	v_mov_b32_e32 v125, v86
	v_mov_b32_e32 v126, v70
	v_mov_b32_e32 v127, v82
	v_mov_b32_e32 v128, v66
	v_mov_b32_e32 v129, v78
	v_mov_b32_e32 v118, v75
	v_mov_b32_e32 v119, v87
	v_mov_b32_e32 v120, v71
	v_mov_b32_e32 v121, v83
	v_mov_b32_e32 v122, v67
	v_mov_b32_e32 v123, v79
	v_mov_b32_e32 v130, v76
	v_mov_b32_e32 v131, v88
	v_mov_b32_e32 v132, v72
	v_mov_b32_e32 v133, v84
	v_mov_b32_e32 v134, v68
	v_mov_b32_e32 v135, v80
	s_waitcnt lgkmcnt(1)
	v_mov_b32_e32 v98, v77
	v_mov_b32_e32 v99, v89
	v_mov_b32_e32 v100, v73
	v_mov_b32_e32 v101, v85
	v_mov_b32_e32 v116, v69
	v_mov_b32_e32 v117, v81
	s_and_saveexec_b64 s[8:9], s[60:61]
	s_xor_b64 s[8:9], exec, s[8:9]
	s_cbranch_execz .LBB0_1145
	s_waitcnt lgkmcnt(0)
	v_cndmask_b32_e64 v97, 0, v97, s[50:51]
	v_cndmask_b32_e64 v119, 0, v96, s[50:51]
	v_cndmask_b32_e64 v96, 0, v93, s[50:51]
	v_cndmask_b32_e64 v118, 0, v92, s[50:51]
	v_pk_add_f32 v[92:93], v[146:147], v[158:159]
	v_mov_b32_e32 v116, v69
	v_mov_b32_e32 v117, v81
	v_pk_mul_f32 v[92:93], v[116:117], v[92:93]
	v_pk_add_f32 v[96:97], v[96:97], v[156:157]
	v_mov_b32_e32 v100, v73
	v_mov_b32_e32 v101, v85
	v_cndmask_b32_e64 v125, 0, v94, s[50:51]
	v_cndmask_b32_e64 v94, 0, v91, s[50:51]
	v_cndmask_b32_e64 v124, 0, v90, s[50:51]
	v_mov_b32_e32 v90, v61
	v_mov_b32_e32 v91, v65
	v_mov_b32_e32 v98, v77
	v_mov_b32_e32 v99, v89
	v_pk_fma_f32 v[92:93], v[100:101], v[96:97], v[92:93]
	v_mov_b32_e32 v77, v88
	v_pk_fma_f32 v[90:91], v[90:91], v[98:99], v[92:93]
	v_pk_add_f32 v[88:89], v[140:141], v[154:155]
	v_mul_f32_e32 v69, 0xbfb8aa3b, v90
	v_exp_f32_e32 v69, v69
	v_mov_b32_e32 v73, v84
	v_cndmask_b32_e64 v95, 0, v95, s[50:51]
	v_mov_b32_e32 v122, v67
	v_add_f32_e32 v69, 1.0, v69
	v_rcp_f32_e32 v69, v69
	v_mov_b32_e32 v123, v79
	v_mov_b32_e32 v120, v71
	v_mov_b32_e32 v121, v83
	v_mul_f32_e32 v69, v90, v69
	v_mul_f32_e32 v92, v69, v91
	v_mov_b32_e32 v69, v80
	v_pk_mul_f32 v[80:81], v[68:69], v[88:89]
	v_pk_add_f32 v[88:89], v[118:119], v[152:153]
	v_mov_b32_e32 v90, v60
	v_mov_b32_e32 v91, v64
	v_pk_fma_f32 v[80:81], v[72:73], v[88:89], v[80:81]
	v_pk_add_f32 v[88:89], v[94:95], v[148:149]
	v_pk_fma_f32 v[80:81], v[90:91], v[76:77], v[80:81]
	v_mov_b32_e32 v118, v75
	v_mul_f32_e32 v84, 0xbfb8aa3b, v80
	v_exp_f32_e32 v84, v84
	v_mov_b32_e32 v119, v87
	v_mov_b32_e32 v71, v82
	v_mov_b32_e32 v75, v86
	v_add_f32_e32 v84, 1.0, v84
	v_rcp_f32_e32 v84, v84
	s_movk_i32 s10, 0x1600
	v_mov_b64_e32 v[134:135], v[68:69]
	v_mov_b64_e32 v[132:133], v[72:73]
	v_mul_f32_e32 v80, v80, v84
	v_pk_add_f32 v[84:85], v[138:139], v[150:151]
	v_mul_f32_e32 v90, v80, v81
	v_pk_mul_f32 v[84:85], v[122:123], v[84:85]
	v_mov_b32_e32 v80, v59
	v_mov_b32_e32 v81, v63
	v_pk_fma_f32 v[84:85], v[120:121], v[88:89], v[84:85]
	v_mov_b64_e32 v[130:131], v[76:77]
	v_pk_fma_f32 v[80:81], v[80:81], v[118:119], v[84:85]
	v_pk_add_f32 v[84:85], v[136:137], v[144:145]
	v_mul_f32_e32 v67, 0xbfb8aa3b, v80
	v_exp_f32_e32 v67, v67
	v_mov_b64_e32 v[126:127], v[70:71]
	v_add_f32_e32 v67, 1.0, v67
	v_rcp_f32_e32 v67, v67
	s_nop 0
	v_mul_f32_e32 v67, v80, v67
	v_mul_f32_e32 v83, v67, v81
	v_mov_b32_e32 v67, v78
	v_pk_mul_f32 v[78:79], v[66:67], v[84:85]
	v_pk_add_f32 v[84:85], v[124:125], v[142:143]
	v_mov_b32_e32 v80, v58
	v_mov_b32_e32 v81, v62
	v_pk_fma_f32 v[78:79], v[70:71], v[84:85], v[78:79]
	v_mov_b64_e32 v[128:129], v[66:67]
	v_pk_fma_f32 v[78:79], v[80:81], v[74:75], v[78:79]
	v_mov_b64_e32 v[124:125], v[74:75]
	v_mul_f32_e32 v80, 0xbfb8aa3b, v78
	v_exp_f32_e32 v80, v80
	s_nop 0
	v_add_f32_e32 v80, 1.0, v80
	v_rcp_f32_e32 v80, v80
	s_nop 0
	v_mul_f32_e32 v78, v78, v80
	v_mov_b64_e32 v[80:81], s[68:69]
	v_mad_i64_i32 v[80:81], s[10:11], v160, s10, v[80:81]
	v_mul_f32_e32 v78, v78, v79
	v_lshl_add_u64 v[80:81], v[188:189], 1, v[80:81]
	s_nop 1
	v_cvt_pk_bf16_f32 v78, v78, v83
	s_nop 1
	v_cvt_pk_bf16_f32 v79, v90, v92
	s_nop 0
	v_mov_b32_e32 v224, v222
	v_mov_b32_e32 v225, v223
	v_mov_b32_e32 v226, v78
	v_mov_b32_e32 v227, v79
	global_store_dwordx4 v[80:81], v[224:227], off
; #define LAS __attribute__((address_space(3)))
; __device__ __forceinline__ float siluf_(float x) { return x * __builtin_amdgcn_rcpf(1.0f + __expf(-x)); }
; #define DPPF(v, ctrl) __builtin_bit_cast(float, __builtin_amdgcn_update_dpp(0, __builtin_bit_cast(int, (v)), (ctrl), 0xf, 0xf, true))
;     __device__ __forceinline__ void operator()(f32x4 (&acc)[2][2][4][2], const Unit& u, int wr, int wc, int fr, int fq) const {
;     ...
;             for (int ai = 0; ai < 2; ++ai)
; #pragma unroll
;                 for (int m = 0; m < 4; ++m) { const float rs = RS[ai * HALF + wr * 64 + m * 16 + fr];
; #pragma unroll
;                     for (int bj = 0; bj < 2; ++bj)
; #pragma unroll
;                         for (int n = 0; n < 2; ++n) acc[ai][bj][m][n] = acc[ai][bj][m][n] * rs; }
;     ...
;                     if (m > 0) {
; #pragma unroll
;                         for (int bj = 0; bj < 2; ++bj)
; #pragma unroll
;                             for (int e = 0; e < 4; ++e) { const float pv = acc[ai][bj][m - 1][n][e]; t1[bj][e] = DPPF(pv, 0x10F); t2[bj][e] = DPPF(pv, 0x10E); }
;                     } else {
;                         const bool has_pred = (wr == 1) || (ai == 1);
;                         const int pai = (wr == 1) ? ai : 0, pwr = (wr == 1) ? 0 : 1;
;                         const LAS float* p14 = X + ((((pai * 2 + pwr) * 4 + wc) * 2 + 0) * 4 + fq) * 16; const LAS float* p15 = p14 + 64;
; #pragma unroll
;                         for (int bj = 0; bj < 2; ++bj) { const f32x4 r14 = *(const LAS f32x4*)(p14 + bj * 8 + n * 4), r15 = *(const LAS f32x4*)(p15 + bj * 8 + n * 4);
; #pragma unroll
;                             for (int e = 0; e < 4; ++e) { t1[bj][e] = (has_pred && fr == 0) ? r15[e] : 0.f; t2[bj][e] = has_pred ? (fr == 0 ? r14[e] : (fr == 1 ? r15[e] : 0.f)) : 0.f; } }
;                     }
;                     float h[2][4];
; #pragma unroll
;                     for (int bj = 0; bj < 2; ++bj)
; #pragma unroll
;                         for (int e = 0; e < 4; ++e) { const float cur = acc[ai][bj][m][n][e];
;                             const float p1 = DPPF(cur, 0x111) + t1[bj][e], p2 = DPPF(cur, 0x112) + t2[bj][e];
;                             h[bj][e] = w[0][bj][e] * p2 + w[1][bj][e] * p1 + w[2][bj][e] * cur; }
;                     float r4[4];
; #pragma unroll
;                     for (int c = 0; c < 4; ++c) r4[c] = siluf_(h[0][c]) * h[1][c];
.LBB0_1145:
	s_andn2_saveexec_b64 s[8:9], s[8:9]
	s_or_b64 exec, exec, s[8:9]
	v_mov_b32_e32 v194, v195
	v_mov_b32_e32 v193, v192
	v_mov_b32_e32 v70, v195
	v_mov_b32_e32 v71, v195
	v_pk_mul_f32 v[72:73], v[38:39], v[194:195]
	v_mov_b32_e32 v38, v192
	v_mov_b32_e32 v39, v192
	v_mov_b32_e32 v66, v196
	v_mov_b32_e32 v67, v196
	v_mov_b32_e32 v68, v197
	v_mov_b32_e32 v69, v197
	v_pk_mul_f32 v[48:49], v[48:49], v[70:71]
	v_pk_mul_f32 v[70:71], v[40:41], v[70:71]
	v_pk_mul_f32 v[40:41], v[44:45], v[38:39]
	v_pk_mul_f32 v[44:45], v[42:43], v[192:193]
	v_pk_mul_f32 v[42:43], v[34:35], v[192:193]
	v_mov_b32_e32 v34, v196
	v_mov_b32_e32 v35, v196
	v_mov_b32_e32 v196, v197
	v_pk_mul_f32 v[38:39], v[36:37], v[38:39]
	v_pk_mul_f32 v[36:37], v[22:23], v[66:67]
	v_pk_mul_f32 v[22:23], v[16:17], v[34:35]
	v_pk_mul_f32 v[16:17], v[20:21], v[196:197]
	v_pk_mul_f32 v[20:21], v[18:19], v[68:69]
	v_pk_mul_f32 v[18:19], v[6:7], v[68:69]
	v_mov_b32_dpp v68, v60 row_shl:15 row_mask:0xf bank_mask:0xf bound_ctrl:1
	v_mov_b32_dpp v60, v60 row_shl:14 row_mask:0xf bank_mask:0xf bound_ctrl:1
	v_mov_b32_dpp v74, v61 row_shl:15 row_mask:0xf bank_mask:0xf bound_ctrl:1
	v_mov_b32_dpp v76, v61 row_shl:14 row_mask:0xf bank_mask:0xf bound_ctrl:1
	v_mov_b32_dpp v61, v64 row_shl:14 row_mask:0xf bank_mask:0xf bound_ctrl:1
	v_mov_b32_dpp v84, v48 row_shr:2 row_mask:0xf bank_mask:0xf bound_ctrl:1
	v_mov_b32_dpp v85, v70 row_shr:2 row_mask:0xf bank_mask:0xf bound_ctrl:1
	v_mov_b32_dpp v69, v64 row_shl:15 row_mask:0xf bank_mask:0xf bound_ctrl:1
	v_mov_b32_dpp v82, v48 row_shr:1 row_mask:0xf bank_mask:0xf bound_ctrl:1
	v_mov_b32_dpp v83, v70 row_shr:1 row_mask:0xf bank_mask:0xf bound_ctrl:1
	v_pk_add_f32 v[60:61], v[60:61], v[84:85]
	v_pk_add_f32 v[68:69], v[68:69], v[82:83]
	v_pk_mul_f32 v[60:61], v[134:135], v[60:61]
	v_pk_mul_f32 v[46:47], v[46:47], v[194:195]
	v_pk_fma_f32 v[60:61], v[132:133], v[68:69], v[60:61]
	v_mov_b32_e32 v68, v48
	v_mov_b32_e32 v69, v70
	v_pk_mul_f32 v[24:25], v[24:25], v[34:35]
	v_pk_mul_f32 v[34:35], v[14:15], v[66:67]
	v_mov_b32_e32 v66, v190
	v_mov_b32_e32 v67, v190
	v_pk_fma_f32 v[60:61], v[68:69], v[130:131], v[60:61]
	v_mov_b32_e32 v191, v190
	v_pk_mul_f32 v[6:7], v[12:13], v[66:67]
	v_pk_mul_f32 v[4:5], v[4:5], v[66:67]
	v_mov_b32_dpp v66, v59 row_shl:14 row_mask:0xf bank_mask:0xf bound_ctrl:1
	v_mov_b32_dpp v67, v63 row_shl:14 row_mask:0xf bank_mask:0xf bound_ctrl:1
	v_mov_b32_dpp v77, v65 row_shl:14 row_mask:0xf bank_mask:0xf bound_ctrl:1
	v_mov_b32_dpp v80, v47 row_shr:2 row_mask:0xf bank_mask:0xf bound_ctrl:1
	v_mov_b32_dpp v88, v49 row_shr:2 row_mask:0xf bank_mask:0xf bound_ctrl:1
	v_mov_b32_dpp v89, v71 row_shr:2 row_mask:0xf bank_mask:0xf bound_ctrl:1
	v_mul_f32_e32 v68, 0xbfb8aa3b, v60
	v_mov_b32_dpp v81, v73 row_shr:2 row_mask:0xf bank_mask:0xf bound_ctrl:1
	v_pk_mul_f32 v[14:15], v[8:9], v[196:197]
	v_pk_mul_f32 v[8:9], v[10:11], v[190:191]
	v_mov_b32_dpp v10, v58 row_shl:15 row_mask:0xf bank_mask:0xf bound_ctrl:1
	v_mov_b32_dpp v12, v58 row_shl:14 row_mask:0xf bank_mask:0xf bound_ctrl:1
	v_mov_b32_dpp v58, v59 row_shl:15 row_mask:0xf bank_mask:0xf bound_ctrl:1
	v_mov_b32_dpp v59, v63 row_shl:15 row_mask:0xf bank_mask:0xf bound_ctrl:1
	v_mov_b32_dpp v75, v65 row_shl:15 row_mask:0xf bank_mask:0xf bound_ctrl:1
	v_mov_b32_dpp v78, v47 row_shr:1 row_mask:0xf bank_mask:0xf bound_ctrl:1
	v_mov_b32_dpp v86, v49 row_shr:1 row_mask:0xf bank_mask:0xf bound_ctrl:1
	v_mov_b32_dpp v87, v71 row_shr:1 row_mask:0xf bank_mask:0xf bound_ctrl:1
	v_pk_add_f32 v[76:77], v[76:77], v[88:89]
	v_mov_b32_dpp v79, v73 row_shr:1 row_mask:0xf bank_mask:0xf bound_ctrl:1
	v_exp_f32_e32 v68, v68
	v_pk_add_f32 v[66:67], v[66:67], v[80:81]
	v_mov_b32_dpp v13, v62 row_shl:14 row_mask:0xf bank_mask:0xf bound_ctrl:1
	v_mov_b32_dpp v64, v46 row_shr:2 row_mask:0xf bank_mask:0xf bound_ctrl:1
	v_mov_b32_dpp v65, v72 row_shr:2 row_mask:0xf bank_mask:0xf bound_ctrl:1
	v_pk_mul_f32 v[76:77], v[116:117], v[76:77]
	v_pk_add_f32 v[74:75], v[74:75], v[86:87]
	v_pk_mul_f32 v[66:67], v[122:123], v[66:67]
	v_pk_add_f32 v[58:59], v[58:59], v[78:79]
	v_mov_b32_dpp v11, v62 row_shl:15 row_mask:0xf bank_mask:0xf bound_ctrl:1
	v_mov_b32_dpp v62, v46 row_shr:1 row_mask:0xf bank_mask:0xf bound_ctrl:1
	v_mov_b32_dpp v63, v72 row_shr:1 row_mask:0xf bank_mask:0xf bound_ctrl:1
	v_pk_fma_f32 v[74:75], v[100:101], v[74:75], v[76:77]
	v_mov_b32_e32 v76, v49
	v_mov_b32_e32 v77, v71
	v_pk_fma_f32 v[58:59], v[120:121], v[58:59], v[66:67]
	v_mov_b32_e32 v66, v47
	v_mov_b32_e32 v67, v73
	v_pk_add_f32 v[12:13], v[12:13], v[64:65]
	v_pk_fma_f32 v[74:75], v[76:77], v[98:99], v[74:75]
	v_pk_fma_f32 v[58:59], v[66:67], v[118:119], v[58:59]
	v_pk_mul_f32 v[12:13], v[128:129], v[12:13]
	v_pk_add_f32 v[10:11], v[10:11], v[62:63]
	v_mul_f32_e32 v76, 0xbfb8aa3b, v74
	v_add_f32_e32 v68, 1.0, v68
	v_mul_f32_e32 v66, 0xbfb8aa3b, v58
	v_pk_fma_f32 v[10:11], v[126:127], v[10:11], v[12:13]
	v_mov_b32_e32 v12, v46
	v_mov_b32_e32 v13, v72
	v_exp_f32_e32 v76, v76
	v_rcp_f32_e32 v68, v68
	v_exp_f32_e32 v66, v66
	v_pk_fma_f32 v[10:11], v[12:13], v[124:125], v[10:11]
	v_add_f32_e32 v76, 1.0, v76
	v_mul_f32_e32 v12, 0xbfb8aa3b, v10
	v_exp_f32_e32 v12, v12
	v_mul_f32_e32 v13, v60, v68
	v_add_f32_e32 v60, 1.0, v66
	v_rcp_f32_e32 v76, v76
	v_rcp_f32_e32 v60, v60
	v_add_f32_e32 v12, 1.0, v12
	v_rcp_f32_e32 v12, v12
	v_mul_f32_e32 v69, v74, v76
	v_mul_f32_e32 v58, v58, v60
	v_mov_b32_dpp v60, v48 row_shl:15 row_mask:0xf bank_mask:0xf bound_ctrl:1
	v_mov_b32_dpp v48, v48 row_shl:14 row_mask:0xf bank_mask:0xf bound_ctrl:1
	v_mov_b32_dpp v62, v49 row_shl:15 row_mask:0xf bank_mask:0xf bound_ctrl:1
; #define LAS __attribute__((address_space(3)))
; __device__ __forceinline__ unsigned cvt_pk_bf16(float lo, float hi) { unsigned r; asm volatile("s_nop 1\n\tv_cvt_pk_bf16_f32 %0, %1, %2" : "=v"(r) : "v"(lo), "v"(hi)); return r; }
; __device__ __forceinline__ float siluf_(float x) { return x * __builtin_amdgcn_rcpf(1.0f + __expf(-x)); }
;     __device__ __forceinline__ void operator()(f32x4 (&acc)[2][2][4][2], const Unit& u, int wr, int wc, int fr, int fq) const {
;     ...
;                     if (m > 0) {
; #pragma unroll
;                         for (int bj = 0; bj < 2; ++bj)
; #pragma unroll
;                             for (int e = 0; e < 4; ++e) { const float pv = acc[ai][bj][m - 1][n][e]; t1[bj][e] = DPPF(pv, 0x10F); t2[bj][e] = DPPF(pv, 0x10E); }
;                     } else {
;                         const bool has_pred = (wr == 1) || (ai == 1);
;                         const int pai = (wr == 1) ? ai : 0, pwr = (wr == 1) ? 0 : 1;
;                         const LAS float* p14 = X + ((((pai * 2 + pwr) * 4 + wc) * 2 + 0) * 4 + fq) * 16; const LAS float* p15 = p14 + 64;
; #pragma unroll
;                         for (int bj = 0; bj < 2; ++bj) { const f32x4 r14 = *(const LAS f32x4*)(p14 + bj * 8 + n * 4), r15 = *(const LAS f32x4*)(p15 + bj * 8 + n * 4);
; #pragma unroll
;                             for (int e = 0; e < 4; ++e) { t1[bj][e] = (has_pred && fr == 0) ? r15[e] : 0.f; t2[bj][e] = has_pred ? (fr == 0 ? r14[e] : (fr == 1 ? r15[e] : 0.f)) : 0.f; } }
;                     }
;                     float h[2][4];
; #pragma unroll
;                     for (int bj = 0; bj < 2; ++bj)
; #pragma unroll
;                         for (int e = 0; e < 4; ++e) { const float cur = acc[ai][bj][m][n][e];
;                             const float p1 = DPPF(cur, 0x111) + t1[bj][e], p2 = DPPF(cur, 0x112) + t2[bj][e];
;                             h[bj][e] = w[0][bj][e] * p2 + w[1][bj][e] * p1 + w[2][bj][e] * cur; }
;                     float r4[4];
; #pragma unroll
;                     for (int c = 0; c < 4; ++c) r4[c] = siluf_(h[0][c]) * h[1][c];
;                     const bool skip = (ai == 0) && (m == 0) && (wr == 0) && (fr < 2);
;                     if (!skip) { u32x2 o; o.x = cvt_pk_bf16(r4[0], r4[1]); o.y = cvt_pk_bf16(r4[2], r4[3]);
;                         *(u32x2*)(ACT + (size_t)(u.pm * BM + ai * HALF + wr * 64 + m * 16 + fr) * DFF + chb + 4 * n) = o; }
	v_mov_b32_dpp v64, v49 row_shl:14 row_mask:0xf bank_mask:0xf bound_ctrl:1
	v_mov_b32_dpp v49, v70 row_shl:14 row_mask:0xf bank_mask:0xf bound_ctrl:1
	v_mov_b32_dpp v76, v40 row_shr:2 row_mask:0xf bank_mask:0xf bound_ctrl:1
	v_mov_b32_dpp v77, v38 row_shr:2 row_mask:0xf bank_mask:0xf bound_ctrl:1
	v_mul_f32_e32 v69, v69, v75
	v_mul_f32_e32 v13, v13, v61
	v_mov_b32_dpp v61, v70 row_shl:15 row_mask:0xf bank_mask:0xf bound_ctrl:1
	v_mov_b32_dpp v74, v40 row_shr:1 row_mask:0xf bank_mask:0xf bound_ctrl:1
	v_mov_b32_dpp v75, v38 row_shr:1 row_mask:0xf bank_mask:0xf bound_ctrl:1
	v_pk_add_f32 v[48:49], v[48:49], v[76:77]
	v_mul_f32_e32 v10, v10, v12
	v_pk_mul_f32 v[48:49], v[134:135], v[48:49]
	v_pk_add_f32 v[60:61], v[60:61], v[74:75]
	v_mul_f32_e32 v10, v10, v11
	v_pk_fma_f32 v[48:49], v[132:133], v[60:61], v[48:49]
	v_mov_b32_e32 v60, v40
	v_mov_b32_e32 v61, v38
	v_mul_f32_e32 v58, v58, v59
	s_nop 1
	v_cvt_pk_bf16_f32 v10, v10, v58
	s_nop 1
	v_cvt_pk_bf16_f32 v11, v13, v69
	v_mov_b32_dpp v12, v46 row_shl:14 row_mask:0xf bank_mask:0xf bound_ctrl:1
	v_mov_b32_dpp v13, v72 row_shl:14 row_mask:0xf bank_mask:0xf bound_ctrl:1
	v_mov_b32_dpp v65, v71 row_shl:14 row_mask:0xf bank_mask:0xf bound_ctrl:1
	v_mov_b32_dpp v68, v44 row_shr:2 row_mask:0xf bank_mask:0xf bound_ctrl:1
	v_mov_b32_dpp v80, v41 row_shr:2 row_mask:0xf bank_mask:0xf bound_ctrl:1
	v_mov_b32_dpp v69, v42 row_shr:2 row_mask:0xf bank_mask:0xf bound_ctrl:1
	v_mov_b32_dpp v81, v39 row_shr:2 row_mask:0xf bank_mask:0xf bound_ctrl:1
	v_pk_fma_f32 v[48:49], v[60:61], v[130:131], v[48:49]
	s_nop 0
	v_mov_b32_e32 v228, v232
	v_mov_b32_e32 v229, v233
	v_mov_b32_e32 v230, v10
	v_mov_b32_e32 v231, v11
	global_store_dwordx4 v[102:103], v[228:231], off
	v_mov_b32_dpp v10, v46 row_shl:15 row_mask:0xf bank_mask:0xf bound_ctrl:1
	v_mov_b32_dpp v46, v47 row_shl:15 row_mask:0xf bank_mask:0xf bound_ctrl:1
	v_mov_b32_dpp v58, v47 row_shl:14 row_mask:0xf bank_mask:0xf bound_ctrl:1
	v_mov_b32_dpp v11, v72 row_shl:15 row_mask:0xf bank_mask:0xf bound_ctrl:1
	v_mov_b32_dpp v47, v73 row_shl:15 row_mask:0xf bank_mask:0xf bound_ctrl:1
	v_mov_b32_dpp v59, v73 row_shl:14 row_mask:0xf bank_mask:0xf bound_ctrl:1
	v_mov_b32_dpp v63, v71 row_shl:15 row_mask:0xf bank_mask:0xf bound_ctrl:1
	v_mov_b32_dpp v66, v44 row_shr:1 row_mask:0xf bank_mask:0xf bound_ctrl:1
	v_mov_b32_dpp v72, v45 row_shr:2 row_mask:0xf bank_mask:0xf bound_ctrl:1
	v_mov_b32_dpp v78, v41 row_shr:1 row_mask:0xf bank_mask:0xf bound_ctrl:1
	v_mov_b32_dpp v67, v42 row_shr:1 row_mask:0xf bank_mask:0xf bound_ctrl:1
	v_mov_b32_dpp v79, v39 row_shr:1 row_mask:0xf bank_mask:0xf bound_ctrl:1
	v_pk_add_f32 v[64:65], v[64:65], v[80:81]
	v_mul_f32_e32 v60, 0xbfb8aa3b, v48
	v_mov_b32_dpp v73, v43 row_shr:2 row_mask:0xf bank_mask:0xf bound_ctrl:1
	v_pk_add_f32 v[12:13], v[12:13], v[68:69]
	v_mov_b32_dpp v70, v45 row_shr:1 row_mask:0xf bank_mask:0xf bound_ctrl:1
	v_pk_mul_f32 v[64:65], v[116:117], v[64:65]
	v_pk_add_f32 v[62:63], v[62:63], v[78:79]
	v_mov_b32_dpp v71, v43 row_shr:1 row_mask:0xf bank_mask:0xf bound_ctrl:1
	v_exp_f32_e32 v60, v60
	v_pk_add_f32 v[58:59], v[58:59], v[72:73]
	v_pk_mul_f32 v[12:13], v[128:129], v[12:13]
	v_pk_add_f32 v[10:11], v[10:11], v[66:67]
	v_pk_fma_f32 v[62:63], v[100:101], v[62:63], v[64:65]
	v_mov_b32_e32 v64, v41
	v_mov_b32_e32 v65, v39
	v_pk_mul_f32 v[58:59], v[122:123], v[58:59]
	v_pk_add_f32 v[46:47], v[46:47], v[70:71]
	v_pk_fma_f32 v[10:11], v[126:127], v[10:11], v[12:13]
	v_mov_b32_e32 v12, v44
	v_mov_b32_e32 v13, v42
	v_pk_fma_f32 v[62:63], v[64:65], v[98:99], v[62:63]
	v_pk_fma_f32 v[46:47], v[120:121], v[46:47], v[58:59]
	v_mov_b32_e32 v58, v45
	v_mov_b32_e32 v59, v43
	v_pk_fma_f32 v[10:11], v[12:13], v[124:125], v[10:11]
	v_mul_f32_e32 v64, 0xbfb8aa3b, v62
	v_pk_fma_f32 v[46:47], v[58:59], v[118:119], v[46:47]
	v_mul_f32_e32 v12, 0xbfb8aa3b, v10
	v_exp_f32_e32 v64, v64
	v_add_f32_e32 v60, 1.0, v60
	v_mul_f32_e32 v58, 0xbfb8aa3b, v46
	v_exp_f32_e32 v12, v12
	v_rcp_f32_e32 v60, v60
	v_exp_f32_e32 v58, v58
	v_add_f32_e32 v64, 1.0, v64
	v_add_f32_e32 v12, 1.0, v12
	v_rcp_f32_e32 v64, v64
	v_mul_f32_e32 v13, v48, v60
	v_add_f32_e32 v48, 1.0, v58
	v_rcp_f32_e32 v12, v12
	v_rcp_f32_e32 v48, v48
	v_mul_f32_e32 v61, v62, v64
	v_mul_f32_e32 v61, v61, v63
	v_mul_f32_e32 v10, v10, v12
	v_mul_f32_e32 v46, v46, v48
	v_mul_f32_e32 v10, v10, v11
	v_mul_f32_e32 v13, v13, v49
	v_mul_f32_e32 v46, v46, v47
	s_nop 1
	v_cvt_pk_bf16_f32 v10, v10, v46
	s_nop 1
	v_cvt_pk_bf16_f32 v11, v13, v61
	v_mov_b32_dpp v60, v41 row_shl:14 row_mask:0xf bank_mask:0xf bound_ctrl:1
	v_mov_b32_dpp v61, v39 row_shl:14 row_mask:0xf bank_mask:0xf bound_ctrl:1
	v_mov_b32_dpp v72, v53 row_shr:2 row_mask:0xf bank_mask:0xf bound_ctrl:1
	v_mov_b32_dpp v73, v57 row_shr:2 row_mask:0xf bank_mask:0xf bound_ctrl:1
	v_mov_b32_dpp v58, v41 row_shl:15 row_mask:0xf bank_mask:0xf bound_ctrl:1
	v_mov_b32_dpp v59, v39 row_shl:15 row_mask:0xf bank_mask:0xf bound_ctrl:1
	v_mov_b32_dpp v70, v53 row_shr:1 row_mask:0xf bank_mask:0xf bound_ctrl:1
	v_mov_b32_dpp v71, v57 row_shr:1 row_mask:0xf bank_mask:0xf bound_ctrl:1
	v_pk_add_f32 v[60:61], v[60:61], v[72:73]
	v_pk_add_f32 v[58:59], v[58:59], v[70:71]
	v_pk_mul_f32 v[60:61], v[116:117], v[60:61]
	s_nop 0
	v_mov_b32_e32 v224, v236
	v_mov_b32_e32 v225, v237
	v_mov_b32_e32 v226, v10
	v_mov_b32_e32 v227, v11
	global_store_dwordx4 v[104:105], v[224:227], off
	v_pk_fma_f32 v[58:59], v[100:101], v[58:59], v[60:61]
	v_mov_b32_e32 v60, v53
	v_mov_b32_e32 v61, v57
	v_pk_fma_f32 v[58:59], v[60:61], v[98:99], v[58:59]
	v_mov_b32_dpp v10, v44 row_shl:15 row_mask:0xf bank_mask:0xf bound_ctrl:1
	v_mul_f32_e32 v53, 0xbfb8aa3b, v58
	v_exp_f32_e32 v53, v53
; #define LAS __attribute__((address_space(3)))
; __device__ __forceinline__ unsigned cvt_pk_bf16(float lo, float hi) { unsigned r; asm volatile("s_nop 1\n\tv_cvt_pk_bf16_f32 %0, %1, %2" : "=v"(r) : "v"(lo), "v"(hi)); return r; }
; __device__ __forceinline__ float siluf_(float x) { return x * __builtin_amdgcn_rcpf(1.0f + __expf(-x)); }
;     __device__ __forceinline__ void operator()(f32x4 (&acc)[2][2][4][2], const Unit& u, int wr, int wc, int fr, int fq) const {
;     ...
;                     if (m > 0) {
; #pragma unroll
;                         for (int bj = 0; bj < 2; ++bj)
; #pragma unroll
;                             for (int e = 0; e < 4; ++e) { const float pv = acc[ai][bj][m - 1][n][e]; t1[bj][e] = DPPF(pv, 0x10F); t2[bj][e] = DPPF(pv, 0x10E); }
;                     } else {
;                         const bool has_pred = (wr == 1) || (ai == 1);
;                         const int pai = (wr == 1) ? ai : 0, pwr = (wr == 1) ? 0 : 1;
;                         const LAS float* p14 = X + ((((pai * 2 + pwr) * 4 + wc) * 2 + 0) * 4 + fq) * 16; const LAS float* p15 = p14 + 64;
; #pragma unroll
;                         for (int bj = 0; bj < 2; ++bj) { const f32x4 r14 = *(const LAS f32x4*)(p14 + bj * 8 + n * 4), r15 = *(const LAS f32x4*)(p15 + bj * 8 + n * 4);
; #pragma unroll
;                             for (int e = 0; e < 4; ++e) { t1[bj][e] = (has_pred && fr == 0) ? r15[e] : 0.f; t2[bj][e] = has_pred ? (fr == 0 ? r14[e] : (fr == 1 ? r15[e] : 0.f)) : 0.f; } }
;                     }
;                     float h[2][4];
; #pragma unroll
;                     for (int bj = 0; bj < 2; ++bj)
; #pragma unroll
;                         for (int e = 0; e < 4; ++e) { const float cur = acc[ai][bj][m][n][e];
;                             const float p1 = DPPF(cur, 0x111) + t1[bj][e], p2 = DPPF(cur, 0x112) + t2[bj][e];
;                             h[bj][e] = w[0][bj][e] * p2 + w[1][bj][e] * p1 + w[2][bj][e] * cur; }
;                     float r4[4];
; #pragma unroll
;                     for (int c = 0; c < 4; ++c) r4[c] = siluf_(h[0][c]) * h[1][c];
;                     const bool skip = (ai == 0) && (m == 0) && (wr == 0) && (fr < 2);
;                     if (!skip) { u32x2 o; o.x = cvt_pk_bf16(r4[0], r4[1]); o.y = cvt_pk_bf16(r4[2], r4[3]);
;                         *(u32x2*)(ACT + (size_t)(u.pm * BM + ai * HALF + wr * 64 + m * 16 + fr) * DFF + chb + 4 * n) = o; }
	v_mov_b32_dpp v12, v44 row_shl:14 row_mask:0xf bank_mask:0xf bound_ctrl:1
	v_mov_b32_dpp v44, v45 row_shl:15 row_mask:0xf bank_mask:0xf bound_ctrl:1
	v_mov_b32_dpp v46, v45 row_shl:14 row_mask:0xf bank_mask:0xf bound_ctrl:1
	v_mov_b32_dpp v11, v42 row_shl:15 row_mask:0xf bank_mask:0xf bound_ctrl:1
	v_mov_b32_dpp v13, v42 row_shl:14 row_mask:0xf bank_mask:0xf bound_ctrl:1
	v_mov_b32_dpp v45, v43 row_shl:15 row_mask:0xf bank_mask:0xf bound_ctrl:1
	v_mov_b32_dpp v47, v43 row_shl:14 row_mask:0xf bank_mask:0xf bound_ctrl:1
	v_mov_b32_dpp v42, v50 row_shr:2 row_mask:0xf bank_mask:0xf bound_ctrl:1
	v_mov_b32_dpp v64, v51 row_shr:2 row_mask:0xf bank_mask:0xf bound_ctrl:1
	v_mov_b32_dpp v43, v54 row_shr:2 row_mask:0xf bank_mask:0xf bound_ctrl:1
	v_mov_b32_dpp v65, v55 row_shr:2 row_mask:0xf bank_mask:0xf bound_ctrl:1
	v_mov_b32_dpp v48, v40 row_shl:15 row_mask:0xf bank_mask:0xf bound_ctrl:1
	v_mov_b32_dpp v40, v40 row_shl:14 row_mask:0xf bank_mask:0xf bound_ctrl:1
	v_mov_b32_dpp v49, v38 row_shl:15 row_mask:0xf bank_mask:0xf bound_ctrl:1
	v_mov_b32_dpp v41, v38 row_shl:14 row_mask:0xf bank_mask:0xf bound_ctrl:1
	v_mov_b32_dpp v38, v50 row_shr:1 row_mask:0xf bank_mask:0xf bound_ctrl:1
	v_mov_b32_dpp v62, v51 row_shr:1 row_mask:0xf bank_mask:0xf bound_ctrl:1
	v_mov_b32_dpp v68, v52 row_shr:2 row_mask:0xf bank_mask:0xf bound_ctrl:1
	v_mov_b32_dpp v39, v54 row_shr:1 row_mask:0xf bank_mask:0xf bound_ctrl:1
	v_mov_b32_dpp v63, v55 row_shr:1 row_mask:0xf bank_mask:0xf bound_ctrl:1
	v_mov_b32_dpp v69, v56 row_shr:2 row_mask:0xf bank_mask:0xf bound_ctrl:1
	v_pk_add_f32 v[46:47], v[46:47], v[64:65]
	v_pk_add_f32 v[12:13], v[12:13], v[42:43]
	v_mov_b32_dpp v66, v52 row_shr:1 row_mask:0xf bank_mask:0xf bound_ctrl:1
	v_mov_b32_dpp v67, v56 row_shr:1 row_mask:0xf bank_mask:0xf bound_ctrl:1
	v_pk_add_f32 v[40:41], v[40:41], v[68:69]
	v_pk_mul_f32 v[46:47], v[122:123], v[46:47]
	v_pk_add_f32 v[44:45], v[44:45], v[62:63]
	v_pk_mul_f32 v[12:13], v[128:129], v[12:13]
	v_pk_add_f32 v[10:11], v[10:11], v[38:39]
	v_add_f32_e32 v53, 1.0, v53
	v_pk_mul_f32 v[40:41], v[134:135], v[40:41]
	v_pk_add_f32 v[48:49], v[48:49], v[66:67]
	v_pk_fma_f32 v[44:45], v[120:121], v[44:45], v[46:47]
	v_mov_b32_e32 v46, v51
	v_pk_fma_f32 v[10:11], v[126:127], v[10:11], v[12:13]
	v_mov_b32_e32 v51, v54
	v_rcp_f32_e32 v57, v53
	v_pk_fma_f32 v[40:41], v[132:133], v[48:49], v[40:41]
	v_mov_b32_e32 v53, v56
	v_mov_b32_e32 v47, v55
	v_pk_fma_f32 v[10:11], v[50:51], v[124:125], v[10:11]
	v_pk_fma_f32 v[40:41], v[52:53], v[130:131], v[40:41]
	v_pk_fma_f32 v[44:45], v[46:47], v[118:119], v[44:45]
	v_mul_f32_e32 v12, 0xbfb8aa3b, v10
	v_mul_f32_e32 v48, 0xbfb8aa3b, v40
	v_mul_f32_e32 v46, 0xbfb8aa3b, v44
	v_exp_f32_e32 v12, v12
	v_exp_f32_e32 v48, v48
	v_exp_f32_e32 v46, v46
	v_mul_f32_e32 v49, v58, v57
	v_add_f32_e32 v12, 1.0, v12
	v_add_f32_e32 v48, 1.0, v48
	v_add_f32_e32 v38, 1.0, v46
	v_rcp_f32_e32 v12, v12
	v_rcp_f32_e32 v48, v48
	v_rcp_f32_e32 v38, v38
	v_mul_f32_e32 v49, v49, v59
	v_mul_f32_e32 v10, v10, v12
	v_mul_f32_e32 v13, v40, v48
	v_mul_f32_e32 v38, v44, v38
	v_mul_f32_e32 v10, v10, v11
	v_mul_f32_e32 v13, v13, v41
	v_mul_f32_e32 v38, v38, v45
	s_nop 1
	v_cvt_pk_bf16_f32 v10, v10, v38
	s_nop 1
	v_cvt_pk_bf16_f32 v11, v13, v49
	s_nop 0
	v_mov_b32_e32 v228, v240
	v_mov_b32_e32 v229, v241
	v_mov_b32_e32 v230, v10
	v_mov_b32_e32 v231, v11
	global_store_dwordx4 v[106:107], v[228:231], off
	ds_read_b128 v[10:13], v0 offset:16
	ds_read_b128 v[38:41], v0 offset:48
	ds_read_b128 v[42:45], v0 offset:272
	ds_read_b128 v[46:49], v0 offset:304
	v_mov_b32_dpp v64, v25 row_shr:2 row_mask:0xf bank_mask:0xf bound_ctrl:1
	v_mov_b32_dpp v65, v23 row_shr:2 row_mask:0xf bank_mask:0xf bound_ctrl:1
	v_mov_b32_dpp v62, v25 row_shr:1 row_mask:0xf bank_mask:0xf bound_ctrl:1
	s_waitcnt lgkmcnt(1)
	v_cndmask_b32_e64 v66, 0, v45, s[42:43]
	v_cndmask_b32_e64 v0, 0, v45, s[44:45]
	s_waitcnt lgkmcnt(0)
	v_cndmask_b32_e64 v45, 0, v49, s[44:45]
	v_cndmask_b32_e64 v69, v45, v41, s[42:43]
	v_cndmask_b32_e64 v68, v0, v13, s[42:43]
	v_mov_b32_dpp v63, v23 row_shr:1 row_mask:0xf bank_mask:0xf bound_ctrl:1
	v_cndmask_b32_e64 v67, 0, v49, s[42:43]
	v_pk_add_f32 v[64:65], v[68:69], v[64:65]
	v_pk_add_f32 v[62:63], v[66:67], v[62:63]
	v_pk_mul_f32 v[64:65], v[116:117], v[64:65]
	v_cndmask_b32_e64 v41, 0, v44, s[44:45]
	v_cndmask_b32_e64 v13, 0, v48, s[44:45]
	v_mov_b32_dpp v60, v24 row_shr:2 row_mask:0xf bank_mask:0xf bound_ctrl:1
	v_pk_fma_f32 v[62:63], v[100:101], v[62:63], v[64:65]
	v_mov_b32_e32 v64, v25
	v_mov_b32_e32 v65, v23
	v_mov_b32_dpp v61, v22 row_shr:2 row_mask:0xf bank_mask:0xf bound_ctrl:1
	v_cndmask_b32_e64 v13, v13, v40, s[42:43]
	v_cndmask_b32_e64 v12, v41, v12, s[42:43]
	v_mov_b32_dpp v58, v24 row_shr:1 row_mask:0xf bank_mask:0xf bound_ctrl:1
	v_pk_fma_f32 v[62:63], v[64:65], v[98:99], v[62:63]
	v_mov_b32_dpp v59, v22 row_shr:1 row_mask:0xf bank_mask:0xf bound_ctrl:1
	v_cndmask_b32_e64 v65, 0, v48, s[42:43]
	v_cndmask_b32_e64 v64, 0, v44, s[42:43]
	v_pk_add_f32 v[12:13], v[12:13], v[60:61]
	v_pk_add_f32 v[40:41], v[64:65], v[58:59]
	v_pk_mul_f32 v[12:13], v[134:135], v[12:13]
	v_cndmask_b32_e64 v44, 0, v47, s[44:45]
	v_pk_fma_f32 v[12:13], v[132:133], v[40:41], v[12:13]
	v_mov_b32_e32 v40, v24
	v_mov_b32_e32 v41, v22
	v_pk_fma_f32 v[12:13], v[40:41], v[130:131], v[12:13]
	v_mov_b32_dpp v56, v37 row_shr:2 row_mask:0xf bank_mask:0xf bound_ctrl:1
	v_mul_f32_e32 v40, 0xbfb8aa3b, v12
	v_exp_f32_e32 v40, v40
	v_mov_b32_dpp v57, v35 row_shr:2 row_mask:0xf bank_mask:0xf bound_ctrl:1
	v_cndmask_b32_e64 v45, v44, v39, s[42:43]
	v_mov_b32_dpp v54, v37 row_shr:1 row_mask:0xf bank_mask:0xf bound_ctrl:1
; #define LAS __attribute__((address_space(3)))
; __device__ __forceinline__ unsigned cvt_pk_bf16(float lo, float hi) { unsigned r; asm volatile("s_nop 1\n\tv_cvt_pk_bf16_f32 %0, %1, %2" : "=v"(r) : "v"(lo), "v"(hi)); return r; }
; __device__ __forceinline__ float siluf_(float x) { return x * __builtin_amdgcn_rcpf(1.0f + __expf(-x)); }
;     __device__ __forceinline__ void operator()(f32x4 (&acc)[2][2][4][2], const Unit& u, int wr, int wc, int fr, int fq) const {
;     ...
;                     if (m > 0) {
; #pragma unroll
;                         for (int bj = 0; bj < 2; ++bj)
; #pragma unroll
;                             for (int e = 0; e < 4; ++e) { const float pv = acc[ai][bj][m - 1][n][e]; t1[bj][e] = DPPF(pv, 0x10F); t2[bj][e] = DPPF(pv, 0x10E); }
;                     } else {
;                         const bool has_pred = (wr == 1) || (ai == 1);
;                         const int pai = (wr == 1) ? ai : 0, pwr = (wr == 1) ? 0 : 1;
;                         const LAS float* p14 = X + ((((pai * 2 + pwr) * 4 + wc) * 2 + 0) * 4 + fq) * 16; const LAS float* p15 = p14 + 64;
; #pragma unroll
;                         for (int bj = 0; bj < 2; ++bj) { const f32x4 r14 = *(const LAS f32x4*)(p14 + bj * 8 + n * 4), r15 = *(const LAS f32x4*)(p15 + bj * 8 + n * 4);
; #pragma unroll
;                             for (int e = 0; e < 4; ++e) { t1[bj][e] = (has_pred && fr == 0) ? r15[e] : 0.f; t2[bj][e] = has_pred ? (fr == 0 ? r14[e] : (fr == 1 ? r15[e] : 0.f)) : 0.f; } }
;                     }
;                     float h[2][4];
; #pragma unroll
;                     for (int bj = 0; bj < 2; ++bj)
; #pragma unroll
;                         for (int e = 0; e < 4; ++e) { const float cur = acc[ai][bj][m][n][e];
;                             const float p1 = DPPF(cur, 0x111) + t1[bj][e], p2 = DPPF(cur, 0x112) + t2[bj][e];
;                             h[bj][e] = w[0][bj][e] * p2 + w[1][bj][e] * p1 + w[2][bj][e] * cur; }
;                     float r4[4];
; #pragma unroll
;                     for (int c = 0; c < 4; ++c) r4[c] = siluf_(h[0][c]) * h[1][c];
;                     const bool skip = (ai == 0) && (m == 0) && (wr == 0) && (fr < 2);
;                     if (!skip) { u32x2 o; o.x = cvt_pk_bf16(r4[0], r4[1]); o.y = cvt_pk_bf16(r4[2], r4[3]);
;                         *(u32x2*)(ACT + (size_t)(u.pm * BM + ai * HALF + wr * 64 + m * 16 + fr) * DFF + chb + 4 * n) = o; }
	v_add_f32_e32 v40, 1.0, v40
	v_rcp_f32_e32 v48, v40
	v_cndmask_b32_e64 v40, 0, v43, s[42:43]
	v_cndmask_b32_e64 v43, 0, v43, s[44:45]
	v_cndmask_b32_e64 v44, v43, v11, s[42:43]
	v_mov_b32_dpp v55, v35 row_shr:1 row_mask:0xf bank_mask:0xf bound_ctrl:1
	v_cndmask_b32_e64 v41, 0, v47, s[42:43]
	v_pk_add_f32 v[44:45], v[44:45], v[56:57]
	v_pk_add_f32 v[40:41], v[40:41], v[54:55]
	v_pk_mul_f32 v[44:45], v[122:123], v[44:45]
	v_cndmask_b32_e64 v39, 0, v42, s[44:45]
	v_pk_fma_f32 v[40:41], v[120:121], v[40:41], v[44:45]
	v_mov_b32_e32 v44, v37
	v_mov_b32_e32 v45, v35
	v_pk_fma_f32 v[40:41], v[44:45], v[118:119], v[40:41]
	v_mov_b32_dpp v52, v36 row_shr:2 row_mask:0xf bank_mask:0xf bound_ctrl:1
	v_mul_f32_e32 v11, 0xbfb8aa3b, v40
	v_exp_f32_e32 v43, v11
	v_cndmask_b32_e64 v11, 0, v46, s[44:45]
	v_mov_b32_dpp v53, v34 row_shr:2 row_mask:0xf bank_mask:0xf bound_ctrl:1
	v_cndmask_b32_e64 v11, v11, v38, s[42:43]
	v_cndmask_b32_e64 v10, v39, v10, s[42:43]
	v_mov_b32_dpp v50, v36 row_shr:1 row_mask:0xf bank_mask:0xf bound_ctrl:1
	v_mov_b32_dpp v51, v34 row_shr:1 row_mask:0xf bank_mask:0xf bound_ctrl:1
	v_cndmask_b32_e64 v45, 0, v46, s[42:43]
	v_cndmask_b32_e64 v44, 0, v42, s[42:43]
	v_pk_add_f32 v[10:11], v[10:11], v[52:53]
	v_pk_add_f32 v[38:39], v[44:45], v[50:51]
	v_pk_mul_f32 v[10:11], v[128:129], v[10:11]
	v_mul_f32_e32 v0, 0xbfb8aa3b, v62
	v_pk_fma_f32 v[10:11], v[126:127], v[38:39], v[10:11]
	v_mov_b32_e32 v38, v36
	v_mov_b32_e32 v39, v34
	v_pk_fma_f32 v[10:11], v[38:39], v[124:125], v[10:11]
	v_exp_f32_e32 v0, v0
	v_mul_f32_e32 v38, 0xbfb8aa3b, v10
	v_exp_f32_e32 v38, v38
	v_add_f32_e32 v39, 1.0, v43
	v_add_f32_e32 v0, 1.0, v0
	v_rcp_f32_e32 v0, v0
	v_add_f32_e32 v38, 1.0, v38
	v_rcp_f32_e32 v38, v38
	v_rcp_f32_e32 v39, v39
	v_mul_f32_e32 v12, v12, v48
	v_mul_f32_e32 v0, v62, v0
	v_mul_f32_e32 v10, v10, v38
	v_mul_f32_e32 v12, v12, v13
	v_mul_f32_e32 v13, v40, v39
	v_mul_f32_e32 v10, v10, v11
	v_mul_f32_e32 v0, v0, v63
	v_mul_f32_e32 v13, v13, v41
	s_nop 1
	v_cvt_pk_bf16_f32 v10, v10, v13
	s_nop 1
	v_cvt_pk_bf16_f32 v11, v12, v0
	s_nop 0
	v_mov_b32_e32 v224, v244
	v_mov_b32_e32 v225, v245
	v_mov_b32_e32 v226, v10
	v_mov_b32_e32 v227, v11
	global_store_dwordx4 v[108:109], v[224:227], off
	v_mov_b32_dpp v12, v36 row_shl:14 row_mask:0xf bank_mask:0xf bound_ctrl:1
	v_mov_b32_dpp v10, v36 row_shl:15 row_mask:0xf bank_mask:0xf bound_ctrl:1
	v_mov_b32_dpp v36, v37 row_shl:15 row_mask:0xf bank_mask:0xf bound_ctrl:1
	v_mov_b32_dpp v38, v37 row_shl:14 row_mask:0xf bank_mask:0xf bound_ctrl:1
	v_mov_b32_dpp v11, v34 row_shl:15 row_mask:0xf bank_mask:0xf bound_ctrl:1
	v_mov_b32_dpp v13, v34 row_shl:14 row_mask:0xf bank_mask:0xf bound_ctrl:1
	v_mov_b32_dpp v37, v35 row_shl:15 row_mask:0xf bank_mask:0xf bound_ctrl:1
	v_mov_b32_dpp v39, v35 row_shl:14 row_mask:0xf bank_mask:0xf bound_ctrl:1
	v_mov_b32_dpp v34, v20 row_shr:2 row_mask:0xf bank_mask:0xf bound_ctrl:1
	v_mov_b32_dpp v48, v21 row_shr:2 row_mask:0xf bank_mask:0xf bound_ctrl:1
	v_mov_b32_dpp v35, v18 row_shr:2 row_mask:0xf bank_mask:0xf bound_ctrl:1
	v_mov_b32_dpp v49, v19 row_shr:2 row_mask:0xf bank_mask:0xf bound_ctrl:1
	v_mov_b32_dpp v42, v25 row_shl:15 row_mask:0xf bank_mask:0xf bound_ctrl:1
	v_mov_b32_dpp v44, v25 row_shl:14 row_mask:0xf bank_mask:0xf bound_ctrl:1
	v_mov_b32_dpp v41, v22 row_shl:15 row_mask:0xf bank_mask:0xf bound_ctrl:1
	v_mov_b32_dpp v25, v22 row_shl:14 row_mask:0xf bank_mask:0xf bound_ctrl:1
	v_mov_b32_dpp v43, v23 row_shl:15 row_mask:0xf bank_mask:0xf bound_ctrl:1
	v_mov_b32_dpp v45, v23 row_shl:14 row_mask:0xf bank_mask:0xf bound_ctrl:1
	v_mov_b32_dpp v22, v20 row_shr:1 row_mask:0xf bank_mask:0xf bound_ctrl:1
	v_mov_b32_dpp v46, v21 row_shr:1 row_mask:0xf bank_mask:0xf bound_ctrl:1
	v_mov_b32_dpp v23, v18 row_shr:1 row_mask:0xf bank_mask:0xf bound_ctrl:1
	v_mov_b32_dpp v47, v19 row_shr:1 row_mask:0xf bank_mask:0xf bound_ctrl:1
	v_pk_add_f32 v[38:39], v[38:39], v[48:49]
	v_pk_add_f32 v[12:13], v[12:13], v[34:35]
	v_mov_b32_dpp v40, v24 row_shl:15 row_mask:0xf bank_mask:0xf bound_ctrl:1
	v_mov_b32_dpp v24, v24 row_shl:14 row_mask:0xf bank_mask:0xf bound_ctrl:1
	v_mov_b32_dpp v52, v16 row_shr:2 row_mask:0xf bank_mask:0xf bound_ctrl:1
	v_mov_b32_dpp v56, v17 row_shr:2 row_mask:0xf bank_mask:0xf bound_ctrl:1
	v_mov_b32_dpp v57, v15 row_shr:2 row_mask:0xf bank_mask:0xf bound_ctrl:1
	v_mov_b32_dpp v53, v14 row_shr:2 row_mask:0xf bank_mask:0xf bound_ctrl:1
	v_pk_mul_f32 v[38:39], v[122:123], v[38:39]
	v_pk_add_f32 v[36:37], v[36:37], v[46:47]
	v_pk_mul_f32 v[12:13], v[128:129], v[12:13]
	v_pk_add_f32 v[10:11], v[10:11], v[22:23]
	v_mov_b32_dpp v50, v16 row_shr:1 row_mask:0xf bank_mask:0xf bound_ctrl:1
	v_mov_b32_dpp v54, v17 row_shr:1 row_mask:0xf bank_mask:0xf bound_ctrl:1
	v_mov_b32_dpp v55, v15 row_shr:1 row_mask:0xf bank_mask:0xf bound_ctrl:1
	v_pk_add_f32 v[44:45], v[44:45], v[56:57]
	v_mov_b32_dpp v51, v14 row_shr:1 row_mask:0xf bank_mask:0xf bound_ctrl:1
	v_pk_add_f32 v[24:25], v[24:25], v[52:53]
	v_pk_fma_f32 v[36:37], v[120:121], v[36:37], v[38:39]
	v_mov_b32_e32 v38, v21
	v_mov_b32_e32 v39, v19
	v_pk_fma_f32 v[10:11], v[126:127], v[10:11], v[12:13]
	v_mov_b32_e32 v12, v20
	v_mov_b32_e32 v13, v18
	v_pk_mul_f32 v[44:45], v[116:117], v[44:45]
	v_pk_add_f32 v[42:43], v[42:43], v[54:55]
	v_pk_mul_f32 v[24:25], v[134:135], v[24:25]
	v_pk_add_f32 v[40:41], v[40:41], v[50:51]
	v_pk_fma_f32 v[36:37], v[38:39], v[118:119], v[36:37]
	v_pk_fma_f32 v[10:11], v[12:13], v[124:125], v[10:11]
	v_pk_fma_f32 v[42:43], v[100:101], v[42:43], v[44:45]
	v_mov_b32_e32 v44, v17
	v_mov_b32_e32 v45, v15
	v_pk_fma_f32 v[24:25], v[132:133], v[40:41], v[24:25]
	v_mov_b32_e32 v40, v16
	v_mov_b32_e32 v41, v14
; #define LAS __attribute__((address_space(3)))
; __device__ __forceinline__ unsigned cvt_pk_bf16(float lo, float hi) { unsigned r; asm volatile("s_nop 1\n\tv_cvt_pk_bf16_f32 %0, %1, %2" : "=v"(r) : "v"(lo), "v"(hi)); return r; }
; __device__ __forceinline__ float siluf_(float x) { return x * __builtin_amdgcn_rcpf(1.0f + __expf(-x)); }
;     __device__ __forceinline__ void operator()(f32x4 (&acc)[2][2][4][2], const Unit& u, int wr, int wc, int fr, int fq) const {
;     ...
;                     if (m > 0) {
; #pragma unroll
;                         for (int bj = 0; bj < 2; ++bj)
; #pragma unroll
;                             for (int e = 0; e < 4; ++e) { const float pv = acc[ai][bj][m - 1][n][e]; t1[bj][e] = DPPF(pv, 0x10F); t2[bj][e] = DPPF(pv, 0x10E); }
;                     } else {
;                         const bool has_pred = (wr == 1) || (ai == 1);
;                         const int pai = (wr == 1) ? ai : 0, pwr = (wr == 1) ? 0 : 1;
;                         const LAS float* p14 = X + ((((pai * 2 + pwr) * 4 + wc) * 2 + 0) * 4 + fq) * 16; const LAS float* p15 = p14 + 64;
; #pragma unroll
;                         for (int bj = 0; bj < 2; ++bj) { const f32x4 r14 = *(const LAS f32x4*)(p14 + bj * 8 + n * 4), r15 = *(const LAS f32x4*)(p15 + bj * 8 + n * 4);
; #pragma unroll
;                             for (int e = 0; e < 4; ++e) { t1[bj][e] = (has_pred && fr == 0) ? r15[e] : 0.f; t2[bj][e] = has_pred ? (fr == 0 ? r14[e] : (fr == 1 ? r15[e] : 0.f)) : 0.f; } }
;                     }
;                     float h[2][4];
; #pragma unroll
;                     for (int bj = 0; bj < 2; ++bj)
; #pragma unroll
;                         for (int e = 0; e < 4; ++e) { const float cur = acc[ai][bj][m][n][e];
;                             const float p1 = DPPF(cur, 0x111) + t1[bj][e], p2 = DPPF(cur, 0x112) + t2[bj][e];
;                             h[bj][e] = w[0][bj][e] * p2 + w[1][bj][e] * p1 + w[2][bj][e] * cur; }
;                     float r4[4];
; #pragma unroll
;                     for (int c = 0; c < 4; ++c) r4[c] = siluf_(h[0][c]) * h[1][c];
;                     const bool skip = (ai == 0) && (m == 0) && (wr == 0) && (fr < 2);
;                     if (!skip) { u32x2 o; o.x = cvt_pk_bf16(r4[0], r4[1]); o.y = cvt_pk_bf16(r4[2], r4[3]);
;                         *(u32x2*)(ACT + (size_t)(u.pm * BM + ai * HALF + wr * 64 + m * 16 + fr) * DFF + chb + 4 * n) = o; }
	v_mul_f32_e32 v38, 0xbfb8aa3b, v36
	v_mul_f32_e32 v12, 0xbfb8aa3b, v10
	v_pk_fma_f32 v[42:43], v[44:45], v[98:99], v[42:43]
	v_pk_fma_f32 v[24:25], v[40:41], v[130:131], v[24:25]
	v_exp_f32_e32 v38, v38
	v_exp_f32_e32 v12, v12
	v_mul_f32_e32 v0, 0xbfb8aa3b, v42
	v_mul_f32_e32 v40, 0xbfb8aa3b, v24
	v_exp_f32_e32 v0, v0
	v_exp_f32_e32 v40, v40
	v_add_f32_e32 v22, 1.0, v38
	v_add_f32_e32 v12, 1.0, v12
	v_rcp_f32_e32 v22, v22
	v_rcp_f32_e32 v12, v12
	v_add_f32_e32 v0, 1.0, v0
	v_add_f32_e32 v40, 1.0, v40
	v_rcp_f32_e32 v0, v0
	v_rcp_f32_e32 v40, v40
	v_mul_f32_e32 v22, v36, v22
	v_mul_f32_e32 v10, v10, v12
	v_pk_mul_f32 v[2:3], v[2:3], v[190:191]
	v_mul_f32_e32 v22, v22, v37
	v_mul_f32_e32 v10, v10, v11
	v_mul_f32_e32 v0, v42, v0
	v_mul_f32_e32 v13, v24, v40
	s_nop 1
	v_cvt_pk_bf16_f32 v10, v10, v22
	v_mov_b32_dpp v22, v21 row_shl:14 row_mask:0xf bank_mask:0xf bound_ctrl:1
	v_mov_b32_dpp v23, v19 row_shl:14 row_mask:0xf bank_mask:0xf bound_ctrl:1
	v_mov_b32_dpp v40, v9 row_shr:2 row_mask:0xf bank_mask:0xf bound_ctrl:1
	v_mov_b32_dpp v41, v3 row_shr:2 row_mask:0xf bank_mask:0xf bound_ctrl:1
	v_mul_f32_e32 v0, v0, v43
	v_mul_f32_e32 v13, v13, v25
	s_nop 1
	v_cvt_pk_bf16_f32 v11, v13, v0
	s_nop 0
	v_mov_b32_e32 v228, v172
	v_mov_b32_e32 v229, v173
	v_mov_b32_e32 v230, v10
	v_mov_b32_e32 v231, v11
	global_store_dwordx4 v[110:111], v[228:231], off
	v_mov_b32_dpp v10, v20 row_shl:15 row_mask:0xf bank_mask:0xf bound_ctrl:1
	v_mov_b32_dpp v12, v20 row_shl:14 row_mask:0xf bank_mask:0xf bound_ctrl:1
	v_mov_b32_dpp v20, v21 row_shl:15 row_mask:0xf bank_mask:0xf bound_ctrl:1
	v_mov_b32_dpp v24, v16 row_shl:15 row_mask:0xf bank_mask:0xf bound_ctrl:1
	v_mov_b32_dpp v16, v16 row_shl:14 row_mask:0xf bank_mask:0xf bound_ctrl:1
	v_mov_b32_dpp v34, v17 row_shl:15 row_mask:0xf bank_mask:0xf bound_ctrl:1
	v_mov_b32_dpp v36, v17 row_shl:14 row_mask:0xf bank_mask:0xf bound_ctrl:1
	v_mov_b32_dpp v21, v19 row_shl:15 row_mask:0xf bank_mask:0xf bound_ctrl:1
	v_mov_b32_dpp v17, v14 row_shl:14 row_mask:0xf bank_mask:0xf bound_ctrl:1
	v_mov_b32_dpp v37, v15 row_shl:14 row_mask:0xf bank_mask:0xf bound_ctrl:1
	v_mov_b32_dpp v38, v9 row_shr:1 row_mask:0xf bank_mask:0xf bound_ctrl:1
	v_mov_b32_dpp v44, v6 row_shr:2 row_mask:0xf bank_mask:0xf bound_ctrl:1
	v_mov_b32_dpp v48, v7 row_shr:2 row_mask:0xf bank_mask:0xf bound_ctrl:1
	v_mov_b32_dpp v49, v5 row_shr:2 row_mask:0xf bank_mask:0xf bound_ctrl:1
	v_mov_b32_dpp v39, v3 row_shr:1 row_mask:0xf bank_mask:0xf bound_ctrl:1
	v_mov_b32_dpp v45, v4 row_shr:2 row_mask:0xf bank_mask:0xf bound_ctrl:1
	v_pk_add_f32 v[22:23], v[22:23], v[40:41]
	v_mov_b32_dpp v11, v18 row_shl:15 row_mask:0xf bank_mask:0xf bound_ctrl:1
	v_mov_b32_dpp v13, v18 row_shl:14 row_mask:0xf bank_mask:0xf bound_ctrl:1
	v_mov_b32_dpp v25, v14 row_shl:15 row_mask:0xf bank_mask:0xf bound_ctrl:1
	v_mov_b32_dpp v35, v15 row_shl:15 row_mask:0xf bank_mask:0xf bound_ctrl:1
	v_mov_b32_dpp v18, v8 row_shr:2 row_mask:0xf bank_mask:0xf bound_ctrl:1
	v_mov_b32_dpp v42, v6 row_shr:1 row_mask:0xf bank_mask:0xf bound_ctrl:1
	v_mov_b32_dpp v46, v7 row_shr:1 row_mask:0xf bank_mask:0xf bound_ctrl:1
	v_mov_b32_dpp v19, v2 row_shr:2 row_mask:0xf bank_mask:0xf bound_ctrl:1
	v_mov_b32_dpp v47, v5 row_shr:1 row_mask:0xf bank_mask:0xf bound_ctrl:1
	v_pk_add_f32 v[36:37], v[36:37], v[48:49]
	v_mov_b32_dpp v43, v4 row_shr:1 row_mask:0xf bank_mask:0xf bound_ctrl:1
	v_pk_add_f32 v[16:17], v[16:17], v[44:45]
	v_pk_mul_f32 v[22:23], v[122:123], v[22:23]
	v_pk_add_f32 v[20:21], v[20:21], v[38:39]
	v_mov_b32_dpp v14, v8 row_shr:1 row_mask:0xf bank_mask:0xf bound_ctrl:1
	v_mov_b32_dpp v15, v2 row_shr:1 row_mask:0xf bank_mask:0xf bound_ctrl:1
	v_pk_mul_f32 v[36:37], v[116:117], v[36:37]
	v_pk_add_f32 v[34:35], v[34:35], v[46:47]
	v_pk_mul_f32 v[16:17], v[134:135], v[16:17]
	v_pk_add_f32 v[24:25], v[24:25], v[42:43]
	v_pk_fma_f32 v[20:21], v[120:121], v[20:21], v[22:23]
	v_mov_b32_e32 v22, v9
	v_mov_b32_e32 v23, v3
	v_pk_add_f32 v[12:13], v[12:13], v[18:19]
	v_pk_fma_f32 v[34:35], v[100:101], v[34:35], v[36:37]
	v_mov_b32_e32 v36, v7
	v_mov_b32_e32 v37, v5
	v_pk_fma_f32 v[16:17], v[132:133], v[24:25], v[16:17]
	v_mov_b32_e32 v24, v6
	v_mov_b32_e32 v25, v4
	v_pk_fma_f32 v[20:21], v[22:23], v[118:119], v[20:21]
	v_pk_mul_f32 v[12:13], v[128:129], v[12:13]
	v_pk_add_f32 v[10:11], v[10:11], v[14:15]
	v_pk_fma_f32 v[34:35], v[36:37], v[98:99], v[34:35]
	v_pk_fma_f32 v[16:17], v[24:25], v[130:131], v[16:17]
	v_mul_f32_e32 v22, 0xbfb8aa3b, v20
	v_pk_fma_f32 v[10:11], v[126:127], v[10:11], v[12:13]
	v_mov_b32_e32 v12, v8
	v_mov_b32_e32 v13, v2
	v_mul_f32_e32 v0, 0xbfb8aa3b, v34
	v_mul_f32_e32 v24, 0xbfb8aa3b, v16
	v_exp_f32_e32 v22, v22
	v_pk_fma_f32 v[10:11], v[12:13], v[124:125], v[10:11]
	v_exp_f32_e32 v0, v0
	v_exp_f32_e32 v24, v24
	v_mul_f32_e32 v12, 0xbfb8aa3b, v10
	v_exp_f32_e32 v12, v12
	v_add_f32_e32 v14, 1.0, v22
	v_add_f32_e32 v0, 1.0, v0
	v_add_f32_e32 v24, 1.0, v24
	v_rcp_f32_e32 v14, v14
	v_rcp_f32_e32 v0, v0
	v_rcp_f32_e32 v24, v24
	v_add_f32_e32 v12, 1.0, v12
; #define LAS __attribute__((address_space(3)))
; __device__ __forceinline__ unsigned cvt_pk_bf16(float lo, float hi) { unsigned r; asm volatile("s_nop 1\n\tv_cvt_pk_bf16_f32 %0, %1, %2" : "=v"(r) : "v"(lo), "v"(hi)); return r; }
;     __device__ __forceinline__ void operator()(f32x4 (&acc)[2][2][4][2], const Unit& u, int wr, int wc, int fr, int fq) const {
;     ...
;                     if (m > 0) {
; #pragma unroll
;                         for (int bj = 0; bj < 2; ++bj)
; #pragma unroll
;                             for (int e = 0; e < 4; ++e) { const float pv = acc[ai][bj][m - 1][n][e]; t1[bj][e] = DPPF(pv, 0x10F); t2[bj][e] = DPPF(pv, 0x10E); }
;                     } else {
;                         const bool has_pred = (wr == 1) || (ai == 1);
;                         const int pai = (wr == 1) ? ai : 0, pwr = (wr == 1) ? 0 : 1;
;                         const LAS float* p14 = X + ((((pai * 2 + pwr) * 4 + wc) * 2 + 0) * 4 + fq) * 16; const LAS float* p15 = p14 + 64;
; #pragma unroll
;                         for (int bj = 0; bj < 2; ++bj) { const f32x4 r14 = *(const LAS f32x4*)(p14 + bj * 8 + n * 4), r15 = *(const LAS f32x4*)(p15 + bj * 8 + n * 4);
; #pragma unroll
;                             for (int e = 0; e < 4; ++e) { t1[bj][e] = (has_pred && fr == 0) ? r15[e] : 0.f; t2[bj][e] = has_pred ? (fr == 0 ? r14[e] : (fr == 1 ? r15[e] : 0.f)) : 0.f; } }
;                     }
;                     float h[2][4];
; #pragma unroll
;                     for (int bj = 0; bj < 2; ++bj)
; #pragma unroll
;                         for (int e = 0; e < 4; ++e) { const float cur = acc[ai][bj][m][n][e];
;                             const float p1 = DPPF(cur, 0x111) + t1[bj][e], p2 = DPPF(cur, 0x112) + t2[bj][e];
;                             h[bj][e] = w[0][bj][e] * p2 + w[1][bj][e] * p1 + w[2][bj][e] * cur; }
;                     float r4[4];
; #pragma unroll
;                     for (int c = 0; c < 4; ++c) r4[c] = siluf_(h[0][c]) * h[1][c];
;                     const bool skip = (ai == 0) && (m == 0) && (wr == 0) && (fr < 2);
;                     if (!skip) { u32x2 o; o.x = cvt_pk_bf16(r4[0], r4[1]); o.y = cvt_pk_bf16(r4[2], r4[3]);
;                         *(u32x2*)(ACT + (size_t)(u.pm * BM + ai * HALF + wr * 64 + m * 16 + fr) * DFF + chb + 4 * n) = o; }
;                 }
;             asm volatile("" ::: "memory");
;         }
	v_rcp_f32_e32 v12, v12
	v_mul_f32_e32 v14, v20, v14
	v_mul_f32_e32 v0, v34, v0
	v_mul_f32_e32 v13, v16, v24
	v_mul_f32_e32 v14, v14, v21
	v_mov_b32_dpp v16, v6 row_shl:15 row_mask:0xf bank_mask:0xf bound_ctrl:1
	v_mov_b32_dpp v6, v6 row_shl:14 row_mask:0xf bank_mask:0xf bound_ctrl:1
	v_mov_b32_dpp v18, v7 row_shl:15 row_mask:0xf bank_mask:0xf bound_ctrl:1
	v_mov_b32_dpp v20, v7 row_shl:14 row_mask:0xf bank_mask:0xf bound_ctrl:1
	v_mov_b32_dpp v7, v4 row_shl:14 row_mask:0xf bank_mask:0xf bound_ctrl:1
	v_mov_b32_dpp v21, v5 row_shl:14 row_mask:0xf bank_mask:0xf bound_ctrl:1
	v_mov_b32_dpp v36, v28 row_shr:2 row_mask:0xf bank_mask:0xf bound_ctrl:1
	v_mov_b32_dpp v40, v29 row_shr:2 row_mask:0xf bank_mask:0xf bound_ctrl:1
	v_mov_b32_dpp v41, v33 row_shr:2 row_mask:0xf bank_mask:0xf bound_ctrl:1
	v_mov_b32_dpp v37, v32 row_shr:2 row_mask:0xf bank_mask:0xf bound_ctrl:1
	v_mul_f32_e32 v0, v0, v35
	v_mul_f32_e32 v13, v13, v17
	v_mul_f32_e32 v10, v10, v12
	v_mov_b32_dpp v17, v4 row_shl:15 row_mask:0xf bank_mask:0xf bound_ctrl:1
	v_mov_b32_dpp v19, v5 row_shl:15 row_mask:0xf bank_mask:0xf bound_ctrl:1
	v_mov_b32_dpp v34, v28 row_shr:1 row_mask:0xf bank_mask:0xf bound_ctrl:1
	v_mov_b32_dpp v38, v29 row_shr:1 row_mask:0xf bank_mask:0xf bound_ctrl:1
	v_mov_b32_dpp v39, v33 row_shr:1 row_mask:0xf bank_mask:0xf bound_ctrl:1
	v_pk_add_f32 v[20:21], v[20:21], v[40:41]
	v_mov_b32_dpp v35, v32 row_shr:1 row_mask:0xf bank_mask:0xf bound_ctrl:1
	v_pk_add_f32 v[6:7], v[6:7], v[36:37]
	v_mul_f32_e32 v10, v10, v11
	v_pk_mul_f32 v[20:21], v[116:117], v[20:21]
	v_pk_add_f32 v[18:19], v[18:19], v[38:39]
	v_pk_mul_f32 v[6:7], v[134:135], v[6:7]
	v_pk_add_f32 v[16:17], v[16:17], v[34:35]
	s_nop 1
	v_cvt_pk_bf16_f32 v10, v10, v14
	v_pk_fma_f32 v[18:19], v[100:101], v[18:19], v[20:21]
	v_mov_b32_e32 v20, v29
	v_pk_fma_f32 v[6:7], v[132:133], v[16:17], v[6:7]
	v_mov_b32_e32 v29, v32
	s_nop 1
	v_cvt_pk_bf16_f32 v11, v13, v0
	s_nop 0
	v_mov_b32_e32 v224, v216
	v_mov_b32_e32 v225, v217
	v_mov_b32_e32 v226, v10
	v_mov_b32_e32 v227, v11
	global_store_dwordx4 v[112:113], v[224:227], off
	v_mov_b32_dpp v10, v8 row_shl:15 row_mask:0xf bank_mask:0xf bound_ctrl:1
	v_mov_b32_dpp v8, v8 row_shl:14 row_mask:0xf bank_mask:0xf bound_ctrl:1
	v_mov_b32_dpp v12, v9 row_shl:15 row_mask:0xf bank_mask:0xf bound_ctrl:1
	v_mov_b32_dpp v14, v9 row_shl:14 row_mask:0xf bank_mask:0xf bound_ctrl:1
	v_mov_b32_dpp v9, v2 row_shl:14 row_mask:0xf bank_mask:0xf bound_ctrl:1
	v_mov_b32_dpp v15, v3 row_shl:14 row_mask:0xf bank_mask:0xf bound_ctrl:1
	v_mov_b32_dpp v4, v26 row_shr:2 row_mask:0xf bank_mask:0xf bound_ctrl:1
	v_mov_b32_dpp v24, v27 row_shr:2 row_mask:0xf bank_mask:0xf bound_ctrl:1
	v_mov_b32_dpp v5, v30 row_shr:2 row_mask:0xf bank_mask:0xf bound_ctrl:1
	v_pk_fma_f32 v[6:7], v[28:29], v[130:131], v[6:7]
	v_mov_b32_dpp v25, v31 row_shr:2 row_mask:0xf bank_mask:0xf bound_ctrl:1
	v_mov_b32_dpp v11, v2 row_shl:15 row_mask:0xf bank_mask:0xf bound_ctrl:1
	v_mov_b32_dpp v13, v3 row_shl:15 row_mask:0xf bank_mask:0xf bound_ctrl:1
	v_mov_b32_dpp v2, v26 row_shr:1 row_mask:0xf bank_mask:0xf bound_ctrl:1
	v_mov_b32_dpp v22, v27 row_shr:1 row_mask:0xf bank_mask:0xf bound_ctrl:1
	v_mov_b32_dpp v3, v30 row_shr:1 row_mask:0xf bank_mask:0xf bound_ctrl:1
	v_mov_b32_dpp v23, v31 row_shr:1 row_mask:0xf bank_mask:0xf bound_ctrl:1
	v_mul_f32_e32 v16, 0xbfb8aa3b, v6
	v_pk_add_f32 v[14:15], v[14:15], v[24:25]
	v_pk_add_f32 v[4:5], v[8:9], v[4:5]
	v_exp_f32_e32 v16, v16
	v_pk_mul_f32 v[14:15], v[122:123], v[14:15]
	v_pk_add_f32 v[12:13], v[12:13], v[22:23]
	v_pk_mul_f32 v[4:5], v[128:129], v[4:5]
	v_pk_add_f32 v[2:3], v[10:11], v[2:3]
	v_pk_fma_f32 v[12:13], v[120:121], v[12:13], v[14:15]
	v_mov_b32_e32 v14, v27
	v_pk_fma_f32 v[2:3], v[126:127], v[2:3], v[4:5]
	v_mov_b32_e32 v27, v30
	v_mov_b32_e32 v21, v33
	v_mov_b32_e32 v15, v31
	v_pk_fma_f32 v[2:3], v[26:27], v[124:125], v[2:3]
	v_pk_fma_f32 v[18:19], v[20:21], v[98:99], v[18:19]
	v_pk_fma_f32 v[12:13], v[14:15], v[118:119], v[12:13]
	v_mul_f32_e32 v4, 0xbfb8aa3b, v2
	v_mul_f32_e32 v0, 0xbfb8aa3b, v18
	v_add_f32_e32 v16, 1.0, v16
	v_mul_f32_e32 v14, 0xbfb8aa3b, v12
	v_exp_f32_e32 v4, v4
	v_exp_f32_e32 v0, v0
	v_rcp_f32_e32 v16, v16
	v_exp_f32_e32 v14, v14
	v_add_f32_e32 v4, 1.0, v4
	v_add_f32_e32 v0, 1.0, v0
	v_mul_f32_e32 v5, v6, v16
	v_add_f32_e32 v6, 1.0, v14
	v_rcp_f32_e32 v4, v4
	v_rcp_f32_e32 v0, v0
	v_rcp_f32_e32 v6, v6
	v_mul_f32_e32 v5, v5, v7
	v_mul_f32_e32 v2, v2, v4
	v_mul_f32_e32 v0, v18, v0
	v_mul_f32_e32 v6, v12, v6
	v_mul_f32_e32 v2, v2, v3
	v_mul_f32_e32 v0, v0, v19
	v_mul_f32_e32 v6, v6, v13
	s_nop 1
	v_cvt_pk_bf16_f32 v2, v2, v6
	s_nop 1
	v_cvt_pk_bf16_f32 v3, v5, v0
	s_nop 0
	v_mov_b32_e32 v228, v218
	v_mov_b32_e32 v229, v219
	v_mov_b32_e32 v230, v2
	v_mov_b32_e32 v231, v3
	global_store_dwordx4 v[114:115], v[228:231], off
	s_andn2_b64 vcc, exec, s[40:41]
	s_mov_b64 s[8:9], -1
	s_cbranch_vccnz .LBB0_1061
	s_andn2_b64 vcc, exec, s[22:23]
	s_cbranch_vccnz .LBB0_1060
	s_barrier
	s_branch .LBB0_1060
